# all-gemm-epilogues-run-with-both-wave-groups-aligned
# baseline (speedup 1.0000x reference)
; #define PG8_STAGE(bufoff, gbase, hoff, imm) do { _Pragma("unroll") for (int _i = 0; _i < 2; ++_i) { \
;         asm volatile("s_mov_b32 m0, %0\n\ts_nop 0\n\tglobal_load_lds_dwordx4 %1, %2" \
;             :: "s"(lds0 + (unsigned)((bufoff) + _i * 8192)), "v"(voff0), "s"((const char*)(gbase) + (size_t)(hoff) + (size_t)(_i * 8192)) : "memory"); } } while (0)
; #define PG8_WAIT_V(n) asm volatile("s_waitcnt vmcnt(" #n ")" ::: "memory")
; #define PG8_BAR __builtin_amdgcn_s_barrier()
; template <class Epi>
; __device__ __forceinline__ void gemm_phase(LAS unsigned char* lds, const Gemm g, const StaticOrder& S, const Epi& E) {
;     ...
;     const char* cA = (const char*)g.A + (size_t)cur.pm * tstepA + (size_t)(cur.pn >> g.gshift) * g.gstride; const char* cB = (const char*)g.Bt + (size_t)cur.pn * tstepB;
;     PG8_STAGE(PG8_SB(0, 0), cB, 0, 0); PG8_STAGE(PG8_SA(0, 0), cA, 0, 0); PG8_STAGE(PG8_SB(0, 1), cB, hB, 0); PG8_STAGE(PG8_SA(0, 1), cA, hA, 0);
;     if (wr == 1) PG8_BAR;
;     PG8_WAIT_V(4); PG8_BAR;
;     PG8_STAGE(PG8_SB(1, 0), cB + KS, 0, 0); PG8_STAGE(PG8_SA(1, 0), cA + KS, 0, 0); PG8_STAGE(PG8_SB(1, 1), cB + KS, hB, 0);
;     PG8_WAIT_V(6); PG8_BAR;
.LBB0_423:
	s_mov_b32 s1, 0
	v_mov_b32_e32 v0, v235
	v_readlane_b32 s2, v255, 6
	v_readlane_b32 s3, v255, 7
	v_readfirstlane_b32 s16, v0
	s_andn2_b64 vcc, exec, s[2:3]
	s_ashr_i32 s0, s16, 6
	s_cbranch_vccnz .LBB0_439
	s_ashr_i32 s3, s1, 31
	s_add_u32 s2, s96, s1
	s_addc_u32 s3, s97, s3
	s_load_dwordx2 s[2:3], s[2:3], 0x90
	v_lshlrev_b32_e32 v130, 4, v0
	s_waitcnt lgkmcnt(0)
	s_add_u32 s17, s2, 0xa630000
	s_addc_u32 s21, s3, 0
	s_add_u32 s22, s2, 0x200000
	s_addc_u32 s24, s3, 0
	s_lshl_b32 s4, s0, 10
	s_ashr_i32 s1, s16, 8
	s_add_i32 s25, s4, 0
	v_readlane_b32 s4, v255, 19
	v_readlane_b32 s5, v255, 20
	s_add_u32 s56, s22, s4
	s_addc_u32 s57, s24, s5
	s_add_i32 s26, s25, 0x10000
	s_add_i32 s27, s25, 0x12000
	s_add_u32 s4, s56, 0x2000
	s_mov_b32 m0, s26
	s_nop 0
	global_load_lds_dwordx4 v130, s[56:57]
	s_addc_u32 s5, s57, 0
	s_mov_b32 m0, s27
	s_nop 0
	global_load_lds_dwordx4 v130, s[4:5]
	v_readlane_b32 s4, v255, 17
	v_readlane_b32 s5, v255, 18
	s_add_u32 s54, s17, s4
	s_addc_u32 s55, s21, s5
	s_add_i32 s28, s25, 0x2000
	s_add_u32 s4, s54, 0x2000
	s_mov_b32 m0, s25
	s_nop 0
	global_load_lds_dwordx4 v130, s[54:55]
	s_addc_u32 s5, s55, 0
	s_add_i32 s29, s25, 0x14000
	s_mov_b32 m0, s28
	s_nop 0
	global_load_lds_dwordx4 v130, s[4:5]
	s_add_u32 s4, s56, 0x80000
	s_addc_u32 s5, s57, 0
	s_add_i32 s30, s25, 0x16000
	s_mov_b32 m0, s29
	s_nop 0
	global_load_lds_dwordx4 v130, s[4:5]
	s_add_u32 s4, s56, 0x82000
	s_addc_u32 s5, s57, 0
	s_add_i32 s34, s25, 0x4000
	s_mov_b32 m0, s30
	s_nop 0
	global_load_lds_dwordx4 v130, s[4:5]
	s_add_u32 s4, s54, 0x80000
	s_addc_u32 s5, s55, 0
	s_add_i32 s37, s25, 0x6000
	s_mov_b32 m0, s34
	s_nop 0
	global_load_lds_dwordx4 v130, s[4:5]
	s_add_u32 s4, s54, 0x82000
	s_addc_u32 s5, s55, 0
	s_mov_b32 m0, s37
	s_nop 0
	global_load_lds_dwordx4 v130, s[4:5]
	s_cmp_lg_u32 s1, 1
	s_cbranch_scc1 .LBB0_426
.LBB0_426:
	s_add_u32 s2, s2, 0x12630000
	v_lshrrev_b32_e32 v2, 1, v0
	s_addc_u32 s3, s3, 0
	v_and_b32_e32 v2, 24, v2
	s_lshl_b32 s0, s0, 5
	v_and_b32_e32 v1, 15, v0
	v_lshlrev_b32_e32 v3, 1, v2
	v_lshlrev_b32_e32 v0, 2, v0
	s_and_b32 s4, s0, 0x60
	v_lshl_or_b32 v131, s1, 6, v1
	v_lshl_or_b32 v1, v1, 6, v3
	s_lshl_b32 s1, s1, 13
	v_and_b32_e32 v0, 32, v0
	s_lshl_b32 s0, s4, 7
	s_add_i32 s38, s25, 0x18000
	v_bitop3_b32 v3, v1, s1, v0 bitop3:0xde
	v_bitop3_b32 v0, v1, s0, v0 bitop3:0xde
	s_add_u32 s0, s56, 0x4000
	s_addc_u32 s1, s57, 0
	s_add_i32 s39, s25, 0x1a000
	s_waitcnt vmcnt(4)
	s_barrier
	s_mov_b32 m0, s38
	s_nop 0
	global_load_lds_dwordx4 v130, s[0:1]
	s_add_u32 s0, s56, 0x6000
	s_addc_u32 s1, s57, 0
	s_add_i32 s40, s25, 0x8000
	s_mov_b32 m0, s39
	s_nop 0
	global_load_lds_dwordx4 v130, s[0:1]
	s_add_u32 s0, s54, 0x4000
	s_addc_u32 s1, s55, 0
	s_add_i32 s41, s25, 0xa000
	s_mov_b32 m0, s40
	s_nop 0
	global_load_lds_dwordx4 v130, s[0:1]
	s_add_u32 s0, s54, 0x6000
	s_addc_u32 s1, s55, 0
	s_add_i32 s42, s25, 0x1c000
	s_mov_b32 m0, s41
	s_nop 0
	global_load_lds_dwordx4 v130, s[0:1]
	s_add_u32 s0, s56, 0x84000
	s_addc_u32 s1, s57, 0
	s_add_i32 s43, s25, 0x1e000
	s_mov_b32 m0, s42
	s_nop 0
	global_load_lds_dwordx4 v130, s[0:1]
	s_add_u32 s0, s56, 0x86000
	s_addc_u32 s1, s57, 0
	s_mov_b32 m0, s43
	s_nop 0
	global_load_lds_dwordx4 v130, s[0:1]
	s_waitcnt vmcnt(6)
	v_readlane_b32 s0, v255, 15
	s_add_i32 s50, s25, 0xc000
	s_add_i32 s51, s25, 0xe000
	v_or_b32_e32 v132, s4, v2
	s_mov_b32 s60, 0
	v_add_u32_e32 v133, 0x10000, v0
	v_add_u32_e32 v134, 0, v3
	v_readlane_b32 s61, v255, 14
	s_mov_b32 s62, s0
	s_barrier
	v_readlane_b32 s1, v255, 16
	s_waitcnt vmcnt(0)

; #define PG8_STAGE(bufoff, gbase, hoff, imm) do { _Pragma("unroll") for (int _i = 0; _i < 2; ++_i) { \
;         asm volatile("s_mov_b32 m0, %0\n\ts_nop 0\n\tglobal_load_lds_dwordx4 %1, %2" \
;             :: "s"(lds0 + (unsigned)((bufoff) + _i * 8192)), "v"(voff0), "s"((const char*)(gbase) + (size_t)(hoff) + (size_t)(_i * 8192)) : "memory"); } } while (0)
; #define PG8_LDA(dst, b, h) do { _Pragma("unroll") for (int m = 0; m < 4; ++m) _Pragma("unroll") for (int k = 0; k < 2; ++k) dst[m][k] = *(const LAS bf16x8*)(lds + PG8_SA(b, h) + aoff + m * 2048 + k * 1024); } while (0)
; #define PG8_LDB(dst, b, h) do { _Pragma("unroll") for (int n = 0; n < 2; ++n) _Pragma("unroll") for (int k = 0; k < 2; ++k) dst[n][k] = *(const LAS bf16x8*)(lds + PG8_SB(b, h) + boff + n * 2048 + k * 1024); } while (0)
; #define PG8_MMA(ai, bj, At, Bt) do { __builtin_amdgcn_s_setprio(1); _Pragma("unroll") for (int m = 0; m < 4; ++m) _Pragma("unroll") for (int n = 0; n < 2; ++n) _Pragma("unroll") for (int k = 0; k < 2; ++k) \
;         acc[ai][bj][m][n] = __builtin_amdgcn_mfma_f32_16x16x32_bf16(Bt[n][k], At[m][k], acc[ai][bj][m][n], 0, 0, 0); __builtin_amdgcn_s_setprio(0); } while (0)
; #define PG8_WAIT_L(n) asm volatile("s_waitcnt lgkmcnt(" #n ")" ::: "memory")
; template <class Epi>
; __device__ __forceinline__ void gemm_phase(LAS unsigned char* lds, const Gemm g, const StaticOrder& S, const Epi& E) {
;     ...
;     if (wr == 1) PG8_BAR;
;     ...
;         const bool has_next = S.next(ui + 1, nxt);
;         const char* nA = has_next ? (const char*)g.A + (size_t)nxt.pm * tstepA + (size_t)(nxt.pn >> g.gshift) * g.gstride : cA;
;         const char* nB = has_next ? (const char*)g.Bt + (size_t)nxt.pn * tstepB : cB;
;         for (int t = 0; t < nt; t += 2) {
;             const bool last = (t == nt - 2);
;             if (last) E.pre(cur, wid, lane, (unsigned)(size_t)(lds + STAGE_BYTES));
;             const char* aT = cA + (size_t)t * KS;
;             const char* a2 = last ? nA : aT + 2 * KS; const char* b2 = last ? nB : cB + (size_t)(t + 2) * KS;
;             PG8_LDB(B0, 0, 0); PG8_SCHED; PG8_LDA(At, 0, 0); PG8_STAGE(PG8_SA(1, 1), aT + KS, hA, 0);
;             PG8_WAIT_L(8); PG8_BAR; PG8_WAIT_L(0); PG8_MMA(0, 0, At, B0); PG8_BAR; PG8_SCHED;
;             PG8_LDB(B1, 0, 1); PG8_STAGE(PG8_SB(0, 0), b2, 0, 0);
;             PG8_BAR; PG8_WAIT_L(0); PG8_MMA(0, 1, At, B1); PG8_BAR;
.LBB0_433:
	s_ashr_i32 s9, s8, 31
	s_lshl_b64 s[0:1], s[8:9], 20
	v_cmp_lt_i64_e32 vcc, s[10:11], v[192:193]
	s_add_u32 s10, s17, s0
	s_addc_u32 s11, s21, s1
	s_and_b64 s[0:1], vcc, exec
	s_cselect_b32 s0, s11, s55
	s_cselect_b32 s1, s10, s54
	s_ashr_i32 s7, s6, 31
	s_lshl_b64 s[52:53], s[6:7], 20
	s_add_u32 s52, s22, s52
	s_addc_u32 s53, s24, s53
	s_and_b64 s[58:59], vcc, exec
	s_cselect_b32 s7, s53, s57
	s_cselect_b32 s9, s52, s56
	s_add_u32 s63, s56, 0x8000
	s_addc_u32 s64, s57, 0
	s_mov_b32 s65, -2
	v_readfirstlane_b32 s66, v235
	s_nop 1
	s_cmpk_lt_u32 s66, 0x100
	s_cbranch_scc1 .Lbg_st_skip
	s_barrier
.Lbg_st_skip:
	s_add_u32 s56, s54, 0x8000
	s_addc_u32 s57, s55, 0
	ds_read_b128 v[136:139], v133
	ds_read_b128 v[140:143], v133 offset:1024
	ds_read_b128 v[144:147], v133 offset:2048
	ds_read_b128 v[148:151], v133 offset:3072
	s_add_u32 s58, s54, 0x84000
	s_addc_u32 s59, s55, 0
	s_add_u32 s66, s54, 0x86000
	s_addc_u32 s67, s55, 0
	s_cmp_eq_u32 s65, 28
	s_cselect_b32 s55, s0, s57
	s_cselect_b32 s54, s1, s56
	ds_read_b128 v[152:155], v134
	ds_read_b128 v[156:159], v134 offset:1024
	ds_read_b128 v[160:163], v134 offset:2048
	ds_read_b128 v[164:167], v134 offset:3072
	ds_read_b128 v[168:171], v134 offset:4096
	ds_read_b128 v[172:175], v134 offset:5120
	ds_read_b128 v[176:179], v134 offset:6144
	ds_read_b128 v[180:183], v134 offset:7168
	s_mov_b32 m0, s50
	s_nop 0
	global_load_lds_dwordx4 v130, s[58:59]
	s_mov_b32 m0, s51
	s_nop 0
	global_load_lds_dwordx4 v130, s[66:67]
	s_waitcnt lgkmcnt(8)
	s_waitcnt vmcnt(10)
	s_barrier
	s_waitcnt lgkmcnt(7)
	v_mfma_f32_16x16x32_bf16 v[124:127], v[136:139], v[152:155], 0
	v_mfma_f32_16x16x32_bf16 v[120:123], v[144:147], v[152:155], 0
	s_waitcnt lgkmcnt(5)
	v_mfma_f32_16x16x32_bf16 v[116:119], v[136:139], v[160:163], 0
	v_mfma_f32_16x16x32_bf16 v[108:111], v[144:147], v[160:163], 0
	s_waitcnt lgkmcnt(3)
	v_mfma_f32_16x16x32_bf16 v[100:103], v[136:139], v[168:171], 0
	v_mfma_f32_16x16x32_bf16 v[92:95], v[144:147], v[168:171], 0
	s_waitcnt lgkmcnt(1)
	v_mfma_f32_16x16x32_bf16 v[84:87], v[136:139], v[176:179], 0
	v_mfma_f32_16x16x32_bf16 v[76:79], v[144:147], v[176:179], 0
	v_mfma_f32_16x16x32_bf16 v[124:127], v[140:143], v[156:159], v[124:127]
	v_mfma_f32_16x16x32_bf16 v[120:123], v[148:151], v[156:159], v[120:123]
	v_mfma_f32_16x16x32_bf16 v[116:119], v[140:143], v[164:167], v[116:119]
	v_mfma_f32_16x16x32_bf16 v[108:111], v[148:151], v[164:167], v[108:111]
	v_mfma_f32_16x16x32_bf16 v[100:103], v[140:143], v[172:175], v[100:103]
	v_mfma_f32_16x16x32_bf16 v[92:95], v[148:151], v[172:175], v[92:95]
	s_waitcnt lgkmcnt(0)
	v_mfma_f32_16x16x32_bf16 v[84:87], v[140:143], v[180:183], v[84:87]
	v_mfma_f32_16x16x32_bf16 v[76:79], v[148:151], v[180:183], v[76:79]
	s_barrier
	ds_read_b128 v[184:187], v133 offset:16384
	ds_read_b128 v[200:203], v133 offset:17408
	ds_read_b128 v[204:207], v133 offset:18432
	ds_read_b128 v[208:211], v133 offset:19456
	s_cselect_b32 s58, s9, s63
	s_cselect_b32 s59, s7, s64
	s_mov_b32 m0, s26
	s_nop 0
	global_load_lds_dwordx4 v130, s[58:59]
	s_add_u32 s66, s58, 0x2000
	s_addc_u32 s67, s59, 0
	s_mov_b32 m0, s27
	s_nop 0
	global_load_lds_dwordx4 v130, s[66:67]
	s_waitcnt vmcnt(10)
	s_barrier
	s_waitcnt lgkmcnt(3)
	v_mfma_f32_16x16x32_bf16 v[112:115], v[184:187], v[152:155], 0
	s_waitcnt lgkmcnt(1)
	v_mfma_f32_16x16x32_bf16 v[104:107], v[204:207], v[152:155], 0
	v_mfma_f32_16x16x32_bf16 v[96:99], v[184:187], v[160:163], 0
	v_mfma_f32_16x16x32_bf16 v[88:91], v[204:207], v[160:163], 0
	v_mfma_f32_16x16x32_bf16 v[80:83], v[184:187], v[168:171], 0
	v_mfma_f32_16x16x32_bf16 v[72:75], v[204:207], v[168:171], 0
	v_mfma_f32_16x16x32_bf16 v[68:71], v[184:187], v[176:179], 0
	v_mfma_f32_16x16x32_bf16 v[64:67], v[204:207], v[176:179], 0
	v_mfma_f32_16x16x32_bf16 v[112:115], v[200:203], v[156:159], v[112:115]
	s_waitcnt lgkmcnt(0)
	v_mfma_f32_16x16x32_bf16 v[104:107], v[208:211], v[156:159], v[104:107]
	v_mfma_f32_16x16x32_bf16 v[96:99], v[200:203], v[164:167], v[96:99]
	v_mfma_f32_16x16x32_bf16 v[88:91], v[208:211], v[164:167], v[88:91]
	v_mfma_f32_16x16x32_bf16 v[80:83], v[200:203], v[172:175], v[80:83]
	v_mfma_f32_16x16x32_bf16 v[72:75], v[208:211], v[172:175], v[72:75]
	v_mfma_f32_16x16x32_bf16 v[68:71], v[200:203], v[180:183], v[68:71]
	v_mfma_f32_16x16x32_bf16 v[64:67], v[208:211], v[180:183], v[64:67]
	s_barrier
	ds_read_b128 v[152:155], v134 offset:16384
	ds_read_b128 v[156:159], v134 offset:17408
	ds_read_b128 v[160:163], v134 offset:18432
	ds_read_b128 v[164:167], v134 offset:19456
	ds_read_b128 v[168:171], v134 offset:20480
	ds_read_b128 v[172:175], v134 offset:21504
	ds_read_b128 v[176:179], v134 offset:22528
	ds_read_b128 v[180:183], v134 offset:23552
	s_mov_b32 m0, s25
	s_nop 0
	global_load_lds_dwordx4 v130, s[54:55]
	s_add_u32 s66, s54, 0x2000
	s_addc_u32 s67, s55, 0
	s_mov_b32 m0, s28
	s_nop 0
	global_load_lds_dwordx4 v130, s[66:67]
	s_barrier
	s_waitcnt lgkmcnt(7)
	v_mfma_f32_16x16x32_bf16 v[60:63], v[136:139], v[152:155], 0
	v_mfma_f32_16x16x32_bf16 v[56:59], v[144:147], v[152:155], 0
	s_waitcnt lgkmcnt(5)
	v_mfma_f32_16x16x32_bf16 v[52:55], v[136:139], v[160:163], 0
	v_mfma_f32_16x16x32_bf16 v[44:47], v[144:147], v[160:163], 0
	s_waitcnt lgkmcnt(3)
	v_mfma_f32_16x16x32_bf16 v[36:39], v[136:139], v[168:171], 0
	v_mfma_f32_16x16x32_bf16 v[28:31], v[144:147], v[168:171], 0
	s_waitcnt lgkmcnt(1)
	v_mfma_f32_16x16x32_bf16 v[20:23], v[136:139], v[176:179], 0
	v_mfma_f32_16x16x32_bf16 v[12:15], v[144:147], v[176:179], 0
	v_mfma_f32_16x16x32_bf16 v[60:63], v[140:143], v[156:159], v[60:63]
	v_mfma_f32_16x16x32_bf16 v[56:59], v[148:151], v[156:159], v[56:59]
	v_mfma_f32_16x16x32_bf16 v[52:55], v[140:143], v[164:167], v[52:55]
	v_mfma_f32_16x16x32_bf16 v[44:47], v[148:151], v[164:167], v[44:47]
	v_mfma_f32_16x16x32_bf16 v[36:39], v[140:143], v[172:175], v[36:39]
	v_mfma_f32_16x16x32_bf16 v[28:31], v[148:151], v[172:175], v[28:31]
	s_waitcnt lgkmcnt(0)
	v_mfma_f32_16x16x32_bf16 v[20:23], v[140:143], v[180:183], v[20:23]
	v_mfma_f32_16x16x32_bf16 v[12:15], v[148:151], v[180:183], v[12:15]
	s_barrier
; #define PG8_STAGE(bufoff, gbase, hoff, imm) do { _Pragma("unroll") for (int _i = 0; _i < 2; ++_i) { \
;         asm volatile("s_mov_b32 m0, %0\n\ts_nop 0\n\tglobal_load_lds_dwordx4 %1, %2" \
;             :: "s"(lds0 + (unsigned)((bufoff) + _i * 8192)), "v"(voff0), "s"((const char*)(gbase) + (size_t)(hoff) + (size_t)(_i * 8192)) : "memory"); } } while (0)
; #define PG8_LDA(dst, b, h) do { _Pragma("unroll") for (int m = 0; m < 4; ++m) _Pragma("unroll") for (int k = 0; k < 2; ++k) dst[m][k] = *(const LAS bf16x8*)(lds + PG8_SA(b, h) + aoff + m * 2048 + k * 1024); } while (0)
; #define PG8_LDB(dst, b, h) do { _Pragma("unroll") for (int n = 0; n < 2; ++n) _Pragma("unroll") for (int k = 0; k < 2; ++k) dst[n][k] = *(const LAS bf16x8*)(lds + PG8_SB(b, h) + boff + n * 2048 + k * 1024); } while (0)
; #define PG8_MMA(ai, bj, At, Bt) do { __builtin_amdgcn_s_setprio(1); _Pragma("unroll") for (int m = 0; m < 4; ++m) _Pragma("unroll") for (int n = 0; n < 2; ++n) _Pragma("unroll") for (int k = 0; k < 2; ++k) \
;         acc[ai][bj][m][n] = __builtin_amdgcn_mfma_f32_16x16x32_bf16(Bt[n][k], At[m][k], acc[ai][bj][m][n], 0, 0, 0); __builtin_amdgcn_s_setprio(0); } while (0)
; #define PG8_WAIT_V(n) asm volatile("s_waitcnt vmcnt(" #n ")" ::: "memory")
; #define PG8_WAIT_L(n) asm volatile("s_waitcnt lgkmcnt(" #n ")" ::: "memory")
; #define PG8_BAR __builtin_amdgcn_s_barrier()
; #define PG8_SCHED __builtin_amdgcn_sched_barrier(0)
; template <class Epi>
; __device__ __forceinline__ void gemm_phase(LAS unsigned char* lds, const Gemm g, const StaticOrder& S, const Epi& E) {
;     ...
;             PG8_LDA(At, 0, 1); PG8_STAGE(PG8_SA(0, 0), a2, 0, 0);
;             PG8_BAR; PG8_WAIT_L(0); PG8_MMA(1, 0, At, B0); PG8_BAR; PG8_SCHED;
;             PG8_STAGE(PG8_SB(0, 1), b2, hB, 0);
;             PG8_WAIT_V(6); PG8_BAR; PG8_MMA(1, 1, At, B1); PG8_BAR;
;             PG8_LDB(B0, 1, 0); PG8_SCHED; PG8_LDA(At, 1, 0); PG8_STAGE(PG8_SA(0, 1), a2, hA, 0);
;             PG8_WAIT_L(8); PG8_BAR; PG8_WAIT_L(0); PG8_MMA(0, 0, At, B0); PG8_BAR; PG8_SCHED;
;             PG8_LDB(B1, 1, 1); PG8_STAGE(PG8_SB(1, 0), b2 + KS, 0, 0);
;             PG8_BAR; PG8_WAIT_L(0); PG8_MMA(0, 1, At, B1); PG8_BAR;
	s_add_u32 s66, s58, 0x80000
	s_addc_u32 s67, s59, 0
	s_mov_b32 m0, s29
	s_nop 0
	global_load_lds_dwordx4 v130, s[66:67]
	s_add_u32 s66, s58, 0x82000
	s_addc_u32 s67, s59, 0
	s_mov_b32 m0, s30
	s_nop 0
	global_load_lds_dwordx4 v130, s[66:67]
	s_waitcnt vmcnt(10)
	s_barrier
	v_mfma_f32_16x16x32_bf16 v[48:51], v[184:187], v[152:155], 0
	v_mfma_f32_16x16x32_bf16 v[40:43], v[204:207], v[152:155], 0
	v_mfma_f32_16x16x32_bf16 v[32:35], v[184:187], v[160:163], 0
	v_mfma_f32_16x16x32_bf16 v[24:27], v[204:207], v[160:163], 0
	v_mfma_f32_16x16x32_bf16 v[16:19], v[184:187], v[168:171], 0
	v_mfma_f32_16x16x32_bf16 v[8:11], v[204:207], v[168:171], 0
	v_mfma_f32_16x16x32_bf16 v[4:7], v[184:187], v[176:179], 0
	v_mfma_f32_16x16x32_bf16 v[0:3], v[204:207], v[176:179], 0
	v_mfma_f32_16x16x32_bf16 v[48:51], v[200:203], v[156:159], v[48:51]
	v_mfma_f32_16x16x32_bf16 v[40:43], v[208:211], v[156:159], v[40:43]
	v_mfma_f32_16x16x32_bf16 v[32:35], v[200:203], v[164:167], v[32:35]
	v_mfma_f32_16x16x32_bf16 v[24:27], v[208:211], v[164:167], v[24:27]
	v_mfma_f32_16x16x32_bf16 v[16:19], v[200:203], v[172:175], v[16:19]
	v_mfma_f32_16x16x32_bf16 v[8:11], v[208:211], v[172:175], v[8:11]
	v_mfma_f32_16x16x32_bf16 v[4:7], v[200:203], v[180:183], v[4:7]
	v_mfma_f32_16x16x32_bf16 v[0:3], v[208:211], v[180:183], v[0:3]
	s_barrier
	ds_read_b128 v[136:139], v133 offset:32768
	ds_read_b128 v[140:143], v133 offset:33792
	ds_read_b128 v[144:147], v133 offset:34816
	ds_read_b128 v[148:151], v133 offset:35840
	ds_read_b128 v[152:155], v134 offset:32768
	ds_read_b128 v[156:159], v134 offset:33792
	ds_read_b128 v[160:163], v134 offset:34816
	ds_read_b128 v[164:167], v134 offset:35840
	ds_read_b128 v[168:171], v134 offset:36864
	ds_read_b128 v[172:175], v134 offset:37888
	ds_read_b128 v[176:179], v134 offset:38912
	ds_read_b128 v[180:183], v134 offset:39936
	s_add_u32 s66, s54, 0x80000
	s_addc_u32 s67, s55, 0
	s_mov_b32 m0, s34
	s_nop 0
	global_load_lds_dwordx4 v130, s[66:67]
	s_add_u32 s66, s54, 0x82000
	s_addc_u32 s67, s55, 0
	s_mov_b32 m0, s37
	s_nop 0
	global_load_lds_dwordx4 v130, s[66:67]
	s_waitcnt lgkmcnt(8)
	s_waitcnt vmcnt(10)
	s_barrier
	s_waitcnt lgkmcnt(7)
	v_mfma_f32_16x16x32_bf16 v[124:127], v[136:139], v[152:155], v[124:127]
	v_mfma_f32_16x16x32_bf16 v[120:123], v[144:147], v[152:155], v[120:123]
	s_waitcnt lgkmcnt(5)
	v_mfma_f32_16x16x32_bf16 v[116:119], v[136:139], v[160:163], v[116:119]
	v_mfma_f32_16x16x32_bf16 v[108:111], v[144:147], v[160:163], v[108:111]
	s_waitcnt lgkmcnt(3)
	v_mfma_f32_16x16x32_bf16 v[100:103], v[136:139], v[168:171], v[100:103]
	v_mfma_f32_16x16x32_bf16 v[92:95], v[144:147], v[168:171], v[92:95]
	s_waitcnt lgkmcnt(1)
	v_mfma_f32_16x16x32_bf16 v[84:87], v[136:139], v[176:179], v[84:87]
	v_mfma_f32_16x16x32_bf16 v[76:79], v[144:147], v[176:179], v[76:79]
	v_mfma_f32_16x16x32_bf16 v[124:127], v[140:143], v[156:159], v[124:127]
	v_mfma_f32_16x16x32_bf16 v[120:123], v[148:151], v[156:159], v[120:123]
	v_mfma_f32_16x16x32_bf16 v[116:119], v[140:143], v[164:167], v[116:119]
	v_mfma_f32_16x16x32_bf16 v[108:111], v[148:151], v[164:167], v[108:111]
	v_mfma_f32_16x16x32_bf16 v[100:103], v[140:143], v[172:175], v[100:103]
	v_mfma_f32_16x16x32_bf16 v[92:95], v[148:151], v[172:175], v[92:95]
	s_waitcnt lgkmcnt(0)
	v_mfma_f32_16x16x32_bf16 v[84:87], v[140:143], v[180:183], v[84:87]
	v_mfma_f32_16x16x32_bf16 v[76:79], v[148:151], v[180:183], v[76:79]
	s_barrier
	ds_read_b128 v[184:187], v133 offset:49152
	ds_read_b128 v[200:203], v133 offset:50176
	ds_read_b128 v[204:207], v133 offset:51200
	ds_read_b128 v[208:211], v133 offset:52224
	s_add_u32 s66, s58, 0x4000
	s_addc_u32 s67, s59, 0
	s_mov_b32 m0, s38
	s_nop 0
	global_load_lds_dwordx4 v130, s[66:67]
	s_add_u32 s66, s58, 0x6000
	s_addc_u32 s67, s59, 0
	s_mov_b32 m0, s39
	s_nop 0
	global_load_lds_dwordx4 v130, s[66:67]
	s_waitcnt vmcnt(10)
	s_barrier
	s_waitcnt lgkmcnt(3)
	v_mfma_f32_16x16x32_bf16 v[112:115], v[184:187], v[152:155], v[112:115]
	s_waitcnt lgkmcnt(1)
	v_mfma_f32_16x16x32_bf16 v[104:107], v[204:207], v[152:155], v[104:107]
	v_mfma_f32_16x16x32_bf16 v[96:99], v[184:187], v[160:163], v[96:99]
	v_mfma_f32_16x16x32_bf16 v[88:91], v[204:207], v[160:163], v[88:91]
	v_mfma_f32_16x16x32_bf16 v[80:83], v[184:187], v[168:171], v[80:83]
	v_mfma_f32_16x16x32_bf16 v[72:75], v[204:207], v[168:171], v[72:75]
	v_mfma_f32_16x16x32_bf16 v[68:71], v[184:187], v[176:179], v[68:71]
	v_mfma_f32_16x16x32_bf16 v[64:67], v[204:207], v[176:179], v[64:67]
	v_mfma_f32_16x16x32_bf16 v[112:115], v[200:203], v[156:159], v[112:115]
	s_waitcnt lgkmcnt(0)
	v_mfma_f32_16x16x32_bf16 v[104:107], v[208:211], v[156:159], v[104:107]
	v_mfma_f32_16x16x32_bf16 v[96:99], v[200:203], v[164:167], v[96:99]
	v_mfma_f32_16x16x32_bf16 v[88:91], v[208:211], v[164:167], v[88:91]
	v_mfma_f32_16x16x32_bf16 v[80:83], v[200:203], v[172:175], v[80:83]
	v_mfma_f32_16x16x32_bf16 v[72:75], v[208:211], v[172:175], v[72:75]
	v_mfma_f32_16x16x32_bf16 v[68:71], v[200:203], v[180:183], v[68:71]
	v_mfma_f32_16x16x32_bf16 v[64:67], v[208:211], v[180:183], v[64:67]
	s_barrier
	ds_read_b128 v[152:155], v134 offset:49152
	ds_read_b128 v[156:159], v134 offset:50176
	ds_read_b128 v[160:163], v134 offset:51200
	ds_read_b128 v[164:167], v134 offset:52224
	ds_read_b128 v[168:171], v134 offset:53248
	ds_read_b128 v[172:175], v134 offset:54272
	ds_read_b128 v[176:179], v134 offset:55296
	ds_read_b128 v[180:183], v134 offset:56320
	s_add_u32 s66, s54, 0x4000
	s_addc_u32 s67, s55, 0
	s_mov_b32 m0, s40
	s_nop 0
	global_load_lds_dwordx4 v130, s[66:67]
	s_add_u32 s54, s54, 0x6000
	s_addc_u32 s55, s55, 0
	s_mov_b32 m0, s41
	s_nop 0
	global_load_lds_dwordx4 v130, s[54:55]
	s_barrier
; #define PG8_STAGE(bufoff, gbase, hoff, imm) do { _Pragma("unroll") for (int _i = 0; _i < 2; ++_i) { \
;         asm volatile("s_mov_b32 m0, %0\n\ts_nop 0\n\tglobal_load_lds_dwordx4 %1, %2" \
;             :: "s"(lds0 + (unsigned)((bufoff) + _i * 8192)), "v"(voff0), "s"((const char*)(gbase) + (size_t)(hoff) + (size_t)(_i * 8192)) : "memory"); } } while (0)
; #define PG8_LDA(dst, b, h) do { _Pragma("unroll") for (int m = 0; m < 4; ++m) _Pragma("unroll") for (int k = 0; k < 2; ++k) dst[m][k] = *(const LAS bf16x8*)(lds + PG8_SA(b, h) + aoff + m * 2048 + k * 1024); } while (0)
; #define PG8_LDB(dst, b, h) do { _Pragma("unroll") for (int n = 0; n < 2; ++n) _Pragma("unroll") for (int k = 0; k < 2; ++k) dst[n][k] = *(const LAS bf16x8*)(lds + PG8_SB(b, h) + boff + n * 2048 + k * 1024); } while (0)
; #define PG8_WAIT_V(n) asm volatile("s_waitcnt vmcnt(" #n ")" ::: "memory")
; #define PG8_WAIT_L(n) asm volatile("s_waitcnt lgkmcnt(" #n ")" ::: "memory")
; #define PG8_BAR __builtin_amdgcn_s_barrier()
; template <class Epi>
; __device__ __forceinline__ void gemm_phase(LAS unsigned char* lds, const Gemm g, const StaticOrder& S, const Epi& E) {
;     ...
;             PG8_LDB(B0, 0, 0); PG8_SCHED; PG8_LDA(At, 0, 0); PG8_STAGE(PG8_SA(1, 1), aT + KS, hA, 0);
;             PG8_WAIT_L(8); PG8_BAR; PG8_WAIT_L(0); PG8_MMA(0, 0, At, B0); PG8_BAR; PG8_SCHED;
;             PG8_LDB(B1, 0, 1); PG8_STAGE(PG8_SB(0, 0), b2, 0, 0);
;             PG8_BAR; PG8_WAIT_L(0); PG8_MMA(0, 1, At, B1); PG8_BAR;
;             PG8_LDA(At, 0, 1); PG8_STAGE(PG8_SA(0, 0), a2, 0, 0);
;             PG8_BAR; PG8_WAIT_L(0); PG8_MMA(1, 0, At, B0); PG8_BAR; PG8_SCHED;
;             PG8_STAGE(PG8_SB(0, 1), b2, hB, 0);
;             PG8_WAIT_V(6); PG8_BAR; PG8_MMA(1, 1, At, B1); PG8_BAR;
;             PG8_LDB(B0, 1, 0); PG8_SCHED; PG8_LDA(At, 1, 0); PG8_STAGE(PG8_SA(0, 1), a2, hA, 0);
;             PG8_WAIT_L(8); PG8_BAR; PG8_WAIT_L(0); PG8_MMA(0, 0, At, B0); PG8_BAR; PG8_SCHED;
;             PG8_LDB(B1, 1, 1); PG8_STAGE(PG8_SB(1, 0), b2 + KS, 0, 0);
;             PG8_BAR; PG8_WAIT_L(0); PG8_MMA(0, 1, At, B1); PG8_BAR;
;             PG8_LDA(At, 1, 1); PG8_STAGE(PG8_SA(1, 0), a2 + KS, 0, 0);
;             PG8_BAR; PG8_WAIT_L(0); PG8_MMA(1, 0, At, B0); PG8_BAR; PG8_SCHED;
;             PG8_STAGE(PG8_SB(1, 1), b2 + KS, hB, 0);
;             PG8_WAIT_V(6); PG8_BAR; PG8_MMA(1, 1, At, B1); PG8_BAR;
	s_waitcnt lgkmcnt(7)
	v_mfma_f32_16x16x32_bf16 v[60:63], v[136:139], v[152:155], v[60:63]
	v_mfma_f32_16x16x32_bf16 v[56:59], v[144:147], v[152:155], v[56:59]
	s_waitcnt lgkmcnt(5)
	v_mfma_f32_16x16x32_bf16 v[52:55], v[136:139], v[160:163], v[52:55]
	v_mfma_f32_16x16x32_bf16 v[44:47], v[144:147], v[160:163], v[44:47]
	s_waitcnt lgkmcnt(3)
	v_mfma_f32_16x16x32_bf16 v[36:39], v[136:139], v[168:171], v[36:39]
	v_mfma_f32_16x16x32_bf16 v[28:31], v[144:147], v[168:171], v[28:31]
	s_waitcnt lgkmcnt(1)
	v_mfma_f32_16x16x32_bf16 v[20:23], v[136:139], v[176:179], v[20:23]
	v_mfma_f32_16x16x32_bf16 v[12:15], v[144:147], v[176:179], v[12:15]
	v_mfma_f32_16x16x32_bf16 v[60:63], v[140:143], v[156:159], v[60:63]
	v_mfma_f32_16x16x32_bf16 v[56:59], v[148:151], v[156:159], v[56:59]
	v_mfma_f32_16x16x32_bf16 v[52:55], v[140:143], v[164:167], v[52:55]
	v_mfma_f32_16x16x32_bf16 v[44:47], v[148:151], v[164:167], v[44:47]
	v_mfma_f32_16x16x32_bf16 v[36:39], v[140:143], v[172:175], v[36:39]
	v_mfma_f32_16x16x32_bf16 v[28:31], v[148:151], v[172:175], v[28:31]
	s_waitcnt lgkmcnt(0)
	v_mfma_f32_16x16x32_bf16 v[20:23], v[140:143], v[180:183], v[20:23]
	v_mfma_f32_16x16x32_bf16 v[12:15], v[148:151], v[180:183], v[12:15]
	s_barrier
	s_add_u32 s54, s58, 0x84000
	s_addc_u32 s55, s59, 0
	s_mov_b32 m0, s42
	s_nop 0
	global_load_lds_dwordx4 v130, s[54:55]
	s_add_u32 s54, s58, 0x86000
	s_addc_u32 s55, s59, 0
	s_mov_b32 m0, s43
	s_nop 0
	global_load_lds_dwordx4 v130, s[54:55]
	s_waitcnt vmcnt(10)
	s_barrier
	v_mfma_f32_16x16x32_bf16 v[48:51], v[184:187], v[152:155], v[48:51]
	v_mfma_f32_16x16x32_bf16 v[40:43], v[204:207], v[152:155], v[40:43]
	v_mfma_f32_16x16x32_bf16 v[32:35], v[184:187], v[160:163], v[32:35]
	v_mfma_f32_16x16x32_bf16 v[24:27], v[204:207], v[160:163], v[24:27]
	v_mfma_f32_16x16x32_bf16 v[16:19], v[184:187], v[168:171], v[16:19]
	v_mfma_f32_16x16x32_bf16 v[8:11], v[204:207], v[168:171], v[8:11]
	v_mfma_f32_16x16x32_bf16 v[4:7], v[184:187], v[176:179], v[4:7]
	v_mfma_f32_16x16x32_bf16 v[0:3], v[204:207], v[176:179], v[0:3]
	v_mfma_f32_16x16x32_bf16 v[48:51], v[200:203], v[156:159], v[48:51]
	v_mfma_f32_16x16x32_bf16 v[40:43], v[208:211], v[156:159], v[40:43]
	v_mfma_f32_16x16x32_bf16 v[32:35], v[200:203], v[164:167], v[32:35]
	v_mfma_f32_16x16x32_bf16 v[24:27], v[208:211], v[164:167], v[24:27]
	v_mfma_f32_16x16x32_bf16 v[16:19], v[200:203], v[172:175], v[16:19]
	v_mfma_f32_16x16x32_bf16 v[8:11], v[208:211], v[172:175], v[8:11]
	v_mfma_f32_16x16x32_bf16 v[4:7], v[200:203], v[180:183], v[4:7]
	v_mfma_f32_16x16x32_bf16 v[0:3], v[208:211], v[180:183], v[0:3]
	s_add_i32 s65, s65, 2
	s_add_u32 s63, s63, 0x8000
	s_addc_u32 s64, s64, 0
	s_cmp_gt_u32 s65, 29
	s_mov_b64 s[54:55], s[56:57]
	s_barrier
.LBB0_434:
	s_add_u32 s56, s54, 0x8000
	s_addc_u32 s57, s55, 0
	ds_read_b128 v[136:139], v133
	ds_read_b128 v[140:143], v133 offset:1024
	ds_read_b128 v[144:147], v133 offset:2048
	ds_read_b128 v[148:151], v133 offset:3072
	s_add_u32 s58, s54, 0x84000
	s_addc_u32 s59, s55, 0
	s_add_u32 s66, s54, 0x86000
	s_addc_u32 s67, s55, 0
	s_cmp_eq_u32 s65, 28
	s_cselect_b32 s55, s0, s57
	s_cselect_b32 s54, s1, s56
	ds_read_b128 v[152:155], v134
	ds_read_b128 v[156:159], v134 offset:1024
	ds_read_b128 v[160:163], v134 offset:2048
	ds_read_b128 v[164:167], v134 offset:3072
	ds_read_b128 v[168:171], v134 offset:4096
	ds_read_b128 v[172:175], v134 offset:5120
	ds_read_b128 v[176:179], v134 offset:6144
	ds_read_b128 v[180:183], v134 offset:7168
	s_mov_b32 m0, s50
	s_nop 0
	global_load_lds_dwordx4 v130, s[58:59]
	s_mov_b32 m0, s51
	s_nop 0
	global_load_lds_dwordx4 v130, s[66:67]
	s_waitcnt lgkmcnt(8)
	s_waitcnt vmcnt(10)
	s_barrier
	s_waitcnt lgkmcnt(7)
	v_mfma_f32_16x16x32_bf16 v[124:127], v[136:139], v[152:155], v[124:127]
	v_mfma_f32_16x16x32_bf16 v[120:123], v[144:147], v[152:155], v[120:123]
	s_waitcnt lgkmcnt(5)
	v_mfma_f32_16x16x32_bf16 v[116:119], v[136:139], v[160:163], v[116:119]
	v_mfma_f32_16x16x32_bf16 v[108:111], v[144:147], v[160:163], v[108:111]
	s_waitcnt lgkmcnt(3)
	v_mfma_f32_16x16x32_bf16 v[100:103], v[136:139], v[168:171], v[100:103]
	v_mfma_f32_16x16x32_bf16 v[92:95], v[144:147], v[168:171], v[92:95]
	s_waitcnt lgkmcnt(1)
	v_mfma_f32_16x16x32_bf16 v[84:87], v[136:139], v[176:179], v[84:87]
	v_mfma_f32_16x16x32_bf16 v[76:79], v[144:147], v[176:179], v[76:79]
	v_mfma_f32_16x16x32_bf16 v[124:127], v[140:143], v[156:159], v[124:127]
	v_mfma_f32_16x16x32_bf16 v[120:123], v[148:151], v[156:159], v[120:123]
	v_mfma_f32_16x16x32_bf16 v[116:119], v[140:143], v[164:167], v[116:119]
	v_mfma_f32_16x16x32_bf16 v[108:111], v[148:151], v[164:167], v[108:111]
	v_mfma_f32_16x16x32_bf16 v[100:103], v[140:143], v[172:175], v[100:103]
	v_mfma_f32_16x16x32_bf16 v[92:95], v[148:151], v[172:175], v[92:95]
	s_waitcnt lgkmcnt(0)
	v_mfma_f32_16x16x32_bf16 v[84:87], v[140:143], v[180:183], v[84:87]
	v_mfma_f32_16x16x32_bf16 v[76:79], v[148:151], v[180:183], v[76:79]
	s_barrier
	ds_read_b128 v[184:187], v133 offset:16384
	ds_read_b128 v[200:203], v133 offset:17408
	ds_read_b128 v[204:207], v133 offset:18432
	ds_read_b128 v[208:211], v133 offset:19456
	s_cselect_b32 s58, s9, s63
	s_cselect_b32 s59, s7, s64
	s_mov_b32 m0, s26
	s_nop 0
	global_load_lds_dwordx4 v130, s[58:59]
	s_add_u32 s66, s58, 0x2000
	s_addc_u32 s67, s59, 0
	s_mov_b32 m0, s27
	s_nop 0
	global_load_lds_dwordx4 v130, s[66:67]
	s_waitcnt vmcnt(10)
	s_barrier
; #define PG8_STAGE(bufoff, gbase, hoff, imm) do { _Pragma("unroll") for (int _i = 0; _i < 2; ++_i) { \
;         asm volatile("s_mov_b32 m0, %0\n\ts_nop 0\n\tglobal_load_lds_dwordx4 %1, %2" \
;             :: "s"(lds0 + (unsigned)((bufoff) + _i * 8192)), "v"(voff0), "s"((const char*)(gbase) + (size_t)(hoff) + (size_t)(_i * 8192)) : "memory"); } } while (0)
; #define PG8_LDA(dst, b, h) do { _Pragma("unroll") for (int m = 0; m < 4; ++m) _Pragma("unroll") for (int k = 0; k < 2; ++k) dst[m][k] = *(const LAS bf16x8*)(lds + PG8_SA(b, h) + aoff + m * 2048 + k * 1024); } while (0)
; #define PG8_LDB(dst, b, h) do { _Pragma("unroll") for (int n = 0; n < 2; ++n) _Pragma("unroll") for (int k = 0; k < 2; ++k) dst[n][k] = *(const LAS bf16x8*)(lds + PG8_SB(b, h) + boff + n * 2048 + k * 1024); } while (0)
; #define PG8_WAIT_V(n) asm volatile("s_waitcnt vmcnt(" #n ")" ::: "memory")
; #define PG8_WAIT_L(n) asm volatile("s_waitcnt lgkmcnt(" #n ")" ::: "memory")
; #define PG8_BAR __builtin_amdgcn_s_barrier()
; template <class Epi>
; __device__ __forceinline__ void gemm_phase(LAS unsigned char* lds, const Gemm g, const StaticOrder& S, const Epi& E) {
;     ...
;             PG8_LDB(B0, 0, 0); PG8_SCHED; PG8_LDA(At, 0, 0); PG8_STAGE(PG8_SA(1, 1), aT + KS, hA, 0);
;             PG8_WAIT_L(8); PG8_BAR; PG8_WAIT_L(0); PG8_MMA(0, 0, At, B0); PG8_BAR; PG8_SCHED;
;             PG8_LDB(B1, 0, 1); PG8_STAGE(PG8_SB(0, 0), b2, 0, 0);
;             PG8_BAR; PG8_WAIT_L(0); PG8_MMA(0, 1, At, B1); PG8_BAR;
;             PG8_LDA(At, 0, 1); PG8_STAGE(PG8_SA(0, 0), a2, 0, 0);
;             PG8_BAR; PG8_WAIT_L(0); PG8_MMA(1, 0, At, B0); PG8_BAR; PG8_SCHED;
;             PG8_STAGE(PG8_SB(0, 1), b2, hB, 0);
;             PG8_WAIT_V(6); PG8_BAR; PG8_MMA(1, 1, At, B1); PG8_BAR;
;             PG8_LDB(B0, 1, 0); PG8_SCHED; PG8_LDA(At, 1, 0); PG8_STAGE(PG8_SA(0, 1), a2, hA, 0);
;             PG8_WAIT_L(8); PG8_BAR; PG8_WAIT_L(0); PG8_MMA(0, 0, At, B0); PG8_BAR; PG8_SCHED;
;             PG8_LDB(B1, 1, 1); PG8_STAGE(PG8_SB(1, 0), b2 + KS, 0, 0);
;             PG8_BAR; PG8_WAIT_L(0); PG8_MMA(0, 1, At, B1); PG8_BAR;
;             PG8_LDA(At, 1, 1); PG8_STAGE(PG8_SA(1, 0), a2 + KS, 0, 0);
;             PG8_BAR; PG8_WAIT_L(0); PG8_MMA(1, 0, At, B0); PG8_BAR; PG8_SCHED;
;             PG8_STAGE(PG8_SB(1, 1), b2 + KS, hB, 0);
;             PG8_WAIT_V(6); PG8_BAR; PG8_MMA(1, 1, At, B1); PG8_BAR;
	s_waitcnt lgkmcnt(3)
	v_mfma_f32_16x16x32_bf16 v[112:115], v[184:187], v[152:155], v[112:115]
	s_waitcnt lgkmcnt(1)
	v_mfma_f32_16x16x32_bf16 v[104:107], v[204:207], v[152:155], v[104:107]
	v_mfma_f32_16x16x32_bf16 v[96:99], v[184:187], v[160:163], v[96:99]
	v_mfma_f32_16x16x32_bf16 v[88:91], v[204:207], v[160:163], v[88:91]
	v_mfma_f32_16x16x32_bf16 v[80:83], v[184:187], v[168:171], v[80:83]
	v_mfma_f32_16x16x32_bf16 v[72:75], v[204:207], v[168:171], v[72:75]
	v_mfma_f32_16x16x32_bf16 v[68:71], v[184:187], v[176:179], v[68:71]
	v_mfma_f32_16x16x32_bf16 v[64:67], v[204:207], v[176:179], v[64:67]
	v_mfma_f32_16x16x32_bf16 v[112:115], v[200:203], v[156:159], v[112:115]
	s_waitcnt lgkmcnt(0)
	v_mfma_f32_16x16x32_bf16 v[104:107], v[208:211], v[156:159], v[104:107]
	v_mfma_f32_16x16x32_bf16 v[96:99], v[200:203], v[164:167], v[96:99]
	v_mfma_f32_16x16x32_bf16 v[88:91], v[208:211], v[164:167], v[88:91]
	v_mfma_f32_16x16x32_bf16 v[80:83], v[200:203], v[172:175], v[80:83]
	v_mfma_f32_16x16x32_bf16 v[72:75], v[208:211], v[172:175], v[72:75]
	v_mfma_f32_16x16x32_bf16 v[68:71], v[200:203], v[180:183], v[68:71]
	v_mfma_f32_16x16x32_bf16 v[64:67], v[208:211], v[180:183], v[64:67]
	s_barrier
	ds_read_b128 v[152:155], v134 offset:16384
	ds_read_b128 v[156:159], v134 offset:17408
	ds_read_b128 v[160:163], v134 offset:18432
	ds_read_b128 v[164:167], v134 offset:19456
	ds_read_b128 v[168:171], v134 offset:20480
	ds_read_b128 v[172:175], v134 offset:21504
	ds_read_b128 v[176:179], v134 offset:22528
	ds_read_b128 v[180:183], v134 offset:23552
	s_mov_b32 m0, s25
	s_nop 0
	global_load_lds_dwordx4 v130, s[54:55]
	s_add_u32 s66, s54, 0x2000
	s_addc_u32 s67, s55, 0
	s_mov_b32 m0, s28
	s_nop 0
	global_load_lds_dwordx4 v130, s[66:67]
	s_barrier
	s_waitcnt lgkmcnt(7)
	v_mfma_f32_16x16x32_bf16 v[60:63], v[136:139], v[152:155], v[60:63]
	v_mfma_f32_16x16x32_bf16 v[56:59], v[144:147], v[152:155], v[56:59]
	s_waitcnt lgkmcnt(5)
	v_mfma_f32_16x16x32_bf16 v[52:55], v[136:139], v[160:163], v[52:55]
	v_mfma_f32_16x16x32_bf16 v[44:47], v[144:147], v[160:163], v[44:47]
	s_waitcnt lgkmcnt(3)
	v_mfma_f32_16x16x32_bf16 v[36:39], v[136:139], v[168:171], v[36:39]
	v_mfma_f32_16x16x32_bf16 v[28:31], v[144:147], v[168:171], v[28:31]
	s_waitcnt lgkmcnt(1)
	v_mfma_f32_16x16x32_bf16 v[20:23], v[136:139], v[176:179], v[20:23]
	v_mfma_f32_16x16x32_bf16 v[12:15], v[144:147], v[176:179], v[12:15]
	v_mfma_f32_16x16x32_bf16 v[60:63], v[140:143], v[156:159], v[60:63]
	v_mfma_f32_16x16x32_bf16 v[56:59], v[148:151], v[156:159], v[56:59]
	v_mfma_f32_16x16x32_bf16 v[52:55], v[140:143], v[164:167], v[52:55]
	v_mfma_f32_16x16x32_bf16 v[44:47], v[148:151], v[164:167], v[44:47]
	v_mfma_f32_16x16x32_bf16 v[36:39], v[140:143], v[172:175], v[36:39]
	v_mfma_f32_16x16x32_bf16 v[28:31], v[148:151], v[172:175], v[28:31]
	s_waitcnt lgkmcnt(0)
	v_mfma_f32_16x16x32_bf16 v[20:23], v[140:143], v[180:183], v[20:23]
	v_mfma_f32_16x16x32_bf16 v[12:15], v[148:151], v[180:183], v[12:15]
	s_barrier
	s_add_u32 s66, s58, 0x80000
	s_addc_u32 s67, s59, 0
	s_mov_b32 m0, s29
	s_nop 0
	global_load_lds_dwordx4 v130, s[66:67]
	s_add_u32 s66, s58, 0x82000
	s_addc_u32 s67, s59, 0
	s_mov_b32 m0, s30
	s_nop 0
	global_load_lds_dwordx4 v130, s[66:67]
	s_waitcnt vmcnt(10)
	s_barrier
	v_mfma_f32_16x16x32_bf16 v[48:51], v[184:187], v[152:155], v[48:51]
	v_mfma_f32_16x16x32_bf16 v[40:43], v[204:207], v[152:155], v[40:43]
	v_mfma_f32_16x16x32_bf16 v[32:35], v[184:187], v[160:163], v[32:35]
	v_mfma_f32_16x16x32_bf16 v[24:27], v[204:207], v[160:163], v[24:27]
	v_mfma_f32_16x16x32_bf16 v[16:19], v[184:187], v[168:171], v[16:19]
	v_mfma_f32_16x16x32_bf16 v[8:11], v[204:207], v[168:171], v[8:11]
	v_mfma_f32_16x16x32_bf16 v[4:7], v[184:187], v[176:179], v[4:7]
	v_mfma_f32_16x16x32_bf16 v[0:3], v[204:207], v[176:179], v[0:3]
	v_mfma_f32_16x16x32_bf16 v[48:51], v[200:203], v[156:159], v[48:51]
	v_mfma_f32_16x16x32_bf16 v[40:43], v[208:211], v[156:159], v[40:43]
	v_mfma_f32_16x16x32_bf16 v[32:35], v[200:203], v[164:167], v[32:35]
	v_mfma_f32_16x16x32_bf16 v[24:27], v[208:211], v[164:167], v[24:27]
	v_mfma_f32_16x16x32_bf16 v[16:19], v[200:203], v[172:175], v[16:19]
	v_mfma_f32_16x16x32_bf16 v[8:11], v[208:211], v[172:175], v[8:11]
	v_mfma_f32_16x16x32_bf16 v[4:7], v[200:203], v[180:183], v[4:7]
	v_mfma_f32_16x16x32_bf16 v[0:3], v[208:211], v[180:183], v[0:3]
	s_barrier
	ds_read_b128 v[136:139], v133 offset:32768
	ds_read_b128 v[140:143], v133 offset:33792
	ds_read_b128 v[144:147], v133 offset:34816
	ds_read_b128 v[148:151], v133 offset:35840
	ds_read_b128 v[152:155], v134 offset:32768
	ds_read_b128 v[156:159], v134 offset:33792
	ds_read_b128 v[160:163], v134 offset:34816
	ds_read_b128 v[164:167], v134 offset:35840
	ds_read_b128 v[168:171], v134 offset:36864
	ds_read_b128 v[172:175], v134 offset:37888
	ds_read_b128 v[176:179], v134 offset:38912
	ds_read_b128 v[180:183], v134 offset:39936
	s_add_u32 s66, s54, 0x80000
	s_addc_u32 s67, s55, 0
	s_mov_b32 m0, s34
	s_nop 0
	global_load_lds_dwordx4 v130, s[66:67]
	s_add_u32 s66, s54, 0x82000
	s_addc_u32 s67, s55, 0
	s_mov_b32 m0, s37
	s_nop 0
	global_load_lds_dwordx4 v130, s[66:67]
	s_waitcnt lgkmcnt(8)
	s_waitcnt vmcnt(10)
	s_barrier
; #define PG8_STAGE(bufoff, gbase, hoff, imm) do { _Pragma("unroll") for (int _i = 0; _i < 2; ++_i) { \
;         asm volatile("s_mov_b32 m0, %0\n\ts_nop 0\n\tglobal_load_lds_dwordx4 %1, %2" \
;             :: "s"(lds0 + (unsigned)((bufoff) + _i * 8192)), "v"(voff0), "s"((const char*)(gbase) + (size_t)(hoff) + (size_t)(_i * 8192)) : "memory"); } } while (0)
; #define PG8_LDA(dst, b, h) do { _Pragma("unroll") for (int m = 0; m < 4; ++m) _Pragma("unroll") for (int k = 0; k < 2; ++k) dst[m][k] = *(const LAS bf16x8*)(lds + PG8_SA(b, h) + aoff + m * 2048 + k * 1024); } while (0)
; #define PG8_LDB(dst, b, h) do { _Pragma("unroll") for (int n = 0; n < 2; ++n) _Pragma("unroll") for (int k = 0; k < 2; ++k) dst[n][k] = *(const LAS bf16x8*)(lds + PG8_SB(b, h) + boff + n * 2048 + k * 1024); } while (0)
; #define PG8_MMA(ai, bj, At, Bt) do { __builtin_amdgcn_s_setprio(1); _Pragma("unroll") for (int m = 0; m < 4; ++m) _Pragma("unroll") for (int n = 0; n < 2; ++n) _Pragma("unroll") for (int k = 0; k < 2; ++k) \
;         acc[ai][bj][m][n] = __builtin_amdgcn_mfma_f32_16x16x32_bf16(Bt[n][k], At[m][k], acc[ai][bj][m][n], 0, 0, 0); __builtin_amdgcn_s_setprio(0); } while (0)
; #define PG8_WAIT_V(n) asm volatile("s_waitcnt vmcnt(" #n ")" ::: "memory")
; #define PG8_WAIT_L(n) asm volatile("s_waitcnt lgkmcnt(" #n ")" ::: "memory")
; #define PG8_BAR __builtin_amdgcn_s_barrier()
; #define PG8_SCHED __builtin_amdgcn_sched_barrier(0)
; template <class Epi>
; __device__ __forceinline__ void gemm_phase(LAS unsigned char* lds, const Gemm g, const StaticOrder& S, const Epi& E) {
;     ...
;             PG8_LDB(B0, 1, 0); PG8_SCHED; PG8_LDA(At, 1, 0); PG8_STAGE(PG8_SA(0, 1), a2, hA, 0);
;             PG8_WAIT_L(8); PG8_BAR; PG8_WAIT_L(0); PG8_MMA(0, 0, At, B0); PG8_BAR; PG8_SCHED;
;             PG8_LDB(B1, 1, 1); PG8_STAGE(PG8_SB(1, 0), b2 + KS, 0, 0);
;             PG8_BAR; PG8_WAIT_L(0); PG8_MMA(0, 1, At, B1); PG8_BAR;
;             PG8_LDA(At, 1, 1); PG8_STAGE(PG8_SA(1, 0), a2 + KS, 0, 0);
;             PG8_BAR; PG8_WAIT_L(0); PG8_MMA(1, 0, At, B0); PG8_BAR; PG8_SCHED;
;             PG8_STAGE(PG8_SB(1, 1), b2 + KS, hB, 0);
;             PG8_WAIT_V(6); PG8_BAR; PG8_MMA(1, 1, At, B1); PG8_BAR;
;     ...
;     if (wr == 0) PG8_BAR;
	s_waitcnt lgkmcnt(7)
	v_mfma_f32_16x16x32_bf16 v[124:127], v[136:139], v[152:155], v[124:127]
	v_mfma_f32_16x16x32_bf16 v[120:123], v[144:147], v[152:155], v[120:123]
	s_waitcnt lgkmcnt(5)
	v_mfma_f32_16x16x32_bf16 v[116:119], v[136:139], v[160:163], v[116:119]
	v_mfma_f32_16x16x32_bf16 v[108:111], v[144:147], v[160:163], v[108:111]
	s_waitcnt lgkmcnt(3)
	v_mfma_f32_16x16x32_bf16 v[100:103], v[136:139], v[168:171], v[100:103]
	v_mfma_f32_16x16x32_bf16 v[92:95], v[144:147], v[168:171], v[92:95]
	s_waitcnt lgkmcnt(1)
	v_mfma_f32_16x16x32_bf16 v[84:87], v[136:139], v[176:179], v[84:87]
	v_mfma_f32_16x16x32_bf16 v[76:79], v[144:147], v[176:179], v[76:79]
	v_mfma_f32_16x16x32_bf16 v[124:127], v[140:143], v[156:159], v[124:127]
	v_mfma_f32_16x16x32_bf16 v[120:123], v[148:151], v[156:159], v[120:123]
	v_mfma_f32_16x16x32_bf16 v[116:119], v[140:143], v[164:167], v[116:119]
	v_mfma_f32_16x16x32_bf16 v[108:111], v[148:151], v[164:167], v[108:111]
	v_mfma_f32_16x16x32_bf16 v[100:103], v[140:143], v[172:175], v[100:103]
	v_mfma_f32_16x16x32_bf16 v[92:95], v[148:151], v[172:175], v[92:95]
	s_waitcnt lgkmcnt(0)
	v_mfma_f32_16x16x32_bf16 v[84:87], v[140:143], v[180:183], v[84:87]
	v_mfma_f32_16x16x32_bf16 v[76:79], v[148:151], v[180:183], v[76:79]
	s_barrier
	ds_read_b128 v[184:187], v133 offset:49152
	ds_read_b128 v[200:203], v133 offset:50176
	ds_read_b128 v[204:207], v133 offset:51200
	ds_read_b128 v[208:211], v133 offset:52224
	s_add_u32 s66, s58, 0x4000
	s_addc_u32 s67, s59, 0
	s_mov_b32 m0, s38
	s_nop 0
	global_load_lds_dwordx4 v130, s[66:67]
	s_add_u32 s66, s58, 0x6000
	s_addc_u32 s67, s59, 0
	s_mov_b32 m0, s39
	s_nop 0
	global_load_lds_dwordx4 v130, s[66:67]
	s_waitcnt vmcnt(10)
	s_barrier
	s_waitcnt lgkmcnt(3)
	v_mfma_f32_16x16x32_bf16 v[112:115], v[184:187], v[152:155], v[112:115]
	s_waitcnt lgkmcnt(1)
	v_mfma_f32_16x16x32_bf16 v[104:107], v[204:207], v[152:155], v[104:107]
	v_mfma_f32_16x16x32_bf16 v[96:99], v[184:187], v[160:163], v[96:99]
	v_mfma_f32_16x16x32_bf16 v[88:91], v[204:207], v[160:163], v[88:91]
	v_mfma_f32_16x16x32_bf16 v[80:83], v[184:187], v[168:171], v[80:83]
	v_mfma_f32_16x16x32_bf16 v[72:75], v[204:207], v[168:171], v[72:75]
	v_mfma_f32_16x16x32_bf16 v[68:71], v[184:187], v[176:179], v[68:71]
	v_mfma_f32_16x16x32_bf16 v[64:67], v[204:207], v[176:179], v[64:67]
	v_mfma_f32_16x16x32_bf16 v[112:115], v[200:203], v[156:159], v[112:115]
	s_waitcnt lgkmcnt(0)
	v_mfma_f32_16x16x32_bf16 v[104:107], v[208:211], v[156:159], v[104:107]
	v_mfma_f32_16x16x32_bf16 v[96:99], v[200:203], v[164:167], v[96:99]
	v_mfma_f32_16x16x32_bf16 v[88:91], v[208:211], v[164:167], v[88:91]
	v_mfma_f32_16x16x32_bf16 v[80:83], v[200:203], v[172:175], v[80:83]
	v_mfma_f32_16x16x32_bf16 v[72:75], v[208:211], v[172:175], v[72:75]
	v_mfma_f32_16x16x32_bf16 v[68:71], v[200:203], v[180:183], v[68:71]
	v_mfma_f32_16x16x32_bf16 v[64:67], v[208:211], v[180:183], v[64:67]
	s_barrier
	ds_read_b128 v[152:155], v134 offset:49152
	ds_read_b128 v[156:159], v134 offset:50176
	ds_read_b128 v[160:163], v134 offset:51200
	ds_read_b128 v[164:167], v134 offset:52224
	ds_read_b128 v[168:171], v134 offset:53248
	ds_read_b128 v[172:175], v134 offset:54272
	ds_read_b128 v[176:179], v134 offset:55296
	ds_read_b128 v[180:183], v134 offset:56320
	s_add_u32 s66, s54, 0x4000
	s_addc_u32 s67, s55, 0
	s_mov_b32 m0, s40
	s_nop 0
	global_load_lds_dwordx4 v130, s[66:67]
	s_add_u32 s54, s54, 0x6000
	s_addc_u32 s55, s55, 0
	s_mov_b32 m0, s41
	s_nop 0
	global_load_lds_dwordx4 v130, s[54:55]
	s_barrier
	s_waitcnt lgkmcnt(7)
	v_mfma_f32_16x16x32_bf16 v[60:63], v[136:139], v[152:155], v[60:63]
	v_mfma_f32_16x16x32_bf16 v[56:59], v[144:147], v[152:155], v[56:59]
	s_waitcnt lgkmcnt(5)
	v_mfma_f32_16x16x32_bf16 v[52:55], v[136:139], v[160:163], v[52:55]
	v_mfma_f32_16x16x32_bf16 v[44:47], v[144:147], v[160:163], v[44:47]
	s_waitcnt lgkmcnt(3)
	v_mfma_f32_16x16x32_bf16 v[36:39], v[136:139], v[168:171], v[36:39]
	v_mfma_f32_16x16x32_bf16 v[28:31], v[144:147], v[168:171], v[28:31]
	s_waitcnt lgkmcnt(1)
	v_mfma_f32_16x16x32_bf16 v[20:23], v[136:139], v[176:179], v[20:23]
	v_mfma_f32_16x16x32_bf16 v[12:15], v[144:147], v[176:179], v[12:15]
	v_mfma_f32_16x16x32_bf16 v[60:63], v[140:143], v[156:159], v[60:63]
	v_mfma_f32_16x16x32_bf16 v[56:59], v[148:151], v[156:159], v[56:59]
	v_mfma_f32_16x16x32_bf16 v[52:55], v[140:143], v[164:167], v[52:55]
	v_mfma_f32_16x16x32_bf16 v[44:47], v[148:151], v[164:167], v[44:47]
	v_mfma_f32_16x16x32_bf16 v[36:39], v[140:143], v[172:175], v[36:39]
	v_mfma_f32_16x16x32_bf16 v[28:31], v[148:151], v[172:175], v[28:31]
	s_waitcnt lgkmcnt(0)
	v_mfma_f32_16x16x32_bf16 v[20:23], v[140:143], v[180:183], v[20:23]
	v_mfma_f32_16x16x32_bf16 v[12:15], v[148:151], v[180:183], v[12:15]
	s_barrier
	s_add_u32 s54, s58, 0x84000
	s_addc_u32 s55, s59, 0
	s_mov_b32 m0, s42
	s_nop 0
	global_load_lds_dwordx4 v130, s[54:55]
	s_add_u32 s54, s58, 0x86000
	s_addc_u32 s55, s59, 0
	s_mov_b32 m0, s43
	s_nop 0
	global_load_lds_dwordx4 v130, s[54:55]
	s_waitcnt vmcnt(10)
	s_barrier
	v_mfma_f32_16x16x32_bf16 v[48:51], v[184:187], v[152:155], v[48:51]
	v_mfma_f32_16x16x32_bf16 v[40:43], v[204:207], v[152:155], v[40:43]
	v_mfma_f32_16x16x32_bf16 v[32:35], v[184:187], v[160:163], v[32:35]
	v_mfma_f32_16x16x32_bf16 v[24:27], v[204:207], v[160:163], v[24:27]
	v_mfma_f32_16x16x32_bf16 v[16:19], v[184:187], v[168:171], v[16:19]
	v_mfma_f32_16x16x32_bf16 v[8:11], v[204:207], v[168:171], v[8:11]
	v_mfma_f32_16x16x32_bf16 v[4:7], v[184:187], v[176:179], v[4:7]
	v_mfma_f32_16x16x32_bf16 v[0:3], v[204:207], v[176:179], v[0:3]
	v_mfma_f32_16x16x32_bf16 v[48:51], v[200:203], v[156:159], v[48:51]
	v_mfma_f32_16x16x32_bf16 v[40:43], v[208:211], v[156:159], v[40:43]
	v_mfma_f32_16x16x32_bf16 v[32:35], v[200:203], v[164:167], v[32:35]
	v_mfma_f32_16x16x32_bf16 v[24:27], v[208:211], v[164:167], v[24:27]
	v_mfma_f32_16x16x32_bf16 v[16:19], v[200:203], v[172:175], v[16:19]
	v_mfma_f32_16x16x32_bf16 v[8:11], v[208:211], v[172:175], v[8:11]
	v_mfma_f32_16x16x32_bf16 v[4:7], v[200:203], v[180:183], v[4:7]
	v_mfma_f32_16x16x32_bf16 v[0:3], v[208:211], v[180:183], v[0:3]
	s_add_i32 s65, s65, 2
	s_add_u32 s63, s63, 0x8000
	s_addc_u32 s64, s64, 0
	s_cmp_gt_u32 s65, 29
	s_mov_b64 s[54:55], s[56:57]
	s_barrier
	s_cbranch_scc0 .LBB0_434
	v_readfirstlane_b32 s66, v235
	s_nop 1
	s_cmpk_lt_u32 s66, 0x100
	s_cbranch_scc0 .Lbg_al_skip
	s_barrier
; #define LAS __attribute__((address_space(3)))
; __device__ __forceinline__ unsigned cvt_pk_bf16(float lo, float hi) { unsigned r; asm volatile("v_cvt_pk_bf16_f32 %0, %1, %2" : "=v"(r) : "v"(lo), "v"(hi)); return r; }
;     __device__ __forceinline__ void operator()(f32x4 (&acc)[2][2][4][2], const Unit& u, int wr, int wc, int fr, int fq, LAS unsigned char*) const {
;         const int row0 = u.pm * BM + wr * 64 + fr, col0 = u.pn * BM + wc * 32 + 8 * fq;
; #pragma unroll
;         for (int ai = 0; ai < 2; ++ai)
; #pragma unroll
;             for (int m = 0; m < 4; ++m) { bf16_t* rowp = O + (size_t)(row0 + ai * HALF + m * 16) * ldc + col0;
; #pragma unroll
;                 for (int bj = 0; bj < 2; ++bj) { const f32x4 v0 = acc[ai][bj][m][0], v1 = acc[ai][bj][m][1];
;                     u32x4 w; w.x = cvt_pk_bf16(v0[0], v0[1]); w.y = cvt_pk_bf16(v0[2], v0[3]); w.z = cvt_pk_bf16(v1[0], v1[1]); w.w = cvt_pk_bf16(v1[2], v1[3]);
;                     *(u32x4*)(rowp + bj * HALF) = w; } }
;     }
.Lbg_al_skip:
	v_lshl_add_u32 v136, s62, 8, v131
	v_lshl_or_b32 v128, s61, 8, v132
	v_ashrrev_i32_e32 v137, 31, v136
	v_ashrrev_i32_e32 v129, 31, v128
	v_lshlrev_b64 v[138:139], 12, v[136:137]
	v_lshl_add_u64 v[138:139], s[2:3], 0, v[138:139]
	v_lshlrev_b64 v[140:141], 1, v[128:129]
	v_lshl_add_u64 v[128:129], v[138:139], 0, v[140:141]
	v_cvt_pk_bf16_f32 v124, v124, v125
	v_cvt_pk_bf16_f32 v125, v126, v127
	v_cvt_pk_bf16_f32 v126, v120, v121
	v_cvt_pk_bf16_f32 v127, v122, v123
	global_store_dwordx4 v[128:129], v[124:127], off
	v_cvt_pk_bf16_f32 v112, v112, v113
	v_cvt_pk_bf16_f32 v113, v114, v115
	v_cvt_pk_bf16_f32 v114, v104, v105
	v_or_b32_e32 v104, 16, v136
	v_ashrrev_i32_e32 v105, 31, v104
	v_lshlrev_b64 v[104:105], 12, v[104:105]
	v_lshl_add_u64 v[104:105], s[2:3], 0, v[104:105]
	v_cvt_pk_bf16_f32 v115, v106, v107
	global_store_dwordx4 v[128:129], v[112:115], off offset:256
	s_mov_b64 s[0:1], 0x80000
	s_mov_b32 s61, s6
	v_lshl_add_u64 v[112:113], v[104:105], 0, v[140:141]
	v_cvt_pk_bf16_f32 v104, v116, v117
	v_cvt_pk_bf16_f32 v105, v118, v119
	v_cvt_pk_bf16_f32 v106, v108, v109
	v_cvt_pk_bf16_f32 v107, v110, v111
	global_store_dwordx4 v[112:113], v[104:107], off
	v_cvt_pk_bf16_f32 v96, v96, v97
	v_cvt_pk_bf16_f32 v97, v98, v99
	v_cvt_pk_bf16_f32 v98, v88, v89
	v_or_b32_e32 v88, 32, v136
	v_ashrrev_i32_e32 v89, 31, v88
	v_lshlrev_b64 v[88:89], 12, v[88:89]
	v_lshl_add_u64 v[88:89], s[2:3], 0, v[88:89]
	v_cvt_pk_bf16_f32 v99, v90, v91
	global_store_dwordx4 v[112:113], v[96:99], off offset:256
	s_mov_b32 s62, s8
	s_mov_b64 s[56:57], s[52:53]
	v_lshl_add_u64 v[96:97], v[88:89], 0, v[140:141]
	v_cvt_pk_bf16_f32 v88, v100, v101
	v_cvt_pk_bf16_f32 v89, v102, v103
	v_cvt_pk_bf16_f32 v90, v92, v93
	v_cvt_pk_bf16_f32 v91, v94, v95
	global_store_dwordx4 v[96:97], v[88:91], off
	v_cvt_pk_bf16_f32 v80, v80, v81
	v_cvt_pk_bf16_f32 v81, v82, v83
	v_cvt_pk_bf16_f32 v82, v72, v73
	v_or_b32_e32 v72, 48, v136
	v_ashrrev_i32_e32 v73, 31, v72
	v_lshlrev_b64 v[72:73], 12, v[72:73]
	v_lshl_add_u64 v[72:73], s[2:3], 0, v[72:73]
	v_cvt_pk_bf16_f32 v83, v74, v75
	global_store_dwordx4 v[96:97], v[80:83], off offset:256
	s_mov_b64 s[54:55], s[10:11]
	s_nop 0
	v_lshl_add_u64 v[80:81], v[72:73], 0, v[140:141]
	v_cvt_pk_bf16_f32 v72, v84, v85
	v_cvt_pk_bf16_f32 v73, v86, v87
	v_cvt_pk_bf16_f32 v74, v76, v77
	v_cvt_pk_bf16_f32 v75, v78, v79
	global_store_dwordx4 v[80:81], v[72:75], off
	v_cvt_pk_bf16_f32 v68, v68, v69
	v_cvt_pk_bf16_f32 v69, v70, v71
	v_cvt_pk_bf16_f32 v70, v64, v65
	v_cvt_pk_bf16_f32 v71, v66, v67
	global_store_dwordx4 v[80:81], v[68:71], off offset:256
	v_cvt_pk_bf16_f32 v60, v60, v61
	v_cvt_pk_bf16_f32 v61, v62, v63
	v_cvt_pk_bf16_f32 v62, v56, v57
	v_add_co_u32_e32 v56, vcc, s93, v128
	v_lshl_add_u64 v[64:65], v[128:129], 0, s[0:1]
	s_nop 0
	v_addc_co_u32_e32 v57, vcc, 0, v129, vcc
	v_cvt_pk_bf16_f32 v63, v58, v59
	global_store_dwordx4 v[56:57], v[60:63], off
	v_cvt_pk_bf16_f32 v48, v48, v49
	v_cvt_pk_bf16_f32 v49, v50, v51
	v_cvt_pk_bf16_f32 v50, v40, v41
	v_cvt_pk_bf16_f32 v51, v42, v43
	global_store_dwordx4 v[64:65], v[48:51], off offset:256
	s_mov_b64 s[0:1], 0x90000
	v_cvt_pk_bf16_f32 v40, v52, v53
	v_cvt_pk_bf16_f32 v41, v54, v55
	v_cvt_pk_bf16_f32 v42, v44, v45
	v_add_co_u32_e32 v44, vcc, s33, v128
	v_lshl_add_u64 v[48:49], v[128:129], 0, s[0:1]
	s_nop 0
	v_addc_co_u32_e32 v45, vcc, 0, v129, vcc
	v_cvt_pk_bf16_f32 v43, v46, v47
	global_store_dwordx4 v[44:45], v[40:43], off
	v_cvt_pk_bf16_f32 v32, v32, v33
	v_cvt_pk_bf16_f32 v33, v34, v35
	v_cvt_pk_bf16_f32 v34, v24, v25
	v_cvt_pk_bf16_f32 v35, v26, v27
	global_store_dwordx4 v[48:49], v[32:35], off offset:256
	s_mov_b64 s[0:1], 0xa0000
	v_cvt_pk_bf16_f32 v24, v36, v37
	v_cvt_pk_bf16_f32 v25, v38, v39
	v_cvt_pk_bf16_f32 v26, v28, v29
	v_add_co_u32_e32 v28, vcc, s18, v128
	v_lshl_add_u64 v[32:33], v[128:129], 0, s[0:1]
	s_nop 0
	v_addc_co_u32_e32 v29, vcc, 0, v129, vcc
	v_cvt_pk_bf16_f32 v27, v30, v31
	global_store_dwordx4 v[28:29], v[24:27], off
	v_cvt_pk_bf16_f32 v16, v16, v17
	v_cvt_pk_bf16_f32 v17, v18, v19
	v_cvt_pk_bf16_f32 v18, v8, v9
	v_cvt_pk_bf16_f32 v19, v10, v11
	global_store_dwordx4 v[32:33], v[16:19], off offset:256
	v_cvt_pk_bf16_f32 v8, v20, v21
	v_cvt_pk_bf16_f32 v9, v22, v23
	v_cvt_pk_bf16_f32 v10, v12, v13
	v_add_co_u32_e32 v12, vcc, s19, v128
	s_mov_b64 s[0:1], 0xb0000
	s_nop 0
	v_addc_co_u32_e32 v13, vcc, 0, v129, vcc
	v_lshl_add_u64 v[16:17], v[128:129], 0, s[0:1]
	s_and_b64 vcc, exec, s[4:5]
	v_cvt_pk_bf16_f32 v11, v14, v15
	global_store_dwordx4 v[12:13], v[8:11], off
	v_cvt_pk_bf16_f32 v4, v4, v5
	v_cvt_pk_bf16_f32 v5, v6, v7
	v_cvt_pk_bf16_f32 v6, v0, v1
	v_cvt_pk_bf16_f32 v7, v2, v3
	global_store_dwordx4 v[16:17], v[4:7], off offset:256
	s_cbranch_vccz .LBB0_427
	s_waitcnt vmcnt(0)
	s_cmpk_gt_u32 s16, 0xff
	v_readlane_b32 s38, v255, 44
	s_cbranch_scc1 .LBB0_438

; #define PG8_STAGE(bufoff, gbase, hoff, imm) do { _Pragma("unroll") for (int _i = 0; _i < 2; ++_i) { \
;         asm volatile("s_mov_b32 m0, %0\n\ts_nop 0\n\tglobal_load_lds_dwordx4 %1, %2" \
;             :: "s"(lds0 + (unsigned)((bufoff) + _i * 8192)), "v"(voff0), "s"((const char*)(gbase) + (size_t)(hoff) + (size_t)(_i * 8192)) : "memory"); } } while (0)
; #define PG8_WAIT_V(n) asm volatile("s_waitcnt vmcnt(" #n ")" ::: "memory")
; #define PG8_BAR __builtin_amdgcn_s_barrier()
; template <class Epi>
; __device__ __forceinline__ void gemm_phase(LAS unsigned char* lds, const Gemm g, const StaticOrder& S, const Epi& E) {
;     ...
;     const char* cA = (const char*)g.A + (size_t)cur.pm * tstepA + (size_t)(cur.pn >> g.gshift) * g.gstride; const char* cB = (const char*)g.Bt + (size_t)cur.pn * tstepB;
;     PG8_STAGE(PG8_SB(0, 0), cB, 0, 0); PG8_STAGE(PG8_SA(0, 0), cA, 0, 0); PG8_STAGE(PG8_SB(0, 1), cB, hB, 0); PG8_STAGE(PG8_SA(0, 1), cA, hA, 0);
;     if (wr == 1) PG8_BAR;
;     PG8_WAIT_V(4); PG8_BAR;
;     PG8_STAGE(PG8_SB(1, 0), cB + KS, 0, 0); PG8_STAGE(PG8_SA(1, 0), cA + KS, 0, 0); PG8_STAGE(PG8_SB(1, 1), cB + KS, hB, 0);
;     PG8_WAIT_V(6); PG8_BAR;
.LBB0_494:
	s_mov_b32 s1, 0
	v_mov_b32_e32 v0, v235
	v_readlane_b32 s2, v255, 8
	v_readlane_b32 s3, v255, 9
	v_readfirstlane_b32 s0, v0
	s_andn2_b64 vcc, exec, s[2:3]
	s_ashr_i32 s8, s0, 6
	s_cbranch_vccnz .LBB0_525
	s_ashr_i32 s3, s1, 31
	s_add_u32 s2, s96, s1
	s_addc_u32 s3, s97, s3
	s_load_dwordx2 s[56:57], s[2:3], 0x90
	s_load_dwordx4 s[4:7], s[2:3], 0x48
	v_readlane_b32 s2, v255, 27
	v_readlane_b32 s3, v255, 28
	v_lshlrev_b32_e32 v168, 4, v0
	s_waitcnt lgkmcnt(0)
	s_add_u32 s16, s56, 0xa630000
	s_addc_u32 s17, s57, 0
	s_add_u32 s21, s56, 0xa00000
	s_addc_u32 s22, s57, 0
	s_lshl_b32 s12, s8, 10
	s_ashr_i32 s1, s0, 8
	s_add_i32 s24, s12, 0
	s_add_u32 s80, s21, s2
	s_addc_u32 s81, s22, s3
	s_add_i32 s25, s24, 0x10000
	s_add_i32 s26, s24, 0x12000
	s_add_u32 s2, s80, 0x2000
	s_mov_b32 m0, s25
	s_nop 0
	global_load_lds_dwordx4 v168, s[80:81]
	s_addc_u32 s3, s81, 0
	s_mov_b32 m0, s26
	s_nop 0
	global_load_lds_dwordx4 v168, s[2:3]
	v_readlane_b32 s2, v255, 25
	v_readlane_b32 s3, v255, 26
	s_add_u32 s78, s16, s2
	s_addc_u32 s79, s17, s3
	s_add_i32 s27, s24, 0x2000
	s_add_u32 s2, s78, 0x2000
	s_mov_b32 m0, s24
	s_nop 0
	global_load_lds_dwordx4 v168, s[78:79]
	s_addc_u32 s3, s79, 0
	s_add_i32 s28, s24, 0x14000
	s_mov_b32 m0, s27
	s_nop 0
	global_load_lds_dwordx4 v168, s[2:3]
	s_add_u32 s2, s80, 0x80000
	s_addc_u32 s3, s81, 0
	s_add_i32 s29, s24, 0x16000
	s_mov_b32 m0, s28
	s_nop 0
	global_load_lds_dwordx4 v168, s[2:3]
	s_add_u32 s2, s80, 0x82000
	s_addc_u32 s3, s81, 0
	s_add_i32 s30, s24, 0x4000
	s_mov_b32 m0, s29
	s_nop 0
	global_load_lds_dwordx4 v168, s[2:3]
	s_add_u32 s2, s78, 0x80000
	s_addc_u32 s3, s79, 0
	s_add_i32 s34, s24, 0x6000
	s_mov_b32 m0, s30
	s_nop 0
	global_load_lds_dwordx4 v168, s[2:3]
	s_add_u32 s2, s78, 0x82000
	s_addc_u32 s3, s79, 0
	s_mov_b32 m0, s34
	s_nop 0
	global_load_lds_dwordx4 v168, s[2:3]
	s_cmp_eq_u32 s1, 1
	s_cselect_b64 s[2:3], -1, 0
	s_cmp_lg_u32 s1, 1
	s_cbranch_scc1 .LBB0_497
.LBB0_497:
	s_add_u32 s10, s56, 0x1a630000
	s_addc_u32 s11, s57, 0
	s_add_u32 s52, s56, 0x12630000
	s_addc_u32 s53, s57, 0
	s_add_u32 s54, s56, 0x28630000
	s_addc_u32 s55, s57, 0
	s_add_u32 s56, s56, 0x29130000
	v_and_b32_e32 v169, 15, v0
	v_lshrrev_b32_e32 v1, 1, v0
	v_and_b32_e32 v171, 48, v0
	v_lshlrev_b32_e32 v0, 2, v0
	s_addc_u32 s57, s57, 0
	s_and_b32 s48, s8, 3
	s_lshl_b32 s9, s1, 13
	v_lshl_or_b32 v2, v169, 6, v171
	v_and_b32_e32 v0, 32, v0
	s_lshl_b32 s37, s1, 6
	v_bitop3_b32 v3, v2, s9, v0 bitop3:0xde
	s_lshl_b32 s9, s48, 12
	s_add_i32 s38, s24, 0x18000
	s_add_u32 s40, s80, 0x4000
	s_addc_u32 s41, s81, 0
	s_add_i32 s39, s24, 0x1a000
	s_waitcnt vmcnt(4)
	s_barrier
	s_mov_b32 m0, s38
	s_nop 0
	global_load_lds_dwordx4 v168, s[40:41]
	s_add_u32 s40, s80, 0x6000
	s_addc_u32 s41, s81, 0
	s_mov_b32 m0, s39
	s_nop 0
	global_load_lds_dwordx4 v168, s[40:41]
	s_add_i32 s40, s24, 0x8000
	s_add_u32 s42, s78, 0x4000
	s_addc_u32 s43, s79, 0
	s_add_i32 s41, s24, 0xa000
	s_mov_b32 m0, s40
	s_nop 0
	global_load_lds_dwordx4 v168, s[42:43]
	s_add_u32 s42, s78, 0x6000
	s_addc_u32 s43, s79, 0
	s_mov_b32 m0, s41
	s_nop 0
	global_load_lds_dwordx4 v168, s[42:43]
	s_add_i32 s42, s24, 0x1c000
	s_add_u32 s50, s80, 0x84000
	s_addc_u32 s51, s81, 0
	s_add_i32 s43, s24, 0x1e000
	s_mov_b32 m0, s42
	s_nop 0
	global_load_lds_dwordx4 v168, s[50:51]
	s_add_u32 s50, s80, 0x86000
	s_addc_u32 s51, s81, 0
	s_cmp_lt_i32 s8, 4
	v_readlane_b32 s49, v255, 38
	s_cselect_b64 s[58:59], -1, 0
	s_add_i32 s12, s49, s12
	v_bitop3_b32 v0, v2, s9, v0 bitop3:0xde
	s_ashr_i32 s9, s8, 31
	s_add_i32 s86, s12, 0x2000
	s_add_i32 s87, s24, 0xc000
	s_lshl_b32 s12, s1, 11
	s_cmp_gt_i32 s1, 0
	s_cselect_b64 s[60:61], -1, 0
	s_cmp_gt_i32 s1, -2
	s_cselect_b64 s[64:65], -1, 0
	s_add_i32 s12, s49, s12
	s_cmpk_lt_u32 s0, 0x100
	s_mov_b32 m0, s43
	s_nop 0
	global_load_lds_dwordx4 v168, s[50:51]
	s_cselect_b64 s[50:51], -1, 0
	s_bfe_u32 s89, s0, 0x10006
	s_lshl_b32 s0, s1, 3
	s_and_b32 s0, s0, 8
	v_cmp_gt_u32_e32 vcc, 2, v169
	s_or_b32 s0, s0, s89
	v_writelane_b32 v255, s50, 48
	s_and_b64 s[66:67], s[50:51], vcc
	s_lshl_b32 s92, s0, 10
	s_add_i32 s96, s24, 0xe000
	s_lshl_b64 s[0:1], s[8:9], 13
	v_and_b32_e32 v1, 24, v1
	s_add_u32 s0, s4, s0
	v_writelane_b32 v255, s51, 49
	s_addc_u32 s1, s5, s1
	v_lshl_or_b32 v173, s48, 5, v1
	s_cmp_eq_u32 s8, 3
	v_lshlrev_b32_e32 v1, 2, v173
	v_readlane_b32 s8, v255, 39
	v_readlane_b32 s9, v255, 40
	v_readlane_b32 s48, v255, 41
	v_readlane_b32 s49, v255, 42
	s_waitcnt vmcnt(6)
	v_lshlrev_b32_e32 v2, 10, v169
	v_add_u32_e32 v174, s12, v1
	v_add_u32_e32 v180, s8, v1
	v_add_u32_e32 v181, s9, v1
	v_add_u32_e32 v182, s48, v1
	v_add_u32_e32 v183, s49, v1
	v_or_b32_e32 v1, 16, v1
	s_waitcnt vmcnt(0)
	v_add_u32_e32 v4, v174, v2
	v_or_b32_e32 v184, 0xfffff800, v2
	v_add_u32_e32 v185, s8, v1
	v_add_u32_e32 v186, s9, v1
	v_add_u32_e32 v187, s48, v1
	v_add_u32_e32 v200, s49, v1
	v_add_u32_e32 v1, s12, v1
	s_cselect_b32 s97, s7, s1
	s_cselect_b32 s12, s6, s0
	v_readlane_b32 s6, v255, 23
	v_or_b32_e32 v170, s37, v169
	v_and_b32_e32 v172, 0x1f0, v168
	s_mov_b32 s88, 0
	v_cmp_lt_u32_e64 s[4:5], 13, v169
	v_add_u32_e32 v175, 0xffffc800, v4
	v_add_u32_e32 v176, 0xffffc810, v4
	v_add_u32_e32 v177, 0xffffd800, v4
	v_add_u32_e32 v178, 0xffffd810, v4
	v_add_u32_e32 v179, -14, v169
	v_add_u32_e32 v201, v1, v184
	v_add_u32_e32 v202, 0x10000, v0
	v_add_u32_e32 v203, 0, v3
	v_readlane_b32 s0, v255, 21
	s_mov_b32 s50, s6
	s_barrier
	v_readlane_b32 s7, v255, 24
	s_branch .LBB0_499

; #define PG8_STAGE(bufoff, gbase, hoff, imm) do { _Pragma("unroll") for (int _i = 0; _i < 2; ++_i) { \
;         asm volatile("s_mov_b32 m0, %0\n\ts_nop 0\n\tglobal_load_lds_dwordx4 %1, %2" \
;             :: "s"(lds0 + (unsigned)((bufoff) + _i * 8192)), "v"(voff0), "s"((const char*)(gbase) + (size_t)(hoff) + (size_t)(_i * 8192)) : "memory"); } } while (0)
; #define PG8_LDA(dst, b, h) do { _Pragma("unroll") for (int m = 0; m < 4; ++m) _Pragma("unroll") for (int k = 0; k < 2; ++k) dst[m][k] = *(const LAS bf16x8*)(lds + PG8_SA(b, h) + aoff + m * 2048 + k * 1024); } while (0)
; #define PG8_LDB(dst, b, h) do { _Pragma("unroll") for (int n = 0; n < 2; ++n) _Pragma("unroll") for (int k = 0; k < 2; ++k) dst[n][k] = *(const LAS bf16x8*)(lds + PG8_SB(b, h) + boff + n * 2048 + k * 1024); } while (0)
; #define PG8_MMA(ai, bj, At, Bt) do { __builtin_amdgcn_s_setprio(1); _Pragma("unroll") for (int m = 0; m < 4; ++m) _Pragma("unroll") for (int n = 0; n < 2; ++n) _Pragma("unroll") for (int k = 0; k < 2; ++k) \
;         acc[ai][bj][m][n] = __builtin_amdgcn_mfma_f32_16x16x32_bf16(Bt[n][k], At[m][k], acc[ai][bj][m][n], 0, 0, 0); __builtin_amdgcn_s_setprio(0); } while (0)
; #define PG8_WAIT_L(n) asm volatile("s_waitcnt lgkmcnt(" #n ")" ::: "memory")
; template <class Epi>
; __device__ __forceinline__ void gemm_phase(LAS unsigned char* lds, const Gemm g, const StaticOrder& S, const Epi& E) {
;     ...
;     if (wr == 1) PG8_BAR;
;     ...
;         const bool has_next = S.next(ui + 1, nxt);
;         const char* nA = has_next ? (const char*)g.A + (size_t)nxt.pm * tstepA + (size_t)(nxt.pn >> g.gshift) * g.gstride : cA;
;         const char* nB = has_next ? (const char*)g.Bt + (size_t)nxt.pn * tstepB : cB;
;         for (int t = 0; t < nt; t += 2) {
;             const bool last = (t == nt - 2);
;             if (last) E.pre(cur, wid, lane, (unsigned)(size_t)(lds + STAGE_BYTES));
;             const char* aT = cA + (size_t)t * KS;
;             const char* a2 = last ? nA : aT + 2 * KS; const char* b2 = last ? nB : cB + (size_t)(t + 2) * KS;
;             PG8_LDB(B0, 0, 0); PG8_SCHED; PG8_LDA(At, 0, 0); PG8_STAGE(PG8_SA(1, 1), aT + KS, hA, 0);
;             PG8_WAIT_L(8); PG8_BAR; PG8_WAIT_L(0); PG8_MMA(0, 0, At, B0); PG8_BAR; PG8_SCHED;
;             PG8_LDB(B1, 0, 1); PG8_STAGE(PG8_SB(0, 0), b2, 0, 0);
;             PG8_BAR; PG8_WAIT_L(0); PG8_MMA(0, 1, At, B1); PG8_BAR;
.LBB0_505:
	s_ashr_i32 s71, s70, 31
	v_cmp_lt_i64_e32 vcc, s[8:9], v[194:195]
	s_lshl_b64 s[8:9], s[70:71], 20
	s_add_u32 s72, s16, s8
	s_addc_u32 s73, s17, s9
	s_and_b64 s[8:9], vcc, exec
	s_cselect_b32 s51, s73, s79
	s_cselect_b32 s71, s72, s78
	s_ashr_i32 s69, s68, 31
	s_lshl_b64 s[8:9], s[68:69], 20
	s_add_u32 s74, s21, s8
	s_addc_u32 s75, s22, s9
	s_and_b64 s[8:9], vcc, exec
	s_cselect_b32 s69, s75, s81
	s_cselect_b32 s62, s74, s80
	s_lshl_b32 s8, s0, 7
	s_ashr_i32 s9, s8, 31
	s_lshl_b64 s[0:1], s[8:9], 2
	s_add_u32 s76, s12, s0
	s_addc_u32 s77, s97, s1
	s_add_u32 s9, s80, 0x8000
	s_addc_u32 s63, s81, 0
	s_mov_b32 s0, -2
	v_readfirstlane_b32 s48, v235
	s_nop 1
	s_cmpk_lt_u32 s48, 0x100
	s_cbranch_scc1 .Lcgu_st_skip
	s_barrier
.Lcgu_st_skip:
	s_mov_b64 s[84:85], 0
	ds_read_b128 v[128:131], v202
	ds_read_b128 v[132:135], v202 offset:1024
	ds_read_b128 v[136:139], v202 offset:2048
	ds_read_b128 v[140:143], v202 offset:3072
	s_add_u32 s80, s78, 0x8000
	s_addc_u32 s81, s79, 0
	s_and_b64 s[82:83], s[84:85], exec
	s_cselect_b32 s83, s51, s81
	s_cselect_b32 s82, s71, s80
	ds_read_b128 v[144:147], v203
	ds_read_b128 v[148:151], v203 offset:1024
	ds_read_b128 v[152:155], v203 offset:2048
	ds_read_b128 v[156:159], v203 offset:3072
	ds_read_b128 v[160:163], v203 offset:4096
	ds_read_b128 v[164:167], v203 offset:5120
	ds_read_b128 v[204:207], v203 offset:6144
	ds_read_b128 v[208:211], v203 offset:7168
	s_add_u32 s48, s78, 0x84000
	s_addc_u32 s49, s79, 0
	s_mov_b32 m0, s87
	s_nop 0
	global_load_lds_dwordx4 v168, s[48:49]
	s_add_u32 s48, s78, 0x86000
	s_addc_u32 s49, s79, 0
	s_mov_b32 m0, s96
	s_nop 0
	global_load_lds_dwordx4 v168, s[48:49]
	s_waitcnt lgkmcnt(8)
	s_waitcnt vmcnt(10)
	s_barrier
	s_waitcnt lgkmcnt(7)
	v_mfma_f32_16x16x32_bf16 v[96:99], v[128:131], v[144:147], 0
	v_mfma_f32_16x16x32_bf16 v[44:47], v[136:139], v[144:147], 0
	s_waitcnt lgkmcnt(5)
	v_mfma_f32_16x16x32_bf16 v[92:95], v[128:131], v[152:155], 0
	v_mfma_f32_16x16x32_bf16 v[40:43], v[136:139], v[152:155], 0
	s_waitcnt lgkmcnt(3)
	v_mfma_f32_16x16x32_bf16 v[84:87], v[128:131], v[160:163], 0
	v_mfma_f32_16x16x32_bf16 v[36:39], v[136:139], v[160:163], 0
	s_waitcnt lgkmcnt(1)
	v_mfma_f32_16x16x32_bf16 v[124:127], v[128:131], v[204:207], 0
	v_mfma_f32_16x16x32_bf16 v[120:123], v[136:139], v[204:207], 0
	v_mfma_f32_16x16x32_bf16 v[96:99], v[132:135], v[148:151], v[96:99]
	v_mfma_f32_16x16x32_bf16 v[44:47], v[140:143], v[148:151], v[44:47]
	v_mfma_f32_16x16x32_bf16 v[92:95], v[132:135], v[156:159], v[92:95]
	v_mfma_f32_16x16x32_bf16 v[40:43], v[140:143], v[156:159], v[40:43]
	v_mfma_f32_16x16x32_bf16 v[84:87], v[132:135], v[164:167], v[84:87]
	v_mfma_f32_16x16x32_bf16 v[36:39], v[140:143], v[164:167], v[36:39]
	s_waitcnt lgkmcnt(0)
	v_mfma_f32_16x16x32_bf16 v[124:127], v[132:135], v[208:211], v[124:127]
	v_mfma_f32_16x16x32_bf16 v[120:123], v[140:143], v[208:211], v[120:123]
	s_barrier
	ds_read_b128 v[212:215], v202 offset:16384
	ds_read_b128 v[236:239], v202 offset:17408
	ds_read_b128 v[240:243], v202 offset:18432
	ds_read_b128 v[244:247], v202 offset:19456
	s_and_b64 s[48:49], s[84:85], exec
	s_cselect_b32 s78, s62, s9
	s_cselect_b32 s79, s69, s63
	s_mov_b32 m0, s25
	s_nop 0
	global_load_lds_dwordx4 v168, s[78:79]
	s_add_u32 s48, s78, 0x2000
	s_addc_u32 s49, s79, 0
	s_mov_b32 m0, s26
	s_nop 0
	global_load_lds_dwordx4 v168, s[48:49]
	s_waitcnt vmcnt(10)
	s_barrier
	s_waitcnt lgkmcnt(3)
	v_mfma_f32_16x16x32_bf16 v[80:83], v[212:215], v[144:147], 0
	s_waitcnt lgkmcnt(1)
	v_mfma_f32_16x16x32_bf16 v[32:35], v[240:243], v[144:147], 0
	v_mfma_f32_16x16x32_bf16 v[76:79], v[212:215], v[152:155], 0
	v_mfma_f32_16x16x32_bf16 v[28:31], v[240:243], v[152:155], 0
	v_mfma_f32_16x16x32_bf16 v[72:75], v[212:215], v[160:163], 0
	v_mfma_f32_16x16x32_bf16 v[24:27], v[240:243], v[160:163], 0
	v_mfma_f32_16x16x32_bf16 v[116:119], v[212:215], v[204:207], 0
	v_mfma_f32_16x16x32_bf16 v[112:115], v[240:243], v[204:207], 0
	v_mfma_f32_16x16x32_bf16 v[80:83], v[236:239], v[148:151], v[80:83]
	s_waitcnt lgkmcnt(0)
	v_mfma_f32_16x16x32_bf16 v[32:35], v[244:247], v[148:151], v[32:35]
	v_mfma_f32_16x16x32_bf16 v[76:79], v[236:239], v[156:159], v[76:79]
	v_mfma_f32_16x16x32_bf16 v[28:31], v[244:247], v[156:159], v[28:31]
	v_mfma_f32_16x16x32_bf16 v[72:75], v[236:239], v[164:167], v[72:75]
	v_mfma_f32_16x16x32_bf16 v[24:27], v[244:247], v[164:167], v[24:27]
	v_mfma_f32_16x16x32_bf16 v[116:119], v[236:239], v[208:211], v[116:119]
	v_mfma_f32_16x16x32_bf16 v[112:115], v[244:247], v[208:211], v[112:115]
	s_barrier
	ds_read_b128 v[144:147], v203 offset:16384
	ds_read_b128 v[148:151], v203 offset:17408
	ds_read_b128 v[152:155], v203 offset:18432
	ds_read_b128 v[156:159], v203 offset:19456
	ds_read_b128 v[160:163], v203 offset:20480
	ds_read_b128 v[164:167], v203 offset:21504
	ds_read_b128 v[204:207], v203 offset:22528
	ds_read_b128 v[208:211], v203 offset:23552
	s_mov_b32 m0, s24
	s_nop 0
	global_load_lds_dwordx4 v168, s[82:83]
	s_add_u32 s48, s82, 0x2000
	s_addc_u32 s49, s83, 0
	s_mov_b32 m0, s27
	s_nop 0
	global_load_lds_dwordx4 v168, s[48:49]
	s_barrier
; #define PG8_STAGE(bufoff, gbase, hoff, imm) do { _Pragma("unroll") for (int _i = 0; _i < 2; ++_i) { \
;         asm volatile("s_mov_b32 m0, %0\n\ts_nop 0\n\tglobal_load_lds_dwordx4 %1, %2" \
;             :: "s"(lds0 + (unsigned)((bufoff) + _i * 8192)), "v"(voff0), "s"((const char*)(gbase) + (size_t)(hoff) + (size_t)(_i * 8192)) : "memory"); } } while (0)
; #define PG8_LDA(dst, b, h) do { _Pragma("unroll") for (int m = 0; m < 4; ++m) _Pragma("unroll") for (int k = 0; k < 2; ++k) dst[m][k] = *(const LAS bf16x8*)(lds + PG8_SA(b, h) + aoff + m * 2048 + k * 1024); } while (0)
; #define PG8_LDB(dst, b, h) do { _Pragma("unroll") for (int n = 0; n < 2; ++n) _Pragma("unroll") for (int k = 0; k < 2; ++k) dst[n][k] = *(const LAS bf16x8*)(lds + PG8_SB(b, h) + boff + n * 2048 + k * 1024); } while (0)
; #define PG8_WAIT_V(n) asm volatile("s_waitcnt vmcnt(" #n ")" ::: "memory")
; #define PG8_WAIT_L(n) asm volatile("s_waitcnt lgkmcnt(" #n ")" ::: "memory")
; #define PG8_BAR __builtin_amdgcn_s_barrier()
; template <class Epi>
; __device__ __forceinline__ void gemm_phase(LAS unsigned char* lds, const Gemm g, const StaticOrder& S, const Epi& E) {
;     ...
;             PG8_LDB(B0, 0, 0); PG8_SCHED; PG8_LDA(At, 0, 0); PG8_STAGE(PG8_SA(1, 1), aT + KS, hA, 0);
;             PG8_WAIT_L(8); PG8_BAR; PG8_WAIT_L(0); PG8_MMA(0, 0, At, B0); PG8_BAR; PG8_SCHED;
;             PG8_LDB(B1, 0, 1); PG8_STAGE(PG8_SB(0, 0), b2, 0, 0);
;             PG8_BAR; PG8_WAIT_L(0); PG8_MMA(0, 1, At, B1); PG8_BAR;
;             PG8_LDA(At, 0, 1); PG8_STAGE(PG8_SA(0, 0), a2, 0, 0);
;             PG8_BAR; PG8_WAIT_L(0); PG8_MMA(1, 0, At, B0); PG8_BAR; PG8_SCHED;
;             PG8_STAGE(PG8_SB(0, 1), b2, hB, 0);
;             PG8_WAIT_V(6); PG8_BAR; PG8_MMA(1, 1, At, B1); PG8_BAR;
;             PG8_LDB(B0, 1, 0); PG8_SCHED; PG8_LDA(At, 1, 0); PG8_STAGE(PG8_SA(0, 1), a2, hA, 0);
;             PG8_WAIT_L(8); PG8_BAR; PG8_WAIT_L(0); PG8_MMA(0, 0, At, B0); PG8_BAR; PG8_SCHED;
;             PG8_LDB(B1, 1, 1); PG8_STAGE(PG8_SB(1, 0), b2 + KS, 0, 0);
;             PG8_BAR; PG8_WAIT_L(0); PG8_MMA(0, 1, At, B1); PG8_BAR;
;             PG8_LDA(At, 1, 1); PG8_STAGE(PG8_SA(1, 0), a2 + KS, 0, 0);
;             PG8_BAR; PG8_WAIT_L(0); PG8_MMA(1, 0, At, B0); PG8_BAR; PG8_SCHED;
;             PG8_STAGE(PG8_SB(1, 1), b2 + KS, hB, 0);
;             PG8_WAIT_V(6); PG8_BAR; PG8_MMA(1, 1, At, B1); PG8_BAR;
	s_waitcnt lgkmcnt(7)
	v_mfma_f32_16x16x32_bf16 v[68:71], v[128:131], v[144:147], 0
	v_mfma_f32_16x16x32_bf16 v[20:23], v[136:139], v[144:147], 0
	s_waitcnt lgkmcnt(5)
	v_mfma_f32_16x16x32_bf16 v[64:67], v[128:131], v[152:155], 0
	v_mfma_f32_16x16x32_bf16 v[16:19], v[136:139], v[152:155], 0
	s_waitcnt lgkmcnt(3)
	v_mfma_f32_16x16x32_bf16 v[60:63], v[128:131], v[160:163], 0
	v_mfma_f32_16x16x32_bf16 v[12:15], v[136:139], v[160:163], 0
	s_waitcnt lgkmcnt(1)
	v_mfma_f32_16x16x32_bf16 v[108:111], v[128:131], v[204:207], 0
	v_mfma_f32_16x16x32_bf16 v[104:107], v[136:139], v[204:207], 0
	v_mfma_f32_16x16x32_bf16 v[68:71], v[132:135], v[148:151], v[68:71]
	v_mfma_f32_16x16x32_bf16 v[20:23], v[140:143], v[148:151], v[20:23]
	v_mfma_f32_16x16x32_bf16 v[64:67], v[132:135], v[156:159], v[64:67]
	v_mfma_f32_16x16x32_bf16 v[16:19], v[140:143], v[156:159], v[16:19]
	v_mfma_f32_16x16x32_bf16 v[60:63], v[132:135], v[164:167], v[60:63]
	v_mfma_f32_16x16x32_bf16 v[12:15], v[140:143], v[164:167], v[12:15]
	s_waitcnt lgkmcnt(0)
	v_mfma_f32_16x16x32_bf16 v[108:111], v[132:135], v[208:211], v[108:111]
	v_mfma_f32_16x16x32_bf16 v[104:107], v[140:143], v[208:211], v[104:107]
	s_barrier
	s_add_u32 s48, s78, 0x80000
	s_addc_u32 s49, s79, 0
	s_mov_b32 m0, s28
	s_nop 0
	global_load_lds_dwordx4 v168, s[48:49]
	s_add_u32 s48, s78, 0x82000
	s_addc_u32 s49, s79, 0
	s_mov_b32 m0, s29
	s_nop 0
	global_load_lds_dwordx4 v168, s[48:49]
	s_waitcnt vmcnt(10)
	s_barrier
	v_mfma_f32_16x16x32_bf16 v[56:59], v[212:215], v[144:147], 0
	v_mfma_f32_16x16x32_bf16 v[8:11], v[240:243], v[144:147], 0
	v_mfma_f32_16x16x32_bf16 v[52:55], v[212:215], v[152:155], 0
	v_mfma_f32_16x16x32_bf16 v[4:7], v[240:243], v[152:155], 0
	v_mfma_f32_16x16x32_bf16 v[48:51], v[212:215], v[160:163], 0
	v_mfma_f32_16x16x32_bf16 v[0:3], v[240:243], v[160:163], 0
	v_mfma_f32_16x16x32_bf16 v[100:103], v[212:215], v[204:207], 0
	v_mfma_f32_16x16x32_bf16 v[88:91], v[240:243], v[204:207], 0
	v_mfma_f32_16x16x32_bf16 v[56:59], v[236:239], v[148:151], v[56:59]
	v_mfma_f32_16x16x32_bf16 v[8:11], v[244:247], v[148:151], v[8:11]
	v_mfma_f32_16x16x32_bf16 v[52:55], v[236:239], v[156:159], v[52:55]
	v_mfma_f32_16x16x32_bf16 v[4:7], v[244:247], v[156:159], v[4:7]
	v_mfma_f32_16x16x32_bf16 v[48:51], v[236:239], v[164:167], v[48:51]
	v_mfma_f32_16x16x32_bf16 v[0:3], v[244:247], v[164:167], v[0:3]
	v_mfma_f32_16x16x32_bf16 v[100:103], v[236:239], v[208:211], v[100:103]
	v_mfma_f32_16x16x32_bf16 v[88:91], v[244:247], v[208:211], v[88:91]
	s_barrier
	ds_read_b128 v[128:131], v202 offset:32768
	ds_read_b128 v[132:135], v202 offset:33792
	ds_read_b128 v[136:139], v202 offset:34816
	ds_read_b128 v[140:143], v202 offset:35840
	ds_read_b128 v[144:147], v203 offset:32768
	ds_read_b128 v[148:151], v203 offset:33792
	ds_read_b128 v[152:155], v203 offset:34816
	ds_read_b128 v[156:159], v203 offset:35840
	ds_read_b128 v[160:163], v203 offset:36864
	ds_read_b128 v[164:167], v203 offset:37888
	ds_read_b128 v[204:207], v203 offset:38912
	ds_read_b128 v[208:211], v203 offset:39936
	s_add_u32 s48, s82, 0x80000
	s_addc_u32 s49, s83, 0
	s_mov_b32 m0, s30
	s_nop 0
	global_load_lds_dwordx4 v168, s[48:49]
	s_add_u32 s48, s82, 0x82000
	s_addc_u32 s49, s83, 0
	s_mov_b32 m0, s34
	s_nop 0
	global_load_lds_dwordx4 v168, s[48:49]
	s_waitcnt lgkmcnt(8)
	s_waitcnt vmcnt(10)
	s_barrier
	s_waitcnt lgkmcnt(7)
	v_mfma_f32_16x16x32_bf16 v[96:99], v[128:131], v[144:147], v[96:99]
	v_mfma_f32_16x16x32_bf16 v[44:47], v[136:139], v[144:147], v[44:47]
	s_waitcnt lgkmcnt(5)
	v_mfma_f32_16x16x32_bf16 v[92:95], v[128:131], v[152:155], v[92:95]
	v_mfma_f32_16x16x32_bf16 v[40:43], v[136:139], v[152:155], v[40:43]
	s_waitcnt lgkmcnt(3)
	v_mfma_f32_16x16x32_bf16 v[84:87], v[128:131], v[160:163], v[84:87]
	v_mfma_f32_16x16x32_bf16 v[36:39], v[136:139], v[160:163], v[36:39]
	s_waitcnt lgkmcnt(1)
	v_mfma_f32_16x16x32_bf16 v[124:127], v[128:131], v[204:207], v[124:127]
	v_mfma_f32_16x16x32_bf16 v[120:123], v[136:139], v[204:207], v[120:123]
	v_mfma_f32_16x16x32_bf16 v[96:99], v[132:135], v[148:151], v[96:99]
	v_mfma_f32_16x16x32_bf16 v[44:47], v[140:143], v[148:151], v[44:47]
	v_mfma_f32_16x16x32_bf16 v[92:95], v[132:135], v[156:159], v[92:95]
	v_mfma_f32_16x16x32_bf16 v[40:43], v[140:143], v[156:159], v[40:43]
	v_mfma_f32_16x16x32_bf16 v[84:87], v[132:135], v[164:167], v[84:87]
	v_mfma_f32_16x16x32_bf16 v[36:39], v[140:143], v[164:167], v[36:39]
	s_waitcnt lgkmcnt(0)
	v_mfma_f32_16x16x32_bf16 v[124:127], v[132:135], v[208:211], v[124:127]
	v_mfma_f32_16x16x32_bf16 v[120:123], v[140:143], v[208:211], v[120:123]
	s_barrier
; #define PG8_STAGE(bufoff, gbase, hoff, imm) do { _Pragma("unroll") for (int _i = 0; _i < 2; ++_i) { \
;         asm volatile("s_mov_b32 m0, %0\n\ts_nop 0\n\tglobal_load_lds_dwordx4 %1, %2" \
;             :: "s"(lds0 + (unsigned)((bufoff) + _i * 8192)), "v"(voff0), "s"((const char*)(gbase) + (size_t)(hoff) + (size_t)(_i * 8192)) : "memory"); } } while (0)
; #define PG8_LDA(dst, b, h) do { _Pragma("unroll") for (int m = 0; m < 4; ++m) _Pragma("unroll") for (int k = 0; k < 2; ++k) dst[m][k] = *(const LAS bf16x8*)(lds + PG8_SA(b, h) + aoff + m * 2048 + k * 1024); } while (0)
; #define PG8_WAIT_V(n) asm volatile("s_waitcnt vmcnt(" #n ")" ::: "memory")
; template <class Epi>
; __device__ __forceinline__ void gemm_phase(LAS unsigned char* lds, const Gemm g, const StaticOrder& S, const Epi& E) {
;     ...
;         for (int t = 0; t < nt; t += 2) {
;             const bool last = (t == nt - 2);
;             if (last) E.pre(cur, wid, lane, (unsigned)(size_t)(lds + STAGE_BYTES));
;             const char* aT = cA + (size_t)t * KS;
;             const char* a2 = last ? nA : aT + 2 * KS; const char* b2 = last ? nB : cB + (size_t)(t + 2) * KS;
;             PG8_LDB(B0, 0, 0); PG8_SCHED; PG8_LDA(At, 0, 0); PG8_STAGE(PG8_SA(1, 1), aT + KS, hA, 0);
;             PG8_WAIT_L(8); PG8_BAR; PG8_WAIT_L(0); PG8_MMA(0, 0, At, B0); PG8_BAR; PG8_SCHED;
;             PG8_LDB(B1, 0, 1); PG8_STAGE(PG8_SB(0, 0), b2, 0, 0);
;             PG8_BAR; PG8_WAIT_L(0); PG8_MMA(0, 1, At, B1); PG8_BAR;
;             PG8_LDA(At, 0, 1); PG8_STAGE(PG8_SA(0, 0), a2, 0, 0);
;             PG8_BAR; PG8_WAIT_L(0); PG8_MMA(1, 0, At, B0); PG8_BAR; PG8_SCHED;
;             PG8_STAGE(PG8_SB(0, 1), b2, hB, 0);
;             PG8_WAIT_V(6); PG8_BAR; PG8_MMA(1, 1, At, B1); PG8_BAR;
;             PG8_LDB(B0, 1, 0); PG8_SCHED; PG8_LDA(At, 1, 0); PG8_STAGE(PG8_SA(0, 1), a2, hA, 0);
;             PG8_WAIT_L(8); PG8_BAR; PG8_WAIT_L(0); PG8_MMA(0, 0, At, B0); PG8_BAR; PG8_SCHED;
;             PG8_LDB(B1, 1, 1); PG8_STAGE(PG8_SB(1, 0), b2 + KS, 0, 0);
;             PG8_BAR; PG8_WAIT_L(0); PG8_MMA(0, 1, At, B1); PG8_BAR;
;             PG8_LDA(At, 1, 1); PG8_STAGE(PG8_SA(1, 0), a2 + KS, 0, 0);
;             PG8_BAR; PG8_WAIT_L(0); PG8_MMA(1, 0, At, B0); PG8_BAR; PG8_SCHED;
;             PG8_STAGE(PG8_SB(1, 1), b2 + KS, hB, 0);
;             PG8_WAIT_V(6); PG8_BAR; PG8_MMA(1, 1, At, B1); PG8_BAR;
	ds_read_b128 v[212:215], v202 offset:49152
	ds_read_b128 v[236:239], v202 offset:50176
	ds_read_b128 v[240:243], v202 offset:51200
	ds_read_b128 v[244:247], v202 offset:52224
	s_add_u32 s48, s78, 0x4000
	s_addc_u32 s49, s79, 0
	s_mov_b32 m0, s38
	s_nop 0
	global_load_lds_dwordx4 v168, s[48:49]
	s_add_u32 s48, s78, 0x6000
	s_addc_u32 s49, s79, 0
	s_mov_b32 m0, s39
	s_nop 0
	global_load_lds_dwordx4 v168, s[48:49]
	s_waitcnt vmcnt(10)
	s_barrier
	s_waitcnt lgkmcnt(3)
	v_mfma_f32_16x16x32_bf16 v[80:83], v[212:215], v[144:147], v[80:83]
	s_waitcnt lgkmcnt(1)
	v_mfma_f32_16x16x32_bf16 v[32:35], v[240:243], v[144:147], v[32:35]
	v_mfma_f32_16x16x32_bf16 v[76:79], v[212:215], v[152:155], v[76:79]
	v_mfma_f32_16x16x32_bf16 v[28:31], v[240:243], v[152:155], v[28:31]
	v_mfma_f32_16x16x32_bf16 v[72:75], v[212:215], v[160:163], v[72:75]
	v_mfma_f32_16x16x32_bf16 v[24:27], v[240:243], v[160:163], v[24:27]
	v_mfma_f32_16x16x32_bf16 v[116:119], v[212:215], v[204:207], v[116:119]
	v_mfma_f32_16x16x32_bf16 v[112:115], v[240:243], v[204:207], v[112:115]
	v_mfma_f32_16x16x32_bf16 v[80:83], v[236:239], v[148:151], v[80:83]
	s_waitcnt lgkmcnt(0)
	v_mfma_f32_16x16x32_bf16 v[32:35], v[244:247], v[148:151], v[32:35]
	v_mfma_f32_16x16x32_bf16 v[76:79], v[236:239], v[156:159], v[76:79]
	v_mfma_f32_16x16x32_bf16 v[28:31], v[244:247], v[156:159], v[28:31]
	v_mfma_f32_16x16x32_bf16 v[72:75], v[236:239], v[164:167], v[72:75]
	v_mfma_f32_16x16x32_bf16 v[24:27], v[244:247], v[164:167], v[24:27]
	v_mfma_f32_16x16x32_bf16 v[116:119], v[236:239], v[208:211], v[116:119]
	v_mfma_f32_16x16x32_bf16 v[112:115], v[244:247], v[208:211], v[112:115]
	s_barrier
	ds_read_b128 v[144:147], v203 offset:49152
	ds_read_b128 v[148:151], v203 offset:50176
	ds_read_b128 v[152:155], v203 offset:51200
	ds_read_b128 v[156:159], v203 offset:52224
	ds_read_b128 v[160:163], v203 offset:53248
	ds_read_b128 v[164:167], v203 offset:54272
	ds_read_b128 v[204:207], v203 offset:55296
	ds_read_b128 v[208:211], v203 offset:56320
	s_add_u32 s48, s82, 0x4000
	s_addc_u32 s49, s83, 0
	s_mov_b32 m0, s40
	s_nop 0
	global_load_lds_dwordx4 v168, s[48:49]
	s_add_u32 s48, s82, 0x6000
	s_addc_u32 s49, s83, 0
	s_mov_b32 m0, s41
	s_nop 0
	global_load_lds_dwordx4 v168, s[48:49]
	s_barrier
	s_waitcnt lgkmcnt(7)
	v_mfma_f32_16x16x32_bf16 v[68:71], v[128:131], v[144:147], v[68:71]
	v_mfma_f32_16x16x32_bf16 v[20:23], v[136:139], v[144:147], v[20:23]
	s_waitcnt lgkmcnt(5)
	v_mfma_f32_16x16x32_bf16 v[64:67], v[128:131], v[152:155], v[64:67]
	v_mfma_f32_16x16x32_bf16 v[16:19], v[136:139], v[152:155], v[16:19]
	s_waitcnt lgkmcnt(3)
	v_mfma_f32_16x16x32_bf16 v[60:63], v[128:131], v[160:163], v[60:63]
	v_mfma_f32_16x16x32_bf16 v[12:15], v[136:139], v[160:163], v[12:15]
	s_waitcnt lgkmcnt(1)
	v_mfma_f32_16x16x32_bf16 v[108:111], v[128:131], v[204:207], v[108:111]
	v_mfma_f32_16x16x32_bf16 v[104:107], v[136:139], v[204:207], v[104:107]
	v_mfma_f32_16x16x32_bf16 v[68:71], v[132:135], v[148:151], v[68:71]
	v_mfma_f32_16x16x32_bf16 v[20:23], v[140:143], v[148:151], v[20:23]
	v_mfma_f32_16x16x32_bf16 v[64:67], v[132:135], v[156:159], v[64:67]
	v_mfma_f32_16x16x32_bf16 v[16:19], v[140:143], v[156:159], v[16:19]
	v_mfma_f32_16x16x32_bf16 v[60:63], v[132:135], v[164:167], v[60:63]
	v_mfma_f32_16x16x32_bf16 v[12:15], v[140:143], v[164:167], v[12:15]
	s_waitcnt lgkmcnt(0)
	v_mfma_f32_16x16x32_bf16 v[108:111], v[132:135], v[208:211], v[108:111]
	v_mfma_f32_16x16x32_bf16 v[104:107], v[140:143], v[208:211], v[104:107]
	s_barrier
	s_add_u32 s48, s78, 0x84000
	s_addc_u32 s49, s79, 0
	s_mov_b32 m0, s42
	s_nop 0
	global_load_lds_dwordx4 v168, s[48:49]
	s_add_u32 s48, s78, 0x86000
	s_addc_u32 s49, s79, 0
	s_mov_b32 m0, s43
	s_nop 0
	global_load_lds_dwordx4 v168, s[48:49]
	s_waitcnt vmcnt(10)
	s_barrier
	v_mfma_f32_16x16x32_bf16 v[56:59], v[212:215], v[144:147], v[56:59]
	v_mfma_f32_16x16x32_bf16 v[8:11], v[240:243], v[144:147], v[8:11]
	v_mfma_f32_16x16x32_bf16 v[52:55], v[212:215], v[152:155], v[52:55]
	v_mfma_f32_16x16x32_bf16 v[4:7], v[240:243], v[152:155], v[4:7]
	v_mfma_f32_16x16x32_bf16 v[48:51], v[212:215], v[160:163], v[48:51]
	v_mfma_f32_16x16x32_bf16 v[0:3], v[240:243], v[160:163], v[0:3]
	v_mfma_f32_16x16x32_bf16 v[100:103], v[212:215], v[204:207], v[100:103]
	v_mfma_f32_16x16x32_bf16 v[88:91], v[240:243], v[204:207], v[88:91]
	v_mfma_f32_16x16x32_bf16 v[56:59], v[236:239], v[148:151], v[56:59]
	v_mfma_f32_16x16x32_bf16 v[8:11], v[244:247], v[148:151], v[8:11]
	v_mfma_f32_16x16x32_bf16 v[52:55], v[236:239], v[156:159], v[52:55]
	v_mfma_f32_16x16x32_bf16 v[4:7], v[244:247], v[156:159], v[4:7]
	v_mfma_f32_16x16x32_bf16 v[48:51], v[236:239], v[164:167], v[48:51]
	v_mfma_f32_16x16x32_bf16 v[0:3], v[244:247], v[164:167], v[0:3]
	v_mfma_f32_16x16x32_bf16 v[100:103], v[236:239], v[208:211], v[100:103]
	v_mfma_f32_16x16x32_bf16 v[88:91], v[244:247], v[208:211], v[88:91]
	s_add_i32 s0, s0, 2
	s_add_u32 s9, s9, 0x8000
	s_addc_u32 s63, s63, 0
	s_cmp_gt_u32 s0, 29
	s_mov_b64 s[78:79], s[80:81]
	s_barrier
	s_branch .LBB0_507

; #define LAS __attribute__((address_space(3)))
; template <class Epi>
; __device__ __forceinline__ void gemm_phase(LAS unsigned char* lds, const Gemm g, const StaticOrder& S, const Epi& E) {
;     ...
;             const bool last = (t == nt - 2);
;             if (last) E.pre(cur, wid, lane, (unsigned)(size_t)(lds + STAGE_BYTES));
;     __device__ __forceinline__ void pre(const Unit& u, int wid, int lane, unsigned ldsx) const {
;         if (wid < 4) {
;             const int c = lane * 4, s = c >> 7;
;             const unsigned vo = (unsigned)(((MODE == 0 && s) ? voff : 0) + (c & 127)) * 4u;
;             const char* base = (const char*)((wid < 3 ? cw + (size_t)wid * C : cb) + 128 * u.pn);
;             unsigned keep;
;             asm volatile("s_mov_b32 %0, m0\n\ts_mov_b32 m0, %1\n\ts_nop 0\n\tglobal_load_lds_dwordx4 %2, %3\n\ts_mov_b32 m0, %0"
;                 : "=&s"(keep) : "s"(ldsx + 8192u + (unsigned)wid * 1024u), "v"(vo), "s"(base) : "memory");
;         }
;     }
;     __device__ __forceinline__ void operator()(f32x4 (&acc)[2][2][4][2], const Unit& u, int wr, int wc, int fr, int fq, LAS unsigned char* xl) const {
;         constexpr int NS = MODE == 0 ? 2 : 1;
;         const int chl = 32 * wc + 8 * fq, ch0 = 128 * u.pn + chl;
;         LAS float* bnd = (LAS float*)xl;
;         LAS float* wt = (LAS float*)(xl + 8192);
;         asm volatile("s_waitcnt vmcnt(16)" ::: "memory");
;         if (MODE == 1) {
; #pragma unroll
;             for (int ai = 0; ai < 2; ++ai)
; #pragma unroll
;                 for (int m = 0; m < 4; ++m)
; #pragma unroll
;                     for (int n = 0; n < 2; ++n) acc[ai][0][m][n] *= acc[ai][1][m][n];
;         }
;         if (fr >= 14) {
; #pragma unroll
;             for (int ai = 0; ai < 2; ++ai)
; #pragma unroll
;                 for (int s = 0; s < NS; ++s)
; #pragma unroll
;                     for (int n = 0; n < 2; ++n) *(LAS f32x4*)(bnd + (((ai * 2 + wr) * 2 + (fr - 14)) * 256 + s * 128 + chl + 4 * n)) = acc[ai][s][3][n];
;             if (wr == 1) {
; #pragma unroll
;                 for (int s = 0; s < NS; ++s)
; #pragma unroll
;                     for (int n = 0; n < 2; ++n) *(f32x4*)(TAIL + (size_t)(u.pm * 2 + (fr - 14)) * C + (s ? voff : 0) + ch0 + 4 * n) = acc[1][s][3][n];
;             }
.LBB0_507:
	s_cmp_eq_u32 s0, 28
	s_cselect_b64 s[84:85], -1, 0
	s_and_b64 s[80:81], s[84:85], s[58:59]
	s_andn2_b64 vcc, exec, s[80:81]
	s_cbranch_vccnz .LBB0_506
	s_mov_b32 s1, m0
	s_mov_b32 m0, s86
	s_nop 0
	global_load_lds_dwordx4 v172, s[76:77]
	s_mov_b32 m0, s1
	s_branch .LBB0_506
.LBB0_509:
	v_readfirstlane_b32 s48, v235
	s_nop 1
	s_cmpk_lt_u32 s48, 0x100
	s_cbranch_scc0 .Lcgu_al_skip
	s_barrier
.Lcgu_al_skip:
	s_waitcnt vmcnt(16)
	v_pk_mul_f32 v[160:161], v[126:127], v[118:119]
	v_pk_mul_f32 v[158:159], v[124:125], v[116:117]
	v_pk_mul_f32 v[134:135], v[122:123], v[114:115]
	v_pk_mul_f32 v[132:133], v[120:121], v[112:113]
	v_pk_mul_f32 v[138:139], v[110:111], v[102:103]
	v_pk_mul_f32 v[136:137], v[108:109], v[100:101]
	v_pk_mul_f32 v[130:131], v[106:107], v[90:91]
	v_pk_mul_f32 v[128:129], v[104:105], v[88:89]
	v_or_b32_e32 v166, s8, v173
	s_and_saveexec_b64 s[8:9], s[4:5]
	s_cbranch_execz .LBB0_512
	s_andn2_b64 vcc, exec, s[2:3]
	ds_write_b128 v175, v[158:161]
	ds_write_b128 v176, v[132:135]
	ds_write_b128 v177, v[136:139]
	ds_write_b128 v178, v[128:131]
	s_cbranch_vccnz .LBB0_512
	v_lshl_add_u32 v88, s50, 1, v179
	v_ashrrev_i32_e32 v89, 31, v88
	v_lshlrev_b64 v[88:89], 13, v[88:89]
	v_ashrrev_i32_e32 v167, 31, v166
	v_lshl_add_u64 v[88:89], s[56:57], 0, v[88:89]
	v_lshl_add_u64 v[88:89], v[166:167], 2, v[88:89]
	global_store_dwordx4 v[88:89], v[136:139], off
	global_store_dwordx4 v[88:89], v[128:131], off offset:16

; #define PG8_WAIT_V(n) asm volatile("s_waitcnt vmcnt(" #n ")" ::: "memory")
; #define PG8_BAR __builtin_amdgcn_s_barrier()
; template <class Epi>
; __device__ __forceinline__ void gemm_phase(LAS unsigned char* lds, const Gemm g, const StaticOrder& S, const Epi& E) {
;     ...
;     PG8_WAIT_V(0);
;     if (wr == 0) PG8_BAR;
;     PG8_BAR;
.LBB0_522:
	v_readlane_b32 s0, v255, 48
	s_waitcnt vmcnt(0)
	v_readlane_b32 s1, v255, 49
	s_andn2_b64 vcc, exec, s[0:1]
	v_readlane_b32 s38, v255, 44
	s_movk_i32 s30, 0x7ff
	v_readlane_b32 s21, v255, 47
	s_cbranch_vccnz .LBB0_524
.LBB0_524:
	v_readlane_b32 s96, v255, 3
	v_readlane_b32 s97, v255, 4
	s_barrier

; #define PG8_STAGE(bufoff, gbase, hoff, imm) do { _Pragma("unroll") for (int _i = 0; _i < 2; ++_i) { \
;         asm volatile("s_mov_b32 m0, %0\n\ts_nop 0\n\tglobal_load_lds_dwordx4 %1, %2" \
;             :: "s"(lds0 + (unsigned)((bufoff) + _i * 8192)), "v"(voff0), "s"((const char*)(gbase) + (size_t)(hoff) + (size_t)(_i * 8192)) : "memory"); } } while (0)
; #define PG8_WAIT_V(n) asm volatile("s_waitcnt vmcnt(" #n ")" ::: "memory")
; #define PG8_BAR __builtin_amdgcn_s_barrier()
; template <class Epi>
; __device__ __forceinline__ void gemm_phase(LAS unsigned char* lds, const Gemm g, const StaticOrder& S, const Epi& E) {
;     int tid = threadIdx.x; asm volatile("" : "+v"(tid));
;     const int wid = __builtin_amdgcn_readfirstlane(tid >> 6), lane = tid & 63, wr = wid >> 2, wc = wid & 3, fr = lane & 15, fq = lane >> 4;
;     const int K = g.K, nt = K / BK;
;     const unsigned voff0 = (unsigned)(tid * 16);
;     const unsigned hA = (unsigned)(g.lda * 256), hB = (unsigned)(K * 256);
;     constexpr int KS = 16384;
;     const size_t tstepA = (size_t)BM * g.lda * 2, tstepB = (size_t)BM * K * 2;
;     const unsigned lds0 = (unsigned)__builtin_amdgcn_readfirstlane((int)((unsigned)(size_t)lds + (unsigned)wid * 1024u));
;     const int aoff = lds_byte(wr * 64 + fr, fq * 8), boff = lds_byte(wc * 32 + fr, fq * 8);
;     ...
;     Unit cur, nxt; int ui = 0;
;     if (!S.next(0, cur)) return;
;     f32x4 acc[2][2][4][2];
; #pragma unroll
;     for (int a = 0; a < 2; ++a)
; #pragma unroll
;         for (int b = 0; b < 2; ++b)
; #pragma unroll
;             for (int m = 0; m < 4; ++m)
; #pragma unroll
;                 for (int n = 0; n < 2; ++n) acc[a][b][m][n] = (f32x4){0.f, 0.f, 0.f, 0.f};
;     bf16x8 At[4][2], B0[2][2], B1[2][2];
;     const char* cA = (const char*)g.A + (size_t)cur.pm * tstepA + (size_t)(cur.pn >> g.gshift) * g.gstride; const char* cB = (const char*)g.Bt + (size_t)cur.pn * tstepB;
;     PG8_STAGE(PG8_SB(0, 0), cB, 0, 0); PG8_STAGE(PG8_SA(0, 0), cA, 0, 0); PG8_STAGE(PG8_SB(0, 1), cB, hB, 0); PG8_STAGE(PG8_SA(0, 1), cA, hA, 0);
;     if (wr == 1) PG8_BAR;
;     PG8_WAIT_V(4); PG8_BAR;
;     PG8_STAGE(PG8_SB(1, 0), cB + KS, 0, 0); PG8_STAGE(PG8_SA(1, 0), cA + KS, 0, 0); PG8_STAGE(PG8_SB(1, 1), cB + KS, hB, 0);
;     PG8_WAIT_V(6); PG8_BAR;
.LBB0_599:
	s_waitcnt vmcnt(0)
	v_mov_b32_e32 v0, v235
	v_readlane_b32 s0, v255, 6
	s_barrier
	v_readlane_b32 s1, v255, 7
	v_readfirstlane_b32 s16, v0
	s_andn2_b64 vcc, exec, s[0:1]
	s_ashr_i32 s0, s16, 6
	s_cbranch_vccnz .LBB0_615
	s_add_u32 s17, s4, 0x1a00000
	s_addc_u32 s21, s5, 0
	s_lshl_b32 s8, s0, 10
	s_ashr_i32 s1, s16, 8
	s_add_i32 s22, s8, 0
	v_readlane_b32 s8, v255, 19
	v_readlane_b32 s9, v255, 20
	s_add_u32 s62, s17, s8
	s_addc_u32 s63, s21, s9
	s_add_i32 s24, s22, 0x10000
	s_add_i32 s25, s22, 0x12000
	s_add_u32 s8, s62, 0x2000
	v_lshlrev_b32_e32 v188, 4, v0
	s_mov_b32 m0, s24
	s_nop 0
	global_load_lds_dwordx4 v188, s[62:63]
	s_addc_u32 s9, s63, 0
	s_mov_b32 m0, s25
	s_nop 0
	global_load_lds_dwordx4 v188, s[8:9]
	v_readlane_b32 s8, v255, 17
	v_readlane_b32 s9, v255, 18
	s_add_u32 s60, s6, s8
	s_addc_u32 s61, s7, s9
	s_add_i32 s26, s22, 0x2000
	s_add_u32 s8, s60, 0x2000
	s_mov_b32 m0, s22
	s_nop 0
	global_load_lds_dwordx4 v188, s[60:61]
	s_addc_u32 s9, s61, 0
	s_add_i32 s27, s22, 0x14000
	s_mov_b32 m0, s26
	s_nop 0
	global_load_lds_dwordx4 v188, s[8:9]
	s_add_u32 s8, s62, 0x80000
	s_addc_u32 s9, s63, 0
	s_add_i32 s28, s22, 0x16000
	s_mov_b32 m0, s27
	s_nop 0
	global_load_lds_dwordx4 v188, s[8:9]
	s_add_u32 s8, s62, 0x82000
	s_addc_u32 s9, s63, 0
	s_add_i32 s29, s22, 0x4000
	s_mov_b32 m0, s28
	s_nop 0
	global_load_lds_dwordx4 v188, s[8:9]
	s_add_u32 s8, s60, 0x80000
	s_addc_u32 s9, s61, 0
	s_add_i32 s30, s22, 0x6000
	s_mov_b32 m0, s29
	s_nop 0
	global_load_lds_dwordx4 v188, s[8:9]
	s_add_u32 s8, s60, 0x82000
	s_addc_u32 s9, s61, 0
	s_mov_b32 m0, s30
	s_nop 0
	global_load_lds_dwordx4 v188, s[8:9]
	s_cmp_lg_u32 s1, 1
	s_cbranch_scc1 .LBB0_602
.LBB0_602:
	s_add_u32 s8, s4, 0x29c30000
	s_addc_u32 s9, s5, 0
	s_cmp_eq_u32 s13, 0
	s_cselect_b64 s[10:11], -1, 0
	s_and_b64 s[10:11], s[2:3], s[10:11]
	s_add_u32 s37, s4, 0x31c34000
	s_addc_u32 s38, s5, 0
	s_and_b64 s[10:11], s[10:11], exec
	s_cselect_b32 s11, s38, s9
	s_cselect_b32 s10, s37, s8
	s_add_u32 s37, s4, 0xa61c000
	v_lshrrev_b32_e32 v2, 1, v0
	s_addc_u32 s38, s5, 0
	v_and_b32_e32 v2, 24, v2
	s_lshl_b32 s0, s0, 5
	v_and_b32_e32 v1, 15, v0
	v_lshlrev_b32_e32 v3, 1, v2
	v_lshlrev_b32_e32 v0, 2, v0
	s_and_b32 s4, s0, 0x60
	v_lshl_or_b32 v233, s1, 6, v1
	v_lshl_or_b32 v1, v1, 6, v3
	s_lshl_b32 s1, s1, 13
	v_and_b32_e32 v0, 32, v0
	s_lshl_b32 s0, s4, 7
	s_add_i32 s39, s22, 0x18000
	v_bitop3_b32 v3, v1, s1, v0 bitop3:0xde
	v_bitop3_b32 v0, v1, s0, v0 bitop3:0xde
	s_add_u32 s0, s62, 0x4000
	s_addc_u32 s1, s63, 0
	s_add_i32 s40, s22, 0x1a000
	s_waitcnt vmcnt(4)
	s_barrier
	s_mov_b32 m0, s39
	s_nop 0
	global_load_lds_dwordx4 v188, s[0:1]
	s_add_u32 s0, s62, 0x6000
	s_addc_u32 s1, s63, 0
	s_add_i32 s41, s22, 0x8000
	s_mov_b32 m0, s40
	s_nop 0
	global_load_lds_dwordx4 v188, s[0:1]
	s_add_u32 s0, s60, 0x4000
	s_addc_u32 s1, s61, 0
	s_add_i32 s42, s22, 0xa000
	s_mov_b32 m0, s41
	s_nop 0
	global_load_lds_dwordx4 v188, s[0:1]
	s_add_u32 s0, s60, 0x6000
	s_addc_u32 s1, s61, 0
	s_add_i32 s43, s22, 0x1c000
	s_mov_b32 m0, s42
	s_nop 0
	global_load_lds_dwordx4 v188, s[0:1]
	s_add_u32 s0, s62, 0x84000
	s_addc_u32 s1, s63, 0
	s_add_i32 s66, s22, 0x1e000
	s_mov_b32 m0, s43
	s_nop 0
	global_load_lds_dwordx4 v188, s[0:1]
	s_add_u32 s0, s62, 0x86000
	s_addc_u32 s1, s63, 0
	s_mov_b32 m0, s66
	s_nop 0
	global_load_lds_dwordx4 v188, s[0:1]
	s_waitcnt vmcnt(6)
	v_readlane_b32 s0, v255, 15
	s_mov_b32 s34, 0
	s_add_i32 s67, s22, 0xc000
	s_add_i32 s68, s22, 0xe000
	v_or_b32_e32 v234, s4, v2
	v_add_u32_e32 v236, 0x10000, v0
	v_add_u32_e32 v237, 0, v3
	v_readlane_b32 s51, v255, 14
	s_mov_b32 s50, s0
	s_barrier
	v_readlane_b32 s1, v255, 16

; #define PG8_STAGE(bufoff, gbase, hoff, imm) do { _Pragma("unroll") for (int _i = 0; _i < 2; ++_i) { \
;         asm volatile("s_mov_b32 m0, %0\n\ts_nop 0\n\tglobal_load_lds_dwordx4 %1, %2" \
;             :: "s"(lds0 + (unsigned)((bufoff) + _i * 8192)), "v"(voff0), "s"((const char*)(gbase) + (size_t)(hoff) + (size_t)(_i * 8192)) : "memory"); } } while (0)
; #define PG8_LDA(dst, b, h) do { _Pragma("unroll") for (int m = 0; m < 4; ++m) _Pragma("unroll") for (int k = 0; k < 2; ++k) dst[m][k] = *(const LAS bf16x8*)(lds + PG8_SA(b, h) + aoff + m * 2048 + k * 1024); } while (0)
; #define PG8_LDB(dst, b, h) do { _Pragma("unroll") for (int n = 0; n < 2; ++n) _Pragma("unroll") for (int k = 0; k < 2; ++k) dst[n][k] = *(const LAS bf16x8*)(lds + PG8_SB(b, h) + boff + n * 2048 + k * 1024); } while (0)
; #define PG8_WAIT_V(n) asm volatile("s_waitcnt vmcnt(" #n ")" ::: "memory")
; #define PG8_WAIT_L(n) asm volatile("s_waitcnt lgkmcnt(" #n ")" ::: "memory")
; #define PG8_BAR __builtin_amdgcn_s_barrier()
; template <class Epi>
; __device__ __forceinline__ void gemm_phase(LAS unsigned char* lds, const Gemm g, const StaticOrder& S, const Epi& E) {
;     ...
;         const bool has_next = S.next(ui + 1, nxt);
;         const char* nA = has_next ? (const char*)g.A + (size_t)nxt.pm * tstepA + (size_t)(nxt.pn >> g.gshift) * g.gstride : cA;
;         const char* nB = has_next ? (const char*)g.Bt + (size_t)nxt.pn * tstepB : cB;
;         for (int t = 0; t < nt; t += 2) {
;             const bool last = (t == nt - 2);
;             if (last) E.pre(cur, wid, lane, (unsigned)(size_t)(lds + STAGE_BYTES));
;             const char* aT = cA + (size_t)t * KS;
;             const char* a2 = last ? nA : aT + 2 * KS; const char* b2 = last ? nB : cB + (size_t)(t + 2) * KS;
;             PG8_LDB(B0, 0, 0); PG8_SCHED; PG8_LDA(At, 0, 0); PG8_STAGE(PG8_SA(1, 1), aT + KS, hA, 0);
;             PG8_WAIT_L(8); PG8_BAR; PG8_WAIT_L(0); PG8_MMA(0, 0, At, B0); PG8_BAR; PG8_SCHED;
;             PG8_LDB(B1, 0, 1); PG8_STAGE(PG8_SB(0, 0), b2, 0, 0);
;             PG8_BAR; PG8_WAIT_L(0); PG8_MMA(0, 1, At, B1); PG8_BAR;
;             PG8_LDA(At, 0, 1); PG8_STAGE(PG8_SA(0, 0), a2, 0, 0);
;             PG8_BAR; PG8_WAIT_L(0); PG8_MMA(1, 0, At, B0); PG8_BAR; PG8_SCHED;
;             PG8_STAGE(PG8_SB(0, 1), b2, hB, 0);
;             PG8_WAIT_V(6); PG8_BAR; PG8_MMA(1, 1, At, B1); PG8_BAR;
.LBB0_609:
	s_ashr_i32 s55, s54, 31
	s_lshl_b64 s[0:1], s[54:55], 20
	v_cmp_lt_i64_e32 vcc, s[56:57], v[192:193]
	s_add_u32 s56, s6, s0
	s_addc_u32 s57, s7, s1
	s_and_b64 s[0:1], vcc, exec
	s_cselect_b32 s0, s57, s61
	s_cselect_b32 s1, s56, s60
	s_ashr_i32 s53, s52, 31
	s_lshl_b64 s[48:49], s[52:53], 20
	s_add_u32 s58, s17, s48
	s_addc_u32 s59, s21, s49
	s_and_b64 s[48:49], vcc, exec
	s_cselect_b32 s53, s59, s63
	s_cselect_b32 s55, s58, s62
	s_add_u32 s69, s62, 0x8000
	s_addc_u32 s70, s63, 0
	s_mov_b32 s71, -2
	s_waitcnt vmcnt(16)
	v_readfirstlane_b32 s48, v235
	s_nop 1
	s_cmpk_lt_u32 s48, 0x100
	s_cbranch_scc1 .Lsout_st_skip
	s_barrier
.Lsout_st_skip:
	s_add_u32 s62, s60, 0x8000
	s_addc_u32 s63, s61, 0
	ds_read_b128 v[120:123], v236
	ds_read_b128 v[124:127], v236 offset:1024
	ds_read_b128 v[128:131], v236 offset:2048
	ds_read_b128 v[132:135], v236 offset:3072
	s_add_u32 s48, s60, 0x84000
	s_addc_u32 s49, s61, 0
	s_add_u32 s64, s60, 0x86000
	s_addc_u32 s65, s61, 0
	s_cmp_eq_u32 s71, 28
	s_cselect_b32 s61, s0, s63
	s_cselect_b32 s60, s1, s62
	ds_read_b128 v[136:139], v237
	ds_read_b128 v[140:143], v237 offset:1024
	ds_read_b128 v[152:155], v237 offset:2048
	ds_read_b128 v[156:159], v237 offset:3072
	ds_read_b128 v[160:163], v237 offset:4096
	ds_read_b128 v[164:167], v237 offset:5120
	ds_read_b128 v[168:171], v237 offset:6144
	ds_read_b128 v[172:175], v237 offset:7168
	s_mov_b32 m0, s67
	s_nop 0
	global_load_lds_dwordx4 v188, s[48:49]
	s_mov_b32 m0, s68
	s_nop 0
	global_load_lds_dwordx4 v188, s[64:65]
	s_waitcnt lgkmcnt(8)
	s_waitcnt vmcnt(10)
	s_barrier
	s_waitcnt lgkmcnt(7)
	v_mfma_f32_16x16x32_bf16 v[148:151], v[120:123], v[136:139], 0
	v_mfma_f32_16x16x32_bf16 v[144:147], v[128:131], v[136:139], 0
	s_waitcnt lgkmcnt(5)
	v_mfma_f32_16x16x32_bf16 v[108:111], v[120:123], v[152:155], 0
	v_mfma_f32_16x16x32_bf16 v[104:107], v[128:131], v[152:155], 0
	s_waitcnt lgkmcnt(3)
	v_mfma_f32_16x16x32_bf16 v[92:95], v[120:123], v[160:163], 0
	v_mfma_f32_16x16x32_bf16 v[88:91], v[128:131], v[160:163], 0
	s_waitcnt lgkmcnt(1)
	v_mfma_f32_16x16x32_bf16 v[76:79], v[120:123], v[168:171], 0
	v_mfma_f32_16x16x32_bf16 v[72:75], v[128:131], v[168:171], 0
	v_mfma_f32_16x16x32_bf16 v[148:151], v[124:127], v[140:143], v[148:151]
	v_mfma_f32_16x16x32_bf16 v[144:147], v[132:135], v[140:143], v[144:147]
	v_mfma_f32_16x16x32_bf16 v[108:111], v[124:127], v[156:159], v[108:111]
	v_mfma_f32_16x16x32_bf16 v[104:107], v[132:135], v[156:159], v[104:107]
	v_mfma_f32_16x16x32_bf16 v[92:95], v[124:127], v[164:167], v[92:95]
	v_mfma_f32_16x16x32_bf16 v[88:91], v[132:135], v[164:167], v[88:91]
	s_waitcnt lgkmcnt(0)
	v_mfma_f32_16x16x32_bf16 v[76:79], v[124:127], v[172:175], v[76:79]
	v_mfma_f32_16x16x32_bf16 v[72:75], v[132:135], v[172:175], v[72:75]
	s_barrier
	ds_read_b128 v[176:179], v236 offset:16384
	ds_read_b128 v[180:183], v236 offset:17408
	ds_read_b128 v[184:187], v236 offset:18432
	ds_read_b128 v[200:203], v236 offset:19456
	s_cselect_b32 s64, s55, s69
	s_cselect_b32 s65, s53, s70
	s_mov_b32 m0, s24
	s_nop 0
	global_load_lds_dwordx4 v188, s[64:65]
	s_add_u32 s48, s64, 0x2000
	s_addc_u32 s49, s65, 0
	s_mov_b32 m0, s25
	s_nop 0
	global_load_lds_dwordx4 v188, s[48:49]
	s_waitcnt vmcnt(10)
	s_barrier
	s_waitcnt lgkmcnt(3)
	v_mfma_f32_16x16x32_bf16 v[116:119], v[176:179], v[136:139], 0
	s_waitcnt lgkmcnt(1)
	v_mfma_f32_16x16x32_bf16 v[112:115], v[184:187], v[136:139], 0
	v_mfma_f32_16x16x32_bf16 v[100:103], v[176:179], v[152:155], 0
	v_mfma_f32_16x16x32_bf16 v[96:99], v[184:187], v[152:155], 0
	v_mfma_f32_16x16x32_bf16 v[84:87], v[176:179], v[160:163], 0
	v_mfma_f32_16x16x32_bf16 v[80:83], v[184:187], v[160:163], 0
	v_mfma_f32_16x16x32_bf16 v[68:71], v[176:179], v[168:171], 0
	v_mfma_f32_16x16x32_bf16 v[64:67], v[184:187], v[168:171], 0
	v_mfma_f32_16x16x32_bf16 v[116:119], v[180:183], v[140:143], v[116:119]
	s_waitcnt lgkmcnt(0)
	v_mfma_f32_16x16x32_bf16 v[112:115], v[200:203], v[140:143], v[112:115]
	v_mfma_f32_16x16x32_bf16 v[100:103], v[180:183], v[156:159], v[100:103]
	v_mfma_f32_16x16x32_bf16 v[96:99], v[200:203], v[156:159], v[96:99]
	v_mfma_f32_16x16x32_bf16 v[84:87], v[180:183], v[164:167], v[84:87]
	v_mfma_f32_16x16x32_bf16 v[80:83], v[200:203], v[164:167], v[80:83]
	v_mfma_f32_16x16x32_bf16 v[68:71], v[180:183], v[172:175], v[68:71]
	v_mfma_f32_16x16x32_bf16 v[64:67], v[200:203], v[172:175], v[64:67]
	s_barrier
	ds_read_b128 v[136:139], v237 offset:16384
	ds_read_b128 v[140:143], v237 offset:17408
	ds_read_b128 v[152:155], v237 offset:18432
	ds_read_b128 v[156:159], v237 offset:19456
	ds_read_b128 v[160:163], v237 offset:20480
	ds_read_b128 v[164:167], v237 offset:21504
	ds_read_b128 v[168:171], v237 offset:22528
	ds_read_b128 v[172:175], v237 offset:23552
	s_mov_b32 m0, s22
	s_nop 0
	global_load_lds_dwordx4 v188, s[60:61]
	s_add_u32 s48, s60, 0x2000
	s_addc_u32 s49, s61, 0
	s_mov_b32 m0, s26
	s_nop 0
	global_load_lds_dwordx4 v188, s[48:49]
	s_barrier
	s_waitcnt lgkmcnt(7)
	v_mfma_f32_16x16x32_bf16 v[60:63], v[120:123], v[136:139], 0
	v_mfma_f32_16x16x32_bf16 v[56:59], v[128:131], v[136:139], 0
	s_waitcnt lgkmcnt(5)
	v_mfma_f32_16x16x32_bf16 v[44:47], v[120:123], v[152:155], 0
	v_mfma_f32_16x16x32_bf16 v[40:43], v[128:131], v[152:155], 0
	s_waitcnt lgkmcnt(3)
	v_mfma_f32_16x16x32_bf16 v[28:31], v[120:123], v[160:163], 0
	v_mfma_f32_16x16x32_bf16 v[24:27], v[128:131], v[160:163], 0
	s_waitcnt lgkmcnt(1)
	v_mfma_f32_16x16x32_bf16 v[12:15], v[120:123], v[168:171], 0
	v_mfma_f32_16x16x32_bf16 v[8:11], v[128:131], v[168:171], 0
	v_mfma_f32_16x16x32_bf16 v[60:63], v[124:127], v[140:143], v[60:63]
	v_mfma_f32_16x16x32_bf16 v[56:59], v[132:135], v[140:143], v[56:59]
	v_mfma_f32_16x16x32_bf16 v[44:47], v[124:127], v[156:159], v[44:47]
	v_mfma_f32_16x16x32_bf16 v[40:43], v[132:135], v[156:159], v[40:43]
	v_mfma_f32_16x16x32_bf16 v[28:31], v[124:127], v[164:167], v[28:31]
	v_mfma_f32_16x16x32_bf16 v[24:27], v[132:135], v[164:167], v[24:27]
	s_waitcnt lgkmcnt(0)
	v_mfma_f32_16x16x32_bf16 v[12:15], v[124:127], v[172:175], v[12:15]
	v_mfma_f32_16x16x32_bf16 v[8:11], v[132:135], v[172:175], v[8:11]
	s_barrier
; #define PG8_STAGE(bufoff, gbase, hoff, imm) do { _Pragma("unroll") for (int _i = 0; _i < 2; ++_i) { \
;         asm volatile("s_mov_b32 m0, %0\n\ts_nop 0\n\tglobal_load_lds_dwordx4 %1, %2" \
;             :: "s"(lds0 + (unsigned)((bufoff) + _i * 8192)), "v"(voff0), "s"((const char*)(gbase) + (size_t)(hoff) + (size_t)(_i * 8192)) : "memory"); } } while (0)
; #define PG8_LDA(dst, b, h) do { _Pragma("unroll") for (int m = 0; m < 4; ++m) _Pragma("unroll") for (int k = 0; k < 2; ++k) dst[m][k] = *(const LAS bf16x8*)(lds + PG8_SA(b, h) + aoff + m * 2048 + k * 1024); } while (0)
; #define PG8_LDB(dst, b, h) do { _Pragma("unroll") for (int n = 0; n < 2; ++n) _Pragma("unroll") for (int k = 0; k < 2; ++k) dst[n][k] = *(const LAS bf16x8*)(lds + PG8_SB(b, h) + boff + n * 2048 + k * 1024); } while (0)
; #define PG8_MMA(ai, bj, At, Bt) do { __builtin_amdgcn_s_setprio(1); _Pragma("unroll") for (int m = 0; m < 4; ++m) _Pragma("unroll") for (int n = 0; n < 2; ++n) _Pragma("unroll") for (int k = 0; k < 2; ++k) \
;         acc[ai][bj][m][n] = __builtin_amdgcn_mfma_f32_16x16x32_bf16(Bt[n][k], At[m][k], acc[ai][bj][m][n], 0, 0, 0); __builtin_amdgcn_s_setprio(0); } while (0)
; #define PG8_WAIT_V(n) asm volatile("s_waitcnt vmcnt(" #n ")" ::: "memory")
; #define PG8_WAIT_L(n) asm volatile("s_waitcnt lgkmcnt(" #n ")" ::: "memory")
; template <class Epi>
; __device__ __forceinline__ void gemm_phase(LAS unsigned char* lds, const Gemm g, const StaticOrder& S, const Epi& E) {
;     ...
;             PG8_LDA(At, 0, 1); PG8_STAGE(PG8_SA(0, 0), a2, 0, 0);
;             PG8_BAR; PG8_WAIT_L(0); PG8_MMA(1, 0, At, B0); PG8_BAR; PG8_SCHED;
;             PG8_STAGE(PG8_SB(0, 1), b2, hB, 0);
;             PG8_WAIT_V(6); PG8_BAR; PG8_MMA(1, 1, At, B1); PG8_BAR;
;             PG8_LDB(B0, 1, 0); PG8_SCHED; PG8_LDA(At, 1, 0); PG8_STAGE(PG8_SA(0, 1), a2, hA, 0);
;             PG8_WAIT_L(8); PG8_BAR; PG8_WAIT_L(0); PG8_MMA(0, 0, At, B0); PG8_BAR; PG8_SCHED;
;             PG8_LDB(B1, 1, 1); PG8_STAGE(PG8_SB(1, 0), b2 + KS, 0, 0);
;             PG8_BAR; PG8_WAIT_L(0); PG8_MMA(0, 1, At, B1); PG8_BAR;
;             PG8_LDA(At, 1, 1); PG8_STAGE(PG8_SA(1, 0), a2 + KS, 0, 0);
;             PG8_BAR; PG8_WAIT_L(0); PG8_MMA(1, 0, At, B0); PG8_BAR; PG8_SCHED;
;             PG8_STAGE(PG8_SB(1, 1), b2 + KS, hB, 0);
;             PG8_WAIT_V(6); PG8_BAR; PG8_MMA(1, 1, At, B1); PG8_BAR;
	s_add_u32 s48, s64, 0x80000
	s_addc_u32 s49, s65, 0
	s_mov_b32 m0, s27
	s_nop 0
	global_load_lds_dwordx4 v188, s[48:49]
	s_add_u32 s48, s64, 0x82000
	s_addc_u32 s49, s65, 0
	s_mov_b32 m0, s28
	s_nop 0
	global_load_lds_dwordx4 v188, s[48:49]
	s_waitcnt vmcnt(10)
	s_barrier
	v_mfma_f32_16x16x32_bf16 v[52:55], v[176:179], v[136:139], 0
	v_mfma_f32_16x16x32_bf16 v[48:51], v[184:187], v[136:139], 0
	v_mfma_f32_16x16x32_bf16 v[36:39], v[176:179], v[152:155], 0
	v_mfma_f32_16x16x32_bf16 v[32:35], v[184:187], v[152:155], 0
	v_mfma_f32_16x16x32_bf16 v[20:23], v[176:179], v[160:163], 0
	v_mfma_f32_16x16x32_bf16 v[16:19], v[184:187], v[160:163], 0
	v_mfma_f32_16x16x32_bf16 v[4:7], v[176:179], v[168:171], 0
	v_mfma_f32_16x16x32_bf16 v[0:3], v[184:187], v[168:171], 0
	v_mfma_f32_16x16x32_bf16 v[52:55], v[180:183], v[140:143], v[52:55]
	v_mfma_f32_16x16x32_bf16 v[48:51], v[200:203], v[140:143], v[48:51]
	v_mfma_f32_16x16x32_bf16 v[36:39], v[180:183], v[156:159], v[36:39]
	v_mfma_f32_16x16x32_bf16 v[32:35], v[200:203], v[156:159], v[32:35]
	v_mfma_f32_16x16x32_bf16 v[20:23], v[180:183], v[164:167], v[20:23]
	v_mfma_f32_16x16x32_bf16 v[16:19], v[200:203], v[164:167], v[16:19]
	v_mfma_f32_16x16x32_bf16 v[4:7], v[180:183], v[172:175], v[4:7]
	v_mfma_f32_16x16x32_bf16 v[0:3], v[200:203], v[172:175], v[0:3]
	s_barrier
	ds_read_b128 v[120:123], v236 offset:32768
	ds_read_b128 v[124:127], v236 offset:33792
	ds_read_b128 v[128:131], v236 offset:34816
	ds_read_b128 v[132:135], v236 offset:35840
	ds_read_b128 v[136:139], v237 offset:32768
	ds_read_b128 v[140:143], v237 offset:33792
	ds_read_b128 v[152:155], v237 offset:34816
	ds_read_b128 v[156:159], v237 offset:35840
	ds_read_b128 v[160:163], v237 offset:36864
	ds_read_b128 v[164:167], v237 offset:37888
	ds_read_b128 v[168:171], v237 offset:38912
	ds_read_b128 v[172:175], v237 offset:39936
	s_add_u32 s48, s60, 0x80000
	s_addc_u32 s49, s61, 0
	s_mov_b32 m0, s29
	s_nop 0
	global_load_lds_dwordx4 v188, s[48:49]
	s_add_u32 s48, s60, 0x82000
	s_addc_u32 s49, s61, 0
	s_mov_b32 m0, s30
	s_nop 0
	global_load_lds_dwordx4 v188, s[48:49]
	s_waitcnt lgkmcnt(8)
	s_waitcnt vmcnt(10)
	s_barrier
	s_waitcnt lgkmcnt(7)
	v_mfma_f32_16x16x32_bf16 v[148:151], v[120:123], v[136:139], v[148:151]
	v_mfma_f32_16x16x32_bf16 v[144:147], v[128:131], v[136:139], v[144:147]
	s_waitcnt lgkmcnt(5)
	v_mfma_f32_16x16x32_bf16 v[108:111], v[120:123], v[152:155], v[108:111]
	v_mfma_f32_16x16x32_bf16 v[104:107], v[128:131], v[152:155], v[104:107]
	s_waitcnt lgkmcnt(3)
	v_mfma_f32_16x16x32_bf16 v[92:95], v[120:123], v[160:163], v[92:95]
	v_mfma_f32_16x16x32_bf16 v[88:91], v[128:131], v[160:163], v[88:91]
	s_waitcnt lgkmcnt(1)
	v_mfma_f32_16x16x32_bf16 v[76:79], v[120:123], v[168:171], v[76:79]
	v_mfma_f32_16x16x32_bf16 v[72:75], v[128:131], v[168:171], v[72:75]
	v_mfma_f32_16x16x32_bf16 v[148:151], v[124:127], v[140:143], v[148:151]
	v_mfma_f32_16x16x32_bf16 v[144:147], v[132:135], v[140:143], v[144:147]
	v_mfma_f32_16x16x32_bf16 v[108:111], v[124:127], v[156:159], v[108:111]
	v_mfma_f32_16x16x32_bf16 v[104:107], v[132:135], v[156:159], v[104:107]
	v_mfma_f32_16x16x32_bf16 v[92:95], v[124:127], v[164:167], v[92:95]
	v_mfma_f32_16x16x32_bf16 v[88:91], v[132:135], v[164:167], v[88:91]
	s_waitcnt lgkmcnt(0)
	v_mfma_f32_16x16x32_bf16 v[76:79], v[124:127], v[172:175], v[76:79]
	v_mfma_f32_16x16x32_bf16 v[72:75], v[132:135], v[172:175], v[72:75]
	s_barrier
	ds_read_b128 v[176:179], v236 offset:49152
	ds_read_b128 v[180:183], v236 offset:50176
	ds_read_b128 v[184:187], v236 offset:51200
	ds_read_b128 v[200:203], v236 offset:52224
	s_add_u32 s48, s64, 0x4000
	s_addc_u32 s49, s65, 0
	s_mov_b32 m0, s39
	s_nop 0
	global_load_lds_dwordx4 v188, s[48:49]
	s_add_u32 s48, s64, 0x6000
	s_addc_u32 s49, s65, 0
	s_mov_b32 m0, s40
	s_nop 0
	global_load_lds_dwordx4 v188, s[48:49]
	s_waitcnt vmcnt(10)
	s_barrier
	s_waitcnt lgkmcnt(3)
	v_mfma_f32_16x16x32_bf16 v[116:119], v[176:179], v[136:139], v[116:119]
	s_waitcnt lgkmcnt(1)
	v_mfma_f32_16x16x32_bf16 v[112:115], v[184:187], v[136:139], v[112:115]
	v_mfma_f32_16x16x32_bf16 v[100:103], v[176:179], v[152:155], v[100:103]
	v_mfma_f32_16x16x32_bf16 v[96:99], v[184:187], v[152:155], v[96:99]
	v_mfma_f32_16x16x32_bf16 v[84:87], v[176:179], v[160:163], v[84:87]
	v_mfma_f32_16x16x32_bf16 v[80:83], v[184:187], v[160:163], v[80:83]
	v_mfma_f32_16x16x32_bf16 v[68:71], v[176:179], v[168:171], v[68:71]
	v_mfma_f32_16x16x32_bf16 v[64:67], v[184:187], v[168:171], v[64:67]
	v_mfma_f32_16x16x32_bf16 v[116:119], v[180:183], v[140:143], v[116:119]
	s_waitcnt lgkmcnt(0)
	v_mfma_f32_16x16x32_bf16 v[112:115], v[200:203], v[140:143], v[112:115]
	v_mfma_f32_16x16x32_bf16 v[100:103], v[180:183], v[156:159], v[100:103]
	v_mfma_f32_16x16x32_bf16 v[96:99], v[200:203], v[156:159], v[96:99]
	v_mfma_f32_16x16x32_bf16 v[84:87], v[180:183], v[164:167], v[84:87]
	v_mfma_f32_16x16x32_bf16 v[80:83], v[200:203], v[164:167], v[80:83]
	v_mfma_f32_16x16x32_bf16 v[68:71], v[180:183], v[172:175], v[68:71]
	v_mfma_f32_16x16x32_bf16 v[64:67], v[200:203], v[172:175], v[64:67]
	s_barrier
	ds_read_b128 v[136:139], v237 offset:49152
	ds_read_b128 v[140:143], v237 offset:50176
	ds_read_b128 v[152:155], v237 offset:51200
	ds_read_b128 v[156:159], v237 offset:52224
	ds_read_b128 v[160:163], v237 offset:53248
	ds_read_b128 v[164:167], v237 offset:54272
	ds_read_b128 v[168:171], v237 offset:55296
	ds_read_b128 v[172:175], v237 offset:56320
	s_add_u32 s48, s60, 0x4000
	s_addc_u32 s49, s61, 0
	s_mov_b32 m0, s41
	s_nop 0
	global_load_lds_dwordx4 v188, s[48:49]
	s_add_u32 s48, s60, 0x6000
	s_addc_u32 s49, s61, 0
	s_mov_b32 m0, s42
	s_nop 0
	global_load_lds_dwordx4 v188, s[48:49]
	s_barrier
; #define PG8_STAGE(bufoff, gbase, hoff, imm) do { _Pragma("unroll") for (int _i = 0; _i < 2; ++_i) { \
;         asm volatile("s_mov_b32 m0, %0\n\ts_nop 0\n\tglobal_load_lds_dwordx4 %1, %2" \
;             :: "s"(lds0 + (unsigned)((bufoff) + _i * 8192)), "v"(voff0), "s"((const char*)(gbase) + (size_t)(hoff) + (size_t)(_i * 8192)) : "memory"); } } while (0)
; #define PG8_LDA(dst, b, h) do { _Pragma("unroll") for (int m = 0; m < 4; ++m) _Pragma("unroll") for (int k = 0; k < 2; ++k) dst[m][k] = *(const LAS bf16x8*)(lds + PG8_SA(b, h) + aoff + m * 2048 + k * 1024); } while (0)
; #define PG8_LDB(dst, b, h) do { _Pragma("unroll") for (int n = 0; n < 2; ++n) _Pragma("unroll") for (int k = 0; k < 2; ++k) dst[n][k] = *(const LAS bf16x8*)(lds + PG8_SB(b, h) + boff + n * 2048 + k * 1024); } while (0)
; #define PG8_BAR __builtin_amdgcn_s_barrier()
; template <class Epi>
; __device__ __forceinline__ void gemm_phase(LAS unsigned char* lds, const Gemm g, const StaticOrder& S, const Epi& E) {
;     ...
;             const char* aT = cA + (size_t)t * KS;
;             const char* a2 = last ? nA : aT + 2 * KS; const char* b2 = last ? nB : cB + (size_t)(t + 2) * KS;
;             PG8_LDB(B0, 0, 0); PG8_SCHED; PG8_LDA(At, 0, 0); PG8_STAGE(PG8_SA(1, 1), aT + KS, hA, 0);
;             PG8_WAIT_L(8); PG8_BAR; PG8_WAIT_L(0); PG8_MMA(0, 0, At, B0); PG8_BAR; PG8_SCHED;
;             PG8_LDB(B1, 0, 1); PG8_STAGE(PG8_SB(0, 0), b2, 0, 0);
;             PG8_BAR; PG8_WAIT_L(0); PG8_MMA(0, 1, At, B1); PG8_BAR;
;             PG8_LDA(At, 0, 1); PG8_STAGE(PG8_SA(0, 0), a2, 0, 0);
;             PG8_BAR; PG8_WAIT_L(0); PG8_MMA(1, 0, At, B0); PG8_BAR; PG8_SCHED;
;             PG8_STAGE(PG8_SB(0, 1), b2, hB, 0);
;             PG8_WAIT_V(6); PG8_BAR; PG8_MMA(1, 1, At, B1); PG8_BAR;
;             PG8_LDB(B0, 1, 0); PG8_SCHED; PG8_LDA(At, 1, 0); PG8_STAGE(PG8_SA(0, 1), a2, hA, 0);
;             PG8_WAIT_L(8); PG8_BAR; PG8_WAIT_L(0); PG8_MMA(0, 0, At, B0); PG8_BAR; PG8_SCHED;
;             PG8_LDB(B1, 1, 1); PG8_STAGE(PG8_SB(1, 0), b2 + KS, 0, 0);
;             PG8_BAR; PG8_WAIT_L(0); PG8_MMA(0, 1, At, B1); PG8_BAR;
;             PG8_LDA(At, 1, 1); PG8_STAGE(PG8_SA(1, 0), a2 + KS, 0, 0);
;             PG8_BAR; PG8_WAIT_L(0); PG8_MMA(1, 0, At, B0); PG8_BAR; PG8_SCHED;
;             PG8_STAGE(PG8_SB(1, 1), b2 + KS, hB, 0);
;             PG8_WAIT_V(6); PG8_BAR; PG8_MMA(1, 1, At, B1); PG8_BAR;
	s_waitcnt lgkmcnt(7)
	v_mfma_f32_16x16x32_bf16 v[60:63], v[120:123], v[136:139], v[60:63]
	v_mfma_f32_16x16x32_bf16 v[56:59], v[128:131], v[136:139], v[56:59]
	s_waitcnt lgkmcnt(5)
	v_mfma_f32_16x16x32_bf16 v[44:47], v[120:123], v[152:155], v[44:47]
	v_mfma_f32_16x16x32_bf16 v[40:43], v[128:131], v[152:155], v[40:43]
	s_waitcnt lgkmcnt(3)
	v_mfma_f32_16x16x32_bf16 v[28:31], v[120:123], v[160:163], v[28:31]
	v_mfma_f32_16x16x32_bf16 v[24:27], v[128:131], v[160:163], v[24:27]
	s_waitcnt lgkmcnt(1)
	v_mfma_f32_16x16x32_bf16 v[12:15], v[120:123], v[168:171], v[12:15]
	v_mfma_f32_16x16x32_bf16 v[8:11], v[128:131], v[168:171], v[8:11]
	v_mfma_f32_16x16x32_bf16 v[60:63], v[124:127], v[140:143], v[60:63]
	v_mfma_f32_16x16x32_bf16 v[56:59], v[132:135], v[140:143], v[56:59]
	v_mfma_f32_16x16x32_bf16 v[44:47], v[124:127], v[156:159], v[44:47]
	v_mfma_f32_16x16x32_bf16 v[40:43], v[132:135], v[156:159], v[40:43]
	v_mfma_f32_16x16x32_bf16 v[28:31], v[124:127], v[164:167], v[28:31]
	v_mfma_f32_16x16x32_bf16 v[24:27], v[132:135], v[164:167], v[24:27]
	s_waitcnt lgkmcnt(0)
	v_mfma_f32_16x16x32_bf16 v[12:15], v[124:127], v[172:175], v[12:15]
	v_mfma_f32_16x16x32_bf16 v[8:11], v[132:135], v[172:175], v[8:11]
	s_barrier
	s_add_u32 s48, s64, 0x84000
	s_addc_u32 s49, s65, 0
	s_mov_b32 m0, s43
	s_nop 0
	global_load_lds_dwordx4 v188, s[48:49]
	s_add_u32 s48, s64, 0x86000
	s_addc_u32 s49, s65, 0
	s_mov_b32 m0, s66
	s_nop 0
	global_load_lds_dwordx4 v188, s[48:49]
	s_waitcnt vmcnt(10)
	s_barrier
	v_mfma_f32_16x16x32_bf16 v[52:55], v[176:179], v[136:139], v[52:55]
	v_mfma_f32_16x16x32_bf16 v[48:51], v[184:187], v[136:139], v[48:51]
	v_mfma_f32_16x16x32_bf16 v[36:39], v[176:179], v[152:155], v[36:39]
	v_mfma_f32_16x16x32_bf16 v[32:35], v[184:187], v[152:155], v[32:35]
	v_mfma_f32_16x16x32_bf16 v[20:23], v[176:179], v[160:163], v[20:23]
	v_mfma_f32_16x16x32_bf16 v[16:19], v[184:187], v[160:163], v[16:19]
	v_mfma_f32_16x16x32_bf16 v[4:7], v[176:179], v[168:171], v[4:7]
	v_mfma_f32_16x16x32_bf16 v[0:3], v[184:187], v[168:171], v[0:3]
	v_mfma_f32_16x16x32_bf16 v[52:55], v[180:183], v[140:143], v[52:55]
	v_mfma_f32_16x16x32_bf16 v[48:51], v[200:203], v[140:143], v[48:51]
	v_mfma_f32_16x16x32_bf16 v[36:39], v[180:183], v[156:159], v[36:39]
	v_mfma_f32_16x16x32_bf16 v[32:35], v[200:203], v[156:159], v[32:35]
	v_mfma_f32_16x16x32_bf16 v[20:23], v[180:183], v[164:167], v[20:23]
	v_mfma_f32_16x16x32_bf16 v[16:19], v[200:203], v[164:167], v[16:19]
	v_mfma_f32_16x16x32_bf16 v[4:7], v[180:183], v[172:175], v[4:7]
	v_mfma_f32_16x16x32_bf16 v[0:3], v[200:203], v[172:175], v[0:3]
	s_add_i32 s71, s71, 2
	s_add_u32 s69, s69, 0x8000
	s_addc_u32 s70, s70, 0
	s_cmp_gt_u32 s71, 29
	s_mov_b64 s[60:61], s[62:63]
	s_barrier
.LBB0_610:
	s_add_u32 s62, s60, 0x8000
	s_addc_u32 s63, s61, 0
	ds_read_b128 v[120:123], v236
	ds_read_b128 v[124:127], v236 offset:1024
	ds_read_b128 v[128:131], v236 offset:2048
	ds_read_b128 v[132:135], v236 offset:3072
	s_add_u32 s48, s60, 0x84000
	s_addc_u32 s49, s61, 0
	s_add_u32 s64, s60, 0x86000
	s_addc_u32 s65, s61, 0
	s_cmp_eq_u32 s71, 28
	s_cselect_b32 s61, s0, s63
	s_cselect_b32 s60, s1, s62
	ds_read_b128 v[136:139], v237
	ds_read_b128 v[140:143], v237 offset:1024
	ds_read_b128 v[152:155], v237 offset:2048
	ds_read_b128 v[156:159], v237 offset:3072
	ds_read_b128 v[160:163], v237 offset:4096
	ds_read_b128 v[164:167], v237 offset:5120
	ds_read_b128 v[168:171], v237 offset:6144
	ds_read_b128 v[172:175], v237 offset:7168
	s_mov_b32 m0, s67
	s_nop 0
	global_load_lds_dwordx4 v188, s[48:49]
	s_mov_b32 m0, s68
	s_nop 0
	global_load_lds_dwordx4 v188, s[64:65]
	s_waitcnt lgkmcnt(8)
	s_waitcnt vmcnt(10)
	s_barrier
	s_waitcnt lgkmcnt(7)
	v_mfma_f32_16x16x32_bf16 v[148:151], v[120:123], v[136:139], v[148:151]
	v_mfma_f32_16x16x32_bf16 v[144:147], v[128:131], v[136:139], v[144:147]
	s_waitcnt lgkmcnt(5)
	v_mfma_f32_16x16x32_bf16 v[108:111], v[120:123], v[152:155], v[108:111]
	v_mfma_f32_16x16x32_bf16 v[104:107], v[128:131], v[152:155], v[104:107]
	s_waitcnt lgkmcnt(3)
	v_mfma_f32_16x16x32_bf16 v[92:95], v[120:123], v[160:163], v[92:95]
	v_mfma_f32_16x16x32_bf16 v[88:91], v[128:131], v[160:163], v[88:91]
	s_waitcnt lgkmcnt(1)
	v_mfma_f32_16x16x32_bf16 v[76:79], v[120:123], v[168:171], v[76:79]
	v_mfma_f32_16x16x32_bf16 v[72:75], v[128:131], v[168:171], v[72:75]
	v_mfma_f32_16x16x32_bf16 v[148:151], v[124:127], v[140:143], v[148:151]
	v_mfma_f32_16x16x32_bf16 v[144:147], v[132:135], v[140:143], v[144:147]
	v_mfma_f32_16x16x32_bf16 v[108:111], v[124:127], v[156:159], v[108:111]
	v_mfma_f32_16x16x32_bf16 v[104:107], v[132:135], v[156:159], v[104:107]
	v_mfma_f32_16x16x32_bf16 v[92:95], v[124:127], v[164:167], v[92:95]
	v_mfma_f32_16x16x32_bf16 v[88:91], v[132:135], v[164:167], v[88:91]
	s_waitcnt lgkmcnt(0)
	v_mfma_f32_16x16x32_bf16 v[76:79], v[124:127], v[172:175], v[76:79]
	v_mfma_f32_16x16x32_bf16 v[72:75], v[132:135], v[172:175], v[72:75]
	s_barrier
	ds_read_b128 v[176:179], v236 offset:16384
	ds_read_b128 v[180:183], v236 offset:17408
	ds_read_b128 v[184:187], v236 offset:18432
	ds_read_b128 v[200:203], v236 offset:19456
	s_cselect_b32 s64, s55, s69
	s_cselect_b32 s65, s53, s70
	s_mov_b32 m0, s24
	s_nop 0
	global_load_lds_dwordx4 v188, s[64:65]
	s_add_u32 s48, s64, 0x2000
	s_addc_u32 s49, s65, 0
	s_mov_b32 m0, s25
	s_nop 0
	global_load_lds_dwordx4 v188, s[48:49]
	s_waitcnt vmcnt(10)
	s_barrier
; #define PG8_STAGE(bufoff, gbase, hoff, imm) do { _Pragma("unroll") for (int _i = 0; _i < 2; ++_i) { \
;         asm volatile("s_mov_b32 m0, %0\n\ts_nop 0\n\tglobal_load_lds_dwordx4 %1, %2" \
;             :: "s"(lds0 + (unsigned)((bufoff) + _i * 8192)), "v"(voff0), "s"((const char*)(gbase) + (size_t)(hoff) + (size_t)(_i * 8192)) : "memory"); } } while (0)
; #define PG8_LDA(dst, b, h) do { _Pragma("unroll") for (int m = 0; m < 4; ++m) _Pragma("unroll") for (int k = 0; k < 2; ++k) dst[m][k] = *(const LAS bf16x8*)(lds + PG8_SA(b, h) + aoff + m * 2048 + k * 1024); } while (0)
; #define PG8_LDB(dst, b, h) do { _Pragma("unroll") for (int n = 0; n < 2; ++n) _Pragma("unroll") for (int k = 0; k < 2; ++k) dst[n][k] = *(const LAS bf16x8*)(lds + PG8_SB(b, h) + boff + n * 2048 + k * 1024); } while (0)
; #define PG8_MMA(ai, bj, At, Bt) do { __builtin_amdgcn_s_setprio(1); _Pragma("unroll") for (int m = 0; m < 4; ++m) _Pragma("unroll") for (int n = 0; n < 2; ++n) _Pragma("unroll") for (int k = 0; k < 2; ++k) \
;         acc[ai][bj][m][n] = __builtin_amdgcn_mfma_f32_16x16x32_bf16(Bt[n][k], At[m][k], acc[ai][bj][m][n], 0, 0, 0); __builtin_amdgcn_s_setprio(0); } while (0)
; #define PG8_WAIT_V(n) asm volatile("s_waitcnt vmcnt(" #n ")" ::: "memory")
; #define PG8_WAIT_L(n) asm volatile("s_waitcnt lgkmcnt(" #n ")" ::: "memory")
; template <class Epi>
; __device__ __forceinline__ void gemm_phase(LAS unsigned char* lds, const Gemm g, const StaticOrder& S, const Epi& E) {
;     ...
;             PG8_LDA(At, 0, 1); PG8_STAGE(PG8_SA(0, 0), a2, 0, 0);
;             PG8_BAR; PG8_WAIT_L(0); PG8_MMA(1, 0, At, B0); PG8_BAR; PG8_SCHED;
;             PG8_STAGE(PG8_SB(0, 1), b2, hB, 0);
;             PG8_WAIT_V(6); PG8_BAR; PG8_MMA(1, 1, At, B1); PG8_BAR;
;             PG8_LDB(B0, 1, 0); PG8_SCHED; PG8_LDA(At, 1, 0); PG8_STAGE(PG8_SA(0, 1), a2, hA, 0);
;             PG8_WAIT_L(8); PG8_BAR; PG8_WAIT_L(0); PG8_MMA(0, 0, At, B0); PG8_BAR; PG8_SCHED;
;             PG8_LDB(B1, 1, 1); PG8_STAGE(PG8_SB(1, 0), b2 + KS, 0, 0);
;             PG8_BAR; PG8_WAIT_L(0); PG8_MMA(0, 1, At, B1); PG8_BAR;
;             PG8_LDA(At, 1, 1); PG8_STAGE(PG8_SA(1, 0), a2 + KS, 0, 0);
;             PG8_BAR; PG8_WAIT_L(0); PG8_MMA(1, 0, At, B0); PG8_BAR; PG8_SCHED;
;             PG8_STAGE(PG8_SB(1, 1), b2 + KS, hB, 0);
;             PG8_WAIT_V(6); PG8_BAR; PG8_MMA(1, 1, At, B1); PG8_BAR;
	s_waitcnt lgkmcnt(3)
	v_mfma_f32_16x16x32_bf16 v[116:119], v[176:179], v[136:139], v[116:119]
	s_waitcnt lgkmcnt(1)
	v_mfma_f32_16x16x32_bf16 v[112:115], v[184:187], v[136:139], v[112:115]
	v_mfma_f32_16x16x32_bf16 v[100:103], v[176:179], v[152:155], v[100:103]
	v_mfma_f32_16x16x32_bf16 v[96:99], v[184:187], v[152:155], v[96:99]
	v_mfma_f32_16x16x32_bf16 v[84:87], v[176:179], v[160:163], v[84:87]
	v_mfma_f32_16x16x32_bf16 v[80:83], v[184:187], v[160:163], v[80:83]
	v_mfma_f32_16x16x32_bf16 v[68:71], v[176:179], v[168:171], v[68:71]
	v_mfma_f32_16x16x32_bf16 v[64:67], v[184:187], v[168:171], v[64:67]
	v_mfma_f32_16x16x32_bf16 v[116:119], v[180:183], v[140:143], v[116:119]
	s_waitcnt lgkmcnt(0)
	v_mfma_f32_16x16x32_bf16 v[112:115], v[200:203], v[140:143], v[112:115]
	v_mfma_f32_16x16x32_bf16 v[100:103], v[180:183], v[156:159], v[100:103]
	v_mfma_f32_16x16x32_bf16 v[96:99], v[200:203], v[156:159], v[96:99]
	v_mfma_f32_16x16x32_bf16 v[84:87], v[180:183], v[164:167], v[84:87]
	v_mfma_f32_16x16x32_bf16 v[80:83], v[200:203], v[164:167], v[80:83]
	v_mfma_f32_16x16x32_bf16 v[68:71], v[180:183], v[172:175], v[68:71]
	v_mfma_f32_16x16x32_bf16 v[64:67], v[200:203], v[172:175], v[64:67]
	s_barrier
	ds_read_b128 v[136:139], v237 offset:16384
	ds_read_b128 v[140:143], v237 offset:17408
	ds_read_b128 v[152:155], v237 offset:18432
	ds_read_b128 v[156:159], v237 offset:19456
	ds_read_b128 v[160:163], v237 offset:20480
	ds_read_b128 v[164:167], v237 offset:21504
	ds_read_b128 v[168:171], v237 offset:22528
	ds_read_b128 v[172:175], v237 offset:23552
	s_mov_b32 m0, s22
	s_nop 0
	global_load_lds_dwordx4 v188, s[60:61]
	s_add_u32 s48, s60, 0x2000
	s_addc_u32 s49, s61, 0
	s_mov_b32 m0, s26
	s_nop 0
	global_load_lds_dwordx4 v188, s[48:49]
	s_barrier
	s_waitcnt lgkmcnt(7)
	v_mfma_f32_16x16x32_bf16 v[60:63], v[120:123], v[136:139], v[60:63]
	v_mfma_f32_16x16x32_bf16 v[56:59], v[128:131], v[136:139], v[56:59]
	s_waitcnt lgkmcnt(5)
	v_mfma_f32_16x16x32_bf16 v[44:47], v[120:123], v[152:155], v[44:47]
	v_mfma_f32_16x16x32_bf16 v[40:43], v[128:131], v[152:155], v[40:43]
	s_waitcnt lgkmcnt(3)
	v_mfma_f32_16x16x32_bf16 v[28:31], v[120:123], v[160:163], v[28:31]
	v_mfma_f32_16x16x32_bf16 v[24:27], v[128:131], v[160:163], v[24:27]
	s_waitcnt lgkmcnt(1)
	v_mfma_f32_16x16x32_bf16 v[12:15], v[120:123], v[168:171], v[12:15]
	v_mfma_f32_16x16x32_bf16 v[8:11], v[128:131], v[168:171], v[8:11]
	v_mfma_f32_16x16x32_bf16 v[60:63], v[124:127], v[140:143], v[60:63]
	v_mfma_f32_16x16x32_bf16 v[56:59], v[132:135], v[140:143], v[56:59]
	v_mfma_f32_16x16x32_bf16 v[44:47], v[124:127], v[156:159], v[44:47]
	v_mfma_f32_16x16x32_bf16 v[40:43], v[132:135], v[156:159], v[40:43]
	v_mfma_f32_16x16x32_bf16 v[28:31], v[124:127], v[164:167], v[28:31]
	v_mfma_f32_16x16x32_bf16 v[24:27], v[132:135], v[164:167], v[24:27]
	s_waitcnt lgkmcnt(0)
	v_mfma_f32_16x16x32_bf16 v[12:15], v[124:127], v[172:175], v[12:15]
	v_mfma_f32_16x16x32_bf16 v[8:11], v[132:135], v[172:175], v[8:11]
	s_barrier
	s_add_u32 s48, s64, 0x80000
	s_addc_u32 s49, s65, 0
	s_mov_b32 m0, s27
	s_nop 0
	global_load_lds_dwordx4 v188, s[48:49]
	s_add_u32 s48, s64, 0x82000
	s_addc_u32 s49, s65, 0
	s_mov_b32 m0, s28
	s_nop 0
	global_load_lds_dwordx4 v188, s[48:49]
	s_waitcnt vmcnt(10)
	s_barrier
	v_mfma_f32_16x16x32_bf16 v[52:55], v[176:179], v[136:139], v[52:55]
	v_mfma_f32_16x16x32_bf16 v[48:51], v[184:187], v[136:139], v[48:51]
	v_mfma_f32_16x16x32_bf16 v[36:39], v[176:179], v[152:155], v[36:39]
	v_mfma_f32_16x16x32_bf16 v[32:35], v[184:187], v[152:155], v[32:35]
	v_mfma_f32_16x16x32_bf16 v[20:23], v[176:179], v[160:163], v[20:23]
	v_mfma_f32_16x16x32_bf16 v[16:19], v[184:187], v[160:163], v[16:19]
	v_mfma_f32_16x16x32_bf16 v[4:7], v[176:179], v[168:171], v[4:7]
	v_mfma_f32_16x16x32_bf16 v[0:3], v[184:187], v[168:171], v[0:3]
	v_mfma_f32_16x16x32_bf16 v[52:55], v[180:183], v[140:143], v[52:55]
	v_mfma_f32_16x16x32_bf16 v[48:51], v[200:203], v[140:143], v[48:51]
	v_mfma_f32_16x16x32_bf16 v[36:39], v[180:183], v[156:159], v[36:39]
	v_mfma_f32_16x16x32_bf16 v[32:35], v[200:203], v[156:159], v[32:35]
	v_mfma_f32_16x16x32_bf16 v[20:23], v[180:183], v[164:167], v[20:23]
	v_mfma_f32_16x16x32_bf16 v[16:19], v[200:203], v[164:167], v[16:19]
	v_mfma_f32_16x16x32_bf16 v[4:7], v[180:183], v[172:175], v[4:7]
	v_mfma_f32_16x16x32_bf16 v[0:3], v[200:203], v[172:175], v[0:3]
	s_barrier
	ds_read_b128 v[120:123], v236 offset:32768
	ds_read_b128 v[124:127], v236 offset:33792
	ds_read_b128 v[128:131], v236 offset:34816
	ds_read_b128 v[132:135], v236 offset:35840
	ds_read_b128 v[136:139], v237 offset:32768
	ds_read_b128 v[140:143], v237 offset:33792
	ds_read_b128 v[152:155], v237 offset:34816
	ds_read_b128 v[156:159], v237 offset:35840
	ds_read_b128 v[160:163], v237 offset:36864
	ds_read_b128 v[164:167], v237 offset:37888
	ds_read_b128 v[168:171], v237 offset:38912
	ds_read_b128 v[172:175], v237 offset:39936
	s_add_u32 s48, s60, 0x80000
	s_addc_u32 s49, s61, 0
	s_mov_b32 m0, s29
	s_nop 0
	global_load_lds_dwordx4 v188, s[48:49]
	s_add_u32 s48, s60, 0x82000
	s_addc_u32 s49, s61, 0
	s_mov_b32 m0, s30
	s_nop 0
	global_load_lds_dwordx4 v188, s[48:49]
	s_waitcnt lgkmcnt(8)
	s_waitcnt vmcnt(10)
	s_barrier
; #define PG8_STAGE(bufoff, gbase, hoff, imm) do { _Pragma("unroll") for (int _i = 0; _i < 2; ++_i) { \
;         asm volatile("s_mov_b32 m0, %0\n\ts_nop 0\n\tglobal_load_lds_dwordx4 %1, %2" \
;             :: "s"(lds0 + (unsigned)((bufoff) + _i * 8192)), "v"(voff0), "s"((const char*)(gbase) + (size_t)(hoff) + (size_t)(_i * 8192)) : "memory"); } } while (0)
; #define PG8_LDA(dst, b, h) do { _Pragma("unroll") for (int m = 0; m < 4; ++m) _Pragma("unroll") for (int k = 0; k < 2; ++k) dst[m][k] = *(const LAS bf16x8*)(lds + PG8_SA(b, h) + aoff + m * 2048 + k * 1024); } while (0)
; #define PG8_LDB(dst, b, h) do { _Pragma("unroll") for (int n = 0; n < 2; ++n) _Pragma("unroll") for (int k = 0; k < 2; ++k) dst[n][k] = *(const LAS bf16x8*)(lds + PG8_SB(b, h) + boff + n * 2048 + k * 1024); } while (0)
; #define PG8_MMA(ai, bj, At, Bt) do { __builtin_amdgcn_s_setprio(1); _Pragma("unroll") for (int m = 0; m < 4; ++m) _Pragma("unroll") for (int n = 0; n < 2; ++n) _Pragma("unroll") for (int k = 0; k < 2; ++k) \
;         acc[ai][bj][m][n] = __builtin_amdgcn_mfma_f32_16x16x32_bf16(Bt[n][k], At[m][k], acc[ai][bj][m][n], 0, 0, 0); __builtin_amdgcn_s_setprio(0); } while (0)
; #define PG8_WAIT_V(n) asm volatile("s_waitcnt vmcnt(" #n ")" ::: "memory")
; #define PG8_WAIT_L(n) asm volatile("s_waitcnt lgkmcnt(" #n ")" ::: "memory")
; #define PG8_BAR __builtin_amdgcn_s_barrier()
; #define PG8_SCHED __builtin_amdgcn_sched_barrier(0)
; template <class Epi>
; __device__ __forceinline__ void gemm_phase(LAS unsigned char* lds, const Gemm g, const StaticOrder& S, const Epi& E) {
;     ...
;             PG8_WAIT_V(6); PG8_BAR; PG8_MMA(1, 1, At, B1); PG8_BAR;
;             PG8_LDB(B0, 1, 0); PG8_SCHED; PG8_LDA(At, 1, 0); PG8_STAGE(PG8_SA(0, 1), a2, hA, 0);
;             PG8_WAIT_L(8); PG8_BAR; PG8_WAIT_L(0); PG8_MMA(0, 0, At, B0); PG8_BAR; PG8_SCHED;
;             PG8_LDB(B1, 1, 1); PG8_STAGE(PG8_SB(1, 0), b2 + KS, 0, 0);
;             PG8_BAR; PG8_WAIT_L(0); PG8_MMA(0, 1, At, B1); PG8_BAR;
;             PG8_LDA(At, 1, 1); PG8_STAGE(PG8_SA(1, 0), a2 + KS, 0, 0);
;             PG8_BAR; PG8_WAIT_L(0); PG8_MMA(1, 0, At, B0); PG8_BAR; PG8_SCHED;
;             PG8_STAGE(PG8_SB(1, 1), b2 + KS, hB, 0);
;             PG8_WAIT_V(6); PG8_BAR; PG8_MMA(1, 1, At, B1); PG8_BAR;
;         }
	s_waitcnt lgkmcnt(7)
	v_mfma_f32_16x16x32_bf16 v[148:151], v[120:123], v[136:139], v[148:151]
	v_mfma_f32_16x16x32_bf16 v[144:147], v[128:131], v[136:139], v[144:147]
	s_waitcnt lgkmcnt(5)
	v_mfma_f32_16x16x32_bf16 v[108:111], v[120:123], v[152:155], v[108:111]
	v_mfma_f32_16x16x32_bf16 v[104:107], v[128:131], v[152:155], v[104:107]
	s_waitcnt lgkmcnt(3)
	v_mfma_f32_16x16x32_bf16 v[92:95], v[120:123], v[160:163], v[92:95]
	v_mfma_f32_16x16x32_bf16 v[88:91], v[128:131], v[160:163], v[88:91]
	s_waitcnt lgkmcnt(1)
	v_mfma_f32_16x16x32_bf16 v[76:79], v[120:123], v[168:171], v[76:79]
	v_mfma_f32_16x16x32_bf16 v[72:75], v[128:131], v[168:171], v[72:75]
	v_mfma_f32_16x16x32_bf16 v[148:151], v[124:127], v[140:143], v[148:151]
	v_mfma_f32_16x16x32_bf16 v[144:147], v[132:135], v[140:143], v[144:147]
	v_mfma_f32_16x16x32_bf16 v[108:111], v[124:127], v[156:159], v[108:111]
	v_mfma_f32_16x16x32_bf16 v[104:107], v[132:135], v[156:159], v[104:107]
	v_mfma_f32_16x16x32_bf16 v[92:95], v[124:127], v[164:167], v[92:95]
	v_mfma_f32_16x16x32_bf16 v[88:91], v[132:135], v[164:167], v[88:91]
	s_waitcnt lgkmcnt(0)
	v_mfma_f32_16x16x32_bf16 v[76:79], v[124:127], v[172:175], v[76:79]
	v_mfma_f32_16x16x32_bf16 v[72:75], v[132:135], v[172:175], v[72:75]
	s_barrier
	ds_read_b128 v[176:179], v236 offset:49152
	ds_read_b128 v[180:183], v236 offset:50176
	ds_read_b128 v[184:187], v236 offset:51200
	ds_read_b128 v[200:203], v236 offset:52224
	s_add_u32 s48, s64, 0x4000
	s_addc_u32 s49, s65, 0
	s_mov_b32 m0, s39
	s_nop 0
	global_load_lds_dwordx4 v188, s[48:49]
	s_add_u32 s48, s64, 0x6000
	s_addc_u32 s49, s65, 0
	s_mov_b32 m0, s40
	s_nop 0
	global_load_lds_dwordx4 v188, s[48:49]
	s_waitcnt vmcnt(10)
	s_barrier
	s_waitcnt lgkmcnt(3)
	v_mfma_f32_16x16x32_bf16 v[116:119], v[176:179], v[136:139], v[116:119]
	s_waitcnt lgkmcnt(1)
	v_mfma_f32_16x16x32_bf16 v[112:115], v[184:187], v[136:139], v[112:115]
	v_mfma_f32_16x16x32_bf16 v[100:103], v[176:179], v[152:155], v[100:103]
	v_mfma_f32_16x16x32_bf16 v[96:99], v[184:187], v[152:155], v[96:99]
	v_mfma_f32_16x16x32_bf16 v[84:87], v[176:179], v[160:163], v[84:87]
	v_mfma_f32_16x16x32_bf16 v[80:83], v[184:187], v[160:163], v[80:83]
	v_mfma_f32_16x16x32_bf16 v[68:71], v[176:179], v[168:171], v[68:71]
	v_mfma_f32_16x16x32_bf16 v[64:67], v[184:187], v[168:171], v[64:67]
	v_mfma_f32_16x16x32_bf16 v[116:119], v[180:183], v[140:143], v[116:119]
	s_waitcnt lgkmcnt(0)
	v_mfma_f32_16x16x32_bf16 v[112:115], v[200:203], v[140:143], v[112:115]
	v_mfma_f32_16x16x32_bf16 v[100:103], v[180:183], v[156:159], v[100:103]
	v_mfma_f32_16x16x32_bf16 v[96:99], v[200:203], v[156:159], v[96:99]
	v_mfma_f32_16x16x32_bf16 v[84:87], v[180:183], v[164:167], v[84:87]
	v_mfma_f32_16x16x32_bf16 v[80:83], v[200:203], v[164:167], v[80:83]
	v_mfma_f32_16x16x32_bf16 v[68:71], v[180:183], v[172:175], v[68:71]
	v_mfma_f32_16x16x32_bf16 v[64:67], v[200:203], v[172:175], v[64:67]
	s_barrier
	ds_read_b128 v[136:139], v237 offset:49152
	ds_read_b128 v[140:143], v237 offset:50176
	ds_read_b128 v[152:155], v237 offset:51200
	ds_read_b128 v[156:159], v237 offset:52224
	ds_read_b128 v[160:163], v237 offset:53248
	ds_read_b128 v[164:167], v237 offset:54272
	ds_read_b128 v[168:171], v237 offset:55296
	ds_read_b128 v[172:175], v237 offset:56320
	s_add_u32 s48, s60, 0x4000
	s_addc_u32 s49, s61, 0
	s_mov_b32 m0, s41
	s_nop 0
	global_load_lds_dwordx4 v188, s[48:49]
	s_add_u32 s48, s60, 0x6000
	s_addc_u32 s49, s61, 0
	s_mov_b32 m0, s42
	s_nop 0
	global_load_lds_dwordx4 v188, s[48:49]
	s_barrier
	s_waitcnt lgkmcnt(7)
	v_mfma_f32_16x16x32_bf16 v[60:63], v[120:123], v[136:139], v[60:63]
	v_mfma_f32_16x16x32_bf16 v[56:59], v[128:131], v[136:139], v[56:59]
	s_waitcnt lgkmcnt(5)
	v_mfma_f32_16x16x32_bf16 v[44:47], v[120:123], v[152:155], v[44:47]
	v_mfma_f32_16x16x32_bf16 v[40:43], v[128:131], v[152:155], v[40:43]
	s_waitcnt lgkmcnt(3)
	v_mfma_f32_16x16x32_bf16 v[28:31], v[120:123], v[160:163], v[28:31]
	v_mfma_f32_16x16x32_bf16 v[24:27], v[128:131], v[160:163], v[24:27]
	s_waitcnt lgkmcnt(1)
	v_mfma_f32_16x16x32_bf16 v[12:15], v[120:123], v[168:171], v[12:15]
	v_mfma_f32_16x16x32_bf16 v[8:11], v[128:131], v[168:171], v[8:11]
	v_mfma_f32_16x16x32_bf16 v[60:63], v[124:127], v[140:143], v[60:63]
	v_mfma_f32_16x16x32_bf16 v[56:59], v[132:135], v[140:143], v[56:59]
	v_mfma_f32_16x16x32_bf16 v[44:47], v[124:127], v[156:159], v[44:47]
	v_mfma_f32_16x16x32_bf16 v[40:43], v[132:135], v[156:159], v[40:43]
	v_mfma_f32_16x16x32_bf16 v[28:31], v[124:127], v[164:167], v[28:31]
	v_mfma_f32_16x16x32_bf16 v[24:27], v[132:135], v[164:167], v[24:27]
	s_waitcnt lgkmcnt(0)
	v_mfma_f32_16x16x32_bf16 v[12:15], v[124:127], v[172:175], v[12:15]
	v_mfma_f32_16x16x32_bf16 v[8:11], v[132:135], v[172:175], v[8:11]
	s_barrier
	s_add_u32 s48, s64, 0x84000
	s_addc_u32 s49, s65, 0
	s_mov_b32 m0, s43
	s_nop 0
	global_load_lds_dwordx4 v188, s[48:49]
	s_add_u32 s48, s64, 0x86000
	s_addc_u32 s49, s65, 0
	s_mov_b32 m0, s66
	s_nop 0
	global_load_lds_dwordx4 v188, s[48:49]
	s_waitcnt vmcnt(10)
	s_barrier
	v_mfma_f32_16x16x32_bf16 v[52:55], v[176:179], v[136:139], v[52:55]
	v_mfma_f32_16x16x32_bf16 v[48:51], v[184:187], v[136:139], v[48:51]
	v_mfma_f32_16x16x32_bf16 v[36:39], v[176:179], v[152:155], v[36:39]
	v_mfma_f32_16x16x32_bf16 v[32:35], v[184:187], v[152:155], v[32:35]
	v_mfma_f32_16x16x32_bf16 v[20:23], v[176:179], v[160:163], v[20:23]
	v_mfma_f32_16x16x32_bf16 v[16:19], v[184:187], v[160:163], v[16:19]
	v_mfma_f32_16x16x32_bf16 v[4:7], v[176:179], v[168:171], v[4:7]
	v_mfma_f32_16x16x32_bf16 v[0:3], v[184:187], v[168:171], v[0:3]
	v_mfma_f32_16x16x32_bf16 v[52:55], v[180:183], v[140:143], v[52:55]
	v_mfma_f32_16x16x32_bf16 v[48:51], v[200:203], v[140:143], v[48:51]
	v_mfma_f32_16x16x32_bf16 v[36:39], v[180:183], v[156:159], v[36:39]
	v_mfma_f32_16x16x32_bf16 v[32:35], v[200:203], v[156:159], v[32:35]
	v_mfma_f32_16x16x32_bf16 v[20:23], v[180:183], v[164:167], v[20:23]
	v_mfma_f32_16x16x32_bf16 v[16:19], v[200:203], v[164:167], v[16:19]
	v_mfma_f32_16x16x32_bf16 v[4:7], v[180:183], v[172:175], v[4:7]
	v_mfma_f32_16x16x32_bf16 v[0:3], v[200:203], v[172:175], v[0:3]
	s_add_i32 s71, s71, 2
	s_add_u32 s69, s69, 0x8000
	s_addc_u32 s70, s70, 0
	s_cmp_gt_u32 s71, 29
	s_mov_b64 s[60:61], s[62:63]
	s_barrier
	s_cbranch_scc0 .LBB0_610
	v_readfirstlane_b32 s48, v235
	s_nop 1
	s_cmpk_lt_u32 s48, 0x100
	s_cbranch_scc0 .Lsout_al_skip
	s_barrier
;     __device__ __forceinline__ void operator()(f32x4 (&acc)[2][2][4][2], const Unit& u, int wr, int wc, int fr, int fq, LAS unsigned char*) const {
;         const int b = u.pm >> 6;
;         const int col0 = u.pn * BM + wc * 32 + 8 * fq;
;         const size_t off0 = (size_t)(u.pm * BM + wr * 64 + fr) * D + col0;
;         f32x4 sc[2][2];
; #pragma unroll
;         for (int bj = 0; bj < 2; ++bj)
; #pragma unroll
;             for (int n = 0; n < 2; ++n) { f32x4 gt = *(const f32x4*)(gate + (size_t)b * MODW + col0 + bj * HALF + n * 4); sc[bj][n] = gt + 1.0f;
;                 if (cs) sc[bj][n] *= *(const f32x4*)(cs + col0 + bj * HALF + n * 4); }
;         if (IN_F32) {
; #pragma unroll
;             for (int ai = 0; ai < 2; ++ai) {
;                 f32x4 r[4][2][2];
; #pragma unroll
;                 for (int m = 0; m < 4; ++m)
; #pragma unroll
;                     for (int bj = 0; bj < 2; ++bj)
; #pragma unroll
;                         for (int n = 0; n < 2; ++n) r[m][bj][n] = *(const f32x4*)((const float*)in + off0 + (size_t)(ai * HALF + m * 16) * D + bj * HALF + n * 4);
; #pragma unroll
;                 for (int m = 0; m < 4; ++m)
; #pragma unroll
;                     for (int bj = 0; bj < 2; ++bj) { const f32x4 r0 = r[m][bj][0] + sc[bj][0] * acc[ai][bj][m][0], r1 = r[m][bj][1] + sc[bj][1] * acc[ai][bj][m][1];
;                         u32x4 w; w.x = cvt_pk_bf16(r0[0], r0[1]); w.y = cvt_pk_bf16(r0[2], r0[3]); w.z = cvt_pk_bf16(r1[0], r1[1]); w.w = cvt_pk_bf16(r1[2], r1[3]);
;                         *(u32x4*)(out + off0 + (size_t)(ai * HALF + m * 16) * D + bj * HALF) = w; }
;                 asm volatile("" ::: "memory");
;             }
;         } else {
;             u32x4 xb[2][4][2];
; #pragma unroll
;             for (int ai = 0; ai < 2; ++ai)
; #pragma unroll
;                 for (int m = 0; m < 4; ++m)
; #pragma unroll
;                     for (int bj = 0; bj < 2; ++bj) xb[ai][m][bj] = *(const u32x4*)((const bf16_t*)in + off0 + (size_t)(ai * HALF + m * 16) * D + bj * HALF);
; #pragma unroll
;             for (int ai = 0; ai < 2; ++ai)
; #pragma unroll
;                 for (int m = 0; m < 4; ++m)
; #pragma unroll
;                     for (int bj = 0; bj < 2; ++bj) { const u32x4 x = xb[ai][m][bj];
.Lsout_al_skip:
	s_ashr_i32 s0, s50, 6
	s_mul_hi_i32 s1, s0, 0xc000
	s_mul_i32 s0, s0, 0xc000
	v_lshl_or_b32 v128, s51, 8, v234
	s_add_u32 s0, s37, s0
	v_ashrrev_i32_e32 v129, 31, v128
	s_addc_u32 s1, s38, s1
	v_lshl_add_u64 v[130:131], v[128:129], 2, s[0:1]
	global_load_dwordx4 v[120:123], v[130:131], off offset:16
	global_load_dwordx4 v[124:127], v[130:131], off
	s_mov_b32 s51, s52
	s_mov_b64 s[62:63], s[58:59]
	s_mov_b64 s[60:61], s[56:57]
	s_waitcnt vmcnt(1)
	v_pk_add_f32 v[210:211], v[122:123], 1.0 op_sel_hi:[1,0]
	s_waitcnt vmcnt(0)
	v_pk_add_f32 v[214:215], v[126:127], 1.0 op_sel_hi:[1,0]
	v_pk_add_f32 v[212:213], v[124:125], 1.0 op_sel_hi:[1,0]
	v_pk_add_f32 v[208:209], v[120:121], 1.0 op_sel_hi:[1,0]
	global_load_dwordx4 v[120:123], v[130:131], off offset:528
	global_load_dwordx4 v[124:127], v[130:131], off offset:512
	s_waitcnt vmcnt(1)
	v_pk_add_f32 v[200:201], v[120:121], 1.0 op_sel_hi:[1,0]
	v_lshl_add_u32 v120, s50, 8, v233
	v_ashrrev_i32_e32 v121, 31, v120
	v_lshlrev_b64 v[120:121], 11, v[120:121]
	v_lshl_add_u64 v[120:121], v[120:121], 0, v[128:129]
	v_lshlrev_b64 v[216:217], 1, v[120:121]
	v_lshl_add_u64 v[120:121], s[8:9], 0, v[216:217]
	global_load_dwordx4 v[238:241], v[120:121], off
	global_load_dwordx4 v[184:187], v[120:121], off offset:256
	v_pk_add_f32 v[202:203], v[122:123], 1.0 op_sel_hi:[1,0]
	v_add_co_u32_e32 v122, vcc, s45, v120
	s_waitcnt vmcnt(2)
	v_pk_add_f32 v[206:207], v[126:127], 1.0 op_sel_hi:[1,0]
	v_addc_co_u32_e32 v123, vcc, 0, v121, vcc
	global_load_dwordx4 v[180:183], v[122:123], off
	global_load_dwordx4 v[176:179], v[122:123], off offset:256
	v_add_co_u32_e32 v122, vcc, s36, v120
	v_pk_add_f32 v[204:205], v[124:125], 1.0 op_sel_hi:[1,0]
	s_nop 0
	v_addc_co_u32_e32 v123, vcc, 0, v121, vcc
	global_load_dwordx4 v[172:175], v[122:123], off
	global_load_dwordx4 v[168:171], v[122:123], off offset:256
	v_add_co_u32_e32 v122, vcc, s23, v120
	s_mov_b32 s50, s54
	s_nop 0
	v_addc_co_u32_e32 v123, vcc, 0, v121, vcc
	global_load_dwordx4 v[164:167], v[122:123], off
	global_load_dwordx4 v[160:163], v[122:123], off offset:256
	v_add_co_u32_e32 v122, vcc, s93, v120
	s_waitcnt vmcnt(7)
	v_lshlrev_b32_e32 v230, 16, v238
	v_addc_co_u32_e32 v123, vcc, 0, v121, vcc
	global_load_dwordx4 v[156:159], v[122:123], off
	global_load_dwordx4 v[152:155], v[122:123], off offset:256
	v_add_co_u32_e32 v122, vcc, s33, v120
	v_and_b32_e32 v231, 0xffff0000, v238
	s_nop 0
	v_addc_co_u32_e32 v123, vcc, 0, v121, vcc
	global_load_dwordx4 v[140:143], v[122:123], off
	global_load_dwordx4 v[136:139], v[122:123], off offset:256
	v_add_co_u32_e32 v122, vcc, s18, v120
	v_lshlrev_b32_e32 v242, 16, v240
	s_nop 0
	v_addc_co_u32_e32 v123, vcc, 0, v121, vcc
	global_load_dwordx4 v[132:135], v[122:123], off
	global_load_dwordx4 v[128:131], v[122:123], off offset:256
	v_add_co_u32_e32 v120, vcc, s19, v120
	v_and_b32_e32 v243, 0xffff0000, v240
	s_nop 0
	v_addc_co_u32_e32 v121, vcc, 0, v121, vcc
	global_load_dwordx4 v[124:127], v[120:121], off
	s_nop 0
	global_load_dwordx4 v[120:123], v[120:121], off offset:256
	v_lshlrev_b32_e32 v238, 16, v239
	v_and_b32_e32 v239, 0xffff0000, v239
	v_lshlrev_b32_e32 v240, 16, v241
	v_and_b32_e32 v241, 0xffff0000, v241
	v_pk_fma_f32 v[148:149], v[148:149], v[212:213], v[230:231]
	v_pk_fma_f32 v[144:145], v[144:145], v[208:209], v[242:243]
	v_pk_fma_f32 v[150:151], v[150:151], v[214:215], v[238:239]
	v_pk_fma_f32 v[230:231], v[146:147], v[210:211], v[240:241]
	v_cvt_pk_bf16_f32 v146, v148, v149
	v_cvt_pk_bf16_f32 v147, v150, v151
	v_cvt_pk_bf16_f32 v148, v144, v145
	v_lshl_add_u64 v[144:145], s[10:11], 0, v[216:217]
	v_cvt_pk_bf16_f32 v149, v230, v231
	global_store_dwordx4 v[144:145], v[146:149], off
	s_waitcnt vmcnt(15)
	v_lshlrev_b32_e32 v150, 16, v186
	v_and_b32_e32 v151, 0xffff0000, v186
	v_lshlrev_b32_e32 v146, 16, v184
	v_and_b32_e32 v147, 0xffff0000, v184
	v_lshlrev_b32_e32 v148, 16, v185
	v_and_b32_e32 v149, 0xffff0000, v185
	v_lshlrev_b32_e32 v184, 16, v187
	v_and_b32_e32 v185, 0xffff0000, v187
	v_pk_fma_f32 v[118:119], v[118:119], v[206:207], v[148:149]
	v_pk_fma_f32 v[116:117], v[116:117], v[204:205], v[146:147]
	v_pk_fma_f32 v[146:147], v[114:115], v[202:203], v[184:185]
	v_pk_fma_f32 v[114:115], v[112:113], v[200:201], v[150:151]
	v_cvt_pk_bf16_f32 v112, v116, v117
	v_cvt_pk_bf16_f32 v113, v118, v119
	s_waitcnt vmcnt(14)
	v_lshlrev_b32_e32 v116, 16, v182
	v_cvt_pk_bf16_f32 v114, v114, v115
	v_cvt_pk_bf16_f32 v115, v146, v147
	global_store_dwordx4 v[144:145], v[112:115], off offset:256
	v_and_b32_e32 v117, 0xffff0000, v182
	v_lshlrev_b32_e32 v118, 16, v183
	v_lshlrev_b32_e32 v112, 16, v180
	v_and_b32_e32 v113, 0xffff0000, v180
	v_and_b32_e32 v119, 0xffff0000, v183
	v_pk_fma_f32 v[108:109], v[108:109], v[212:213], v[112:113]
	v_lshlrev_b32_e32 v114, 16, v181
	v_and_b32_e32 v115, 0xffff0000, v181
	v_pk_fma_f32 v[112:113], v[106:107], v[210:211], v[118:119]
	v_pk_fma_f32 v[106:107], v[104:105], v[208:209], v[116:117]
	v_cvt_pk_bf16_f32 v104, v108, v109
	v_add_co_u32_e32 v108, vcc, s45, v144
	v_pk_fma_f32 v[110:111], v[110:111], v[214:215], v[114:115]
	s_nop 0
	v_addc_co_u32_e32 v109, vcc, 0, v145, vcc
	v_cvt_pk_bf16_f32 v105, v110, v111
	v_cvt_pk_bf16_f32 v106, v106, v107
	v_cvt_pk_bf16_f32 v107, v112, v113
	global_store_dwordx4 v[108:109], v[104:107], off
	s_waitcnt vmcnt(15)
	v_lshlrev_b32_e32 v110, 16, v178
	v_and_b32_e32 v111, 0xffff0000, v178
	v_lshlrev_b32_e32 v104, 16, v176
	v_and_b32_e32 v105, 0xffff0000, v176
	v_lshlrev_b32_e32 v106, 16, v177
	v_and_b32_e32 v107, 0xffff0000, v177
	v_lshlrev_b32_e32 v112, 16, v179
	v_and_b32_e32 v113, 0xffff0000, v179
	v_pk_fma_f32 v[102:103], v[102:103], v[206:207], v[106:107]
	v_pk_fma_f32 v[100:101], v[100:101], v[204:205], v[104:105]
	v_pk_fma_f32 v[104:105], v[98:99], v[202:203], v[112:113]
	v_pk_fma_f32 v[98:99], v[96:97], v[200:201], v[110:111]
	v_cvt_pk_bf16_f32 v96, v100, v101
	v_cvt_pk_bf16_f32 v97, v102, v103
	s_waitcnt vmcnt(14)
; __device__ __forceinline__ unsigned cvt_pk_bf16(float lo, float hi) { unsigned r; asm volatile("v_cvt_pk_bf16_f32 %0, %1, %2" : "=v"(r) : "v"(lo), "v"(hi)); return r; }
;     __device__ __forceinline__ void operator()(f32x4 (&acc)[2][2][4][2], const Unit& u, int wr, int wc, int fr, int fq, LAS unsigned char*) const {
;     ...
;             for (int ai = 0; ai < 2; ++ai)
; #pragma unroll
;                 for (int m = 0; m < 4; ++m)
; #pragma unroll
;                     for (int bj = 0; bj < 2; ++bj) { const u32x4 x = xb[ai][m][bj];
;                         f32x4 r0 = (f32x4){__uint_as_float(x.x << 16), __uint_as_float(x.x & 0xffff0000u), __uint_as_float(x.y << 16), __uint_as_float(x.y & 0xffff0000u)};
;                         f32x4 r1 = (f32x4){__uint_as_float(x.z << 16), __uint_as_float(x.z & 0xffff0000u), __uint_as_float(x.w << 16), __uint_as_float(x.w & 0xffff0000u)};
;                         r0 += sc[bj][0] * acc[ai][bj][m][0]; r1 += sc[bj][1] * acc[ai][bj][m][1];
;                         u32x4 w; w.x = cvt_pk_bf16(r0[0], r0[1]); w.y = cvt_pk_bf16(r0[2], r0[3]); w.z = cvt_pk_bf16(r1[0], r1[1]); w.w = cvt_pk_bf16(r1[2], r1[3]);
;                         *(u32x4*)(out + off0 + (size_t)(ai * HALF + m * 16) * D + bj * HALF) = w; }
	v_lshlrev_b32_e32 v100, 16, v174
	v_cvt_pk_bf16_f32 v98, v98, v99
	v_cvt_pk_bf16_f32 v99, v104, v105
	global_store_dwordx4 v[108:109], v[96:99], off offset:256
	v_and_b32_e32 v101, 0xffff0000, v174
	v_lshlrev_b32_e32 v102, 16, v175
	v_lshlrev_b32_e32 v96, 16, v172
	v_and_b32_e32 v97, 0xffff0000, v172
	v_and_b32_e32 v103, 0xffff0000, v175
	v_pk_fma_f32 v[92:93], v[92:93], v[212:213], v[96:97]
	v_lshlrev_b32_e32 v98, 16, v173
	v_and_b32_e32 v99, 0xffff0000, v173
	v_pk_fma_f32 v[96:97], v[90:91], v[210:211], v[102:103]
	v_pk_fma_f32 v[90:91], v[88:89], v[208:209], v[100:101]
	v_cvt_pk_bf16_f32 v88, v92, v93
	v_add_co_u32_e32 v92, vcc, s36, v144
	v_pk_fma_f32 v[94:95], v[94:95], v[214:215], v[98:99]
	s_nop 0
	v_addc_co_u32_e32 v93, vcc, 0, v145, vcc
	v_cvt_pk_bf16_f32 v89, v94, v95
	v_cvt_pk_bf16_f32 v90, v90, v91
	v_cvt_pk_bf16_f32 v91, v96, v97
	global_store_dwordx4 v[92:93], v[88:91], off
	s_waitcnt vmcnt(15)
	v_lshlrev_b32_e32 v94, 16, v170
	v_and_b32_e32 v95, 0xffff0000, v170
	v_lshlrev_b32_e32 v88, 16, v168
	v_and_b32_e32 v89, 0xffff0000, v168
	v_lshlrev_b32_e32 v90, 16, v169
	v_and_b32_e32 v91, 0xffff0000, v169
	v_lshlrev_b32_e32 v96, 16, v171
	v_and_b32_e32 v97, 0xffff0000, v171
	v_pk_fma_f32 v[86:87], v[86:87], v[206:207], v[90:91]
	v_pk_fma_f32 v[84:85], v[84:85], v[204:205], v[88:89]
	v_pk_fma_f32 v[88:89], v[82:83], v[202:203], v[96:97]
	v_pk_fma_f32 v[82:83], v[80:81], v[200:201], v[94:95]
	v_cvt_pk_bf16_f32 v80, v84, v85
	v_cvt_pk_bf16_f32 v81, v86, v87
	s_waitcnt vmcnt(14)
	v_lshlrev_b32_e32 v84, 16, v166
	v_cvt_pk_bf16_f32 v82, v82, v83
	v_cvt_pk_bf16_f32 v83, v88, v89
	global_store_dwordx4 v[92:93], v[80:83], off offset:256
	v_and_b32_e32 v85, 0xffff0000, v166
	v_lshlrev_b32_e32 v86, 16, v167
	v_lshlrev_b32_e32 v80, 16, v164
	v_and_b32_e32 v81, 0xffff0000, v164
	v_and_b32_e32 v87, 0xffff0000, v167
	v_pk_fma_f32 v[76:77], v[76:77], v[212:213], v[80:81]
	v_lshlrev_b32_e32 v82, 16, v165
	v_and_b32_e32 v83, 0xffff0000, v165
	v_pk_fma_f32 v[80:81], v[74:75], v[210:211], v[86:87]
	v_pk_fma_f32 v[74:75], v[72:73], v[208:209], v[84:85]
	v_cvt_pk_bf16_f32 v72, v76, v77
	v_add_co_u32_e32 v76, vcc, s23, v144
	v_pk_fma_f32 v[78:79], v[78:79], v[214:215], v[82:83]
	s_nop 0
	v_addc_co_u32_e32 v77, vcc, 0, v145, vcc
	v_cvt_pk_bf16_f32 v73, v78, v79
	v_cvt_pk_bf16_f32 v74, v74, v75
	v_cvt_pk_bf16_f32 v75, v80, v81
	global_store_dwordx4 v[76:77], v[72:75], off
	s_waitcnt vmcnt(15)
	v_lshlrev_b32_e32 v78, 16, v162
	v_and_b32_e32 v79, 0xffff0000, v162
	v_lshlrev_b32_e32 v72, 16, v160
	v_and_b32_e32 v73, 0xffff0000, v160
	v_lshlrev_b32_e32 v74, 16, v161
	v_and_b32_e32 v75, 0xffff0000, v161
	v_lshlrev_b32_e32 v80, 16, v163
	v_and_b32_e32 v81, 0xffff0000, v163
	v_pk_fma_f32 v[70:71], v[70:71], v[206:207], v[74:75]
	v_pk_fma_f32 v[68:69], v[68:69], v[204:205], v[72:73]
	v_pk_fma_f32 v[72:73], v[66:67], v[202:203], v[80:81]
	v_pk_fma_f32 v[66:67], v[64:65], v[200:201], v[78:79]
	v_cvt_pk_bf16_f32 v64, v68, v69
	v_cvt_pk_bf16_f32 v65, v70, v71
	s_waitcnt vmcnt(14)
	v_lshlrev_b32_e32 v68, 16, v158
	v_cvt_pk_bf16_f32 v66, v66, v67
	v_cvt_pk_bf16_f32 v67, v72, v73
	global_store_dwordx4 v[76:77], v[64:67], off offset:256
	v_and_b32_e32 v69, 0xffff0000, v158
	v_lshlrev_b32_e32 v70, 16, v159
	v_lshlrev_b32_e32 v64, 16, v156
	v_and_b32_e32 v65, 0xffff0000, v156
	v_and_b32_e32 v71, 0xffff0000, v159
	v_pk_fma_f32 v[60:61], v[60:61], v[212:213], v[64:65]
	v_lshlrev_b32_e32 v66, 16, v157
	v_and_b32_e32 v67, 0xffff0000, v157
	v_pk_fma_f32 v[64:65], v[58:59], v[210:211], v[70:71]
	v_pk_fma_f32 v[58:59], v[56:57], v[208:209], v[68:69]
	v_cvt_pk_bf16_f32 v56, v60, v61
	v_add_co_u32_e32 v60, vcc, s93, v144
	v_pk_fma_f32 v[62:63], v[62:63], v[214:215], v[66:67]
	s_nop 0
	v_addc_co_u32_e32 v61, vcc, 0, v145, vcc
	v_cvt_pk_bf16_f32 v57, v62, v63
	v_cvt_pk_bf16_f32 v58, v58, v59
	v_cvt_pk_bf16_f32 v59, v64, v65
	global_store_dwordx4 v[60:61], v[56:59], off
	s_waitcnt vmcnt(15)
	v_lshlrev_b32_e32 v62, 16, v154
	v_and_b32_e32 v63, 0xffff0000, v154
	v_lshlrev_b32_e32 v56, 16, v152
	v_and_b32_e32 v57, 0xffff0000, v152
	v_lshlrev_b32_e32 v58, 16, v153
	v_and_b32_e32 v59, 0xffff0000, v153
	v_lshlrev_b32_e32 v64, 16, v155
	v_and_b32_e32 v65, 0xffff0000, v155
	v_pk_fma_f32 v[54:55], v[54:55], v[206:207], v[58:59]
	v_pk_fma_f32 v[52:53], v[52:53], v[204:205], v[56:57]
	v_pk_fma_f32 v[56:57], v[50:51], v[202:203], v[64:65]
	v_pk_fma_f32 v[50:51], v[48:49], v[200:201], v[62:63]
	v_cvt_pk_bf16_f32 v48, v52, v53
	v_cvt_pk_bf16_f32 v49, v54, v55
	s_waitcnt vmcnt(14)
; __device__ __forceinline__ unsigned cvt_pk_bf16(float lo, float hi) { unsigned r; asm volatile("v_cvt_pk_bf16_f32 %0, %1, %2" : "=v"(r) : "v"(lo), "v"(hi)); return r; }
; #define PG8_WAIT_V(n) asm volatile("s_waitcnt vmcnt(" #n ")" ::: "memory")
; #define PG8_BAR __builtin_amdgcn_s_barrier()
; template <class Epi>
; __device__ __forceinline__ void gemm_phase(LAS unsigned char* lds, const Gemm g, const StaticOrder& S, const Epi& E) {
;     ...
;     PG8_WAIT_V(0);
;     if (wr == 0) PG8_BAR;
;     PG8_BAR;
;     __device__ __forceinline__ void operator()(f32x4 (&acc)[2][2][4][2], const Unit& u, int wr, int wc, int fr, int fq, LAS unsigned char*) const {
;     ...
;             for (int ai = 0; ai < 2; ++ai)
; #pragma unroll
;                 for (int m = 0; m < 4; ++m)
; #pragma unroll
;                     for (int bj = 0; bj < 2; ++bj) { const u32x4 x = xb[ai][m][bj];
;                         f32x4 r0 = (f32x4){__uint_as_float(x.x << 16), __uint_as_float(x.x & 0xffff0000u), __uint_as_float(x.y << 16), __uint_as_float(x.y & 0xffff0000u)};
;                         f32x4 r1 = (f32x4){__uint_as_float(x.z << 16), __uint_as_float(x.z & 0xffff0000u), __uint_as_float(x.w << 16), __uint_as_float(x.w & 0xffff0000u)};
;                         r0 += sc[bj][0] * acc[ai][bj][m][0]; r1 += sc[bj][1] * acc[ai][bj][m][1];
;                         u32x4 w; w.x = cvt_pk_bf16(r0[0], r0[1]); w.y = cvt_pk_bf16(r0[2], r0[3]); w.z = cvt_pk_bf16(r1[0], r1[1]); w.w = cvt_pk_bf16(r1[2], r1[3]);
;                         *(u32x4*)(out + off0 + (size_t)(ai * HALF + m * 16) * D + bj * HALF) = w; }
	v_lshlrev_b32_e32 v52, 16, v142
	v_cvt_pk_bf16_f32 v50, v50, v51
	v_cvt_pk_bf16_f32 v51, v56, v57
	global_store_dwordx4 v[60:61], v[48:51], off offset:256
	v_and_b32_e32 v53, 0xffff0000, v142
	v_lshlrev_b32_e32 v54, 16, v143
	v_lshlrev_b32_e32 v48, 16, v140
	v_and_b32_e32 v49, 0xffff0000, v140
	v_and_b32_e32 v55, 0xffff0000, v143
	v_pk_fma_f32 v[44:45], v[44:45], v[212:213], v[48:49]
	v_lshlrev_b32_e32 v50, 16, v141
	v_and_b32_e32 v51, 0xffff0000, v141
	v_pk_fma_f32 v[48:49], v[42:43], v[210:211], v[54:55]
	v_pk_fma_f32 v[42:43], v[40:41], v[208:209], v[52:53]
	v_cvt_pk_bf16_f32 v40, v44, v45
	v_add_co_u32_e32 v44, vcc, s33, v144
	v_pk_fma_f32 v[46:47], v[46:47], v[214:215], v[50:51]
	s_nop 0
	v_addc_co_u32_e32 v45, vcc, 0, v145, vcc
	v_cvt_pk_bf16_f32 v41, v46, v47
	v_cvt_pk_bf16_f32 v42, v42, v43
	v_cvt_pk_bf16_f32 v43, v48, v49
	global_store_dwordx4 v[44:45], v[40:43], off
	s_waitcnt vmcnt(15)
	v_lshlrev_b32_e32 v46, 16, v138
	v_and_b32_e32 v47, 0xffff0000, v138
	v_lshlrev_b32_e32 v40, 16, v136
	v_and_b32_e32 v41, 0xffff0000, v136
	v_lshlrev_b32_e32 v42, 16, v137
	v_and_b32_e32 v43, 0xffff0000, v137
	v_lshlrev_b32_e32 v48, 16, v139
	v_and_b32_e32 v49, 0xffff0000, v139
	v_pk_fma_f32 v[38:39], v[38:39], v[206:207], v[42:43]
	v_pk_fma_f32 v[36:37], v[36:37], v[204:205], v[40:41]
	v_pk_fma_f32 v[40:41], v[34:35], v[202:203], v[48:49]
	v_pk_fma_f32 v[34:35], v[32:33], v[200:201], v[46:47]
	v_cvt_pk_bf16_f32 v32, v36, v37
	v_cvt_pk_bf16_f32 v33, v38, v39
	s_waitcnt vmcnt(14)
	v_lshlrev_b32_e32 v36, 16, v134
	v_cvt_pk_bf16_f32 v34, v34, v35
	v_cvt_pk_bf16_f32 v35, v40, v41
	global_store_dwordx4 v[44:45], v[32:35], off offset:256
	v_and_b32_e32 v37, 0xffff0000, v134
	v_lshlrev_b32_e32 v38, 16, v135
	v_lshlrev_b32_e32 v32, 16, v132
	v_and_b32_e32 v33, 0xffff0000, v132
	v_and_b32_e32 v39, 0xffff0000, v135
	v_pk_fma_f32 v[28:29], v[28:29], v[212:213], v[32:33]
	v_lshlrev_b32_e32 v34, 16, v133
	v_and_b32_e32 v35, 0xffff0000, v133
	v_pk_fma_f32 v[32:33], v[26:27], v[210:211], v[38:39]
	v_pk_fma_f32 v[26:27], v[24:25], v[208:209], v[36:37]
	v_cvt_pk_bf16_f32 v24, v28, v29
	v_add_co_u32_e32 v28, vcc, s18, v144
	v_pk_fma_f32 v[30:31], v[30:31], v[214:215], v[34:35]
	s_nop 0
	v_addc_co_u32_e32 v29, vcc, 0, v145, vcc
	v_cvt_pk_bf16_f32 v25, v30, v31
	v_cvt_pk_bf16_f32 v26, v26, v27
	v_cvt_pk_bf16_f32 v27, v32, v33
	global_store_dwordx4 v[28:29], v[24:27], off
	s_waitcnt vmcnt(15)
	v_lshlrev_b32_e32 v30, 16, v130
	v_and_b32_e32 v31, 0xffff0000, v130
	v_lshlrev_b32_e32 v24, 16, v128
	v_and_b32_e32 v25, 0xffff0000, v128
	v_lshlrev_b32_e32 v26, 16, v129
	v_and_b32_e32 v27, 0xffff0000, v129
	v_lshlrev_b32_e32 v32, 16, v131
	v_and_b32_e32 v33, 0xffff0000, v131
	v_pk_fma_f32 v[22:23], v[22:23], v[206:207], v[26:27]
	v_pk_fma_f32 v[20:21], v[20:21], v[204:205], v[24:25]
	v_pk_fma_f32 v[24:25], v[18:19], v[202:203], v[32:33]
	v_pk_fma_f32 v[18:19], v[16:17], v[200:201], v[30:31]
	v_cvt_pk_bf16_f32 v16, v20, v21
	v_cvt_pk_bf16_f32 v17, v22, v23
	s_waitcnt vmcnt(14)
	v_lshlrev_b32_e32 v20, 16, v126
	v_cvt_pk_bf16_f32 v18, v18, v19
	v_cvt_pk_bf16_f32 v19, v24, v25
	global_store_dwordx4 v[28:29], v[16:19], off offset:256
	v_and_b32_e32 v21, 0xffff0000, v126
	v_lshlrev_b32_e32 v22, 16, v127
	v_lshlrev_b32_e32 v16, 16, v124
	v_and_b32_e32 v17, 0xffff0000, v124
	v_and_b32_e32 v23, 0xffff0000, v127
	v_pk_fma_f32 v[12:13], v[12:13], v[212:213], v[16:17]
	v_lshlrev_b32_e32 v18, 16, v125
	v_and_b32_e32 v19, 0xffff0000, v125
	v_pk_fma_f32 v[16:17], v[10:11], v[210:211], v[22:23]
	v_pk_fma_f32 v[10:11], v[8:9], v[208:209], v[20:21]
	v_cvt_pk_bf16_f32 v8, v12, v13
	v_add_co_u32_e32 v12, vcc, s19, v144
	v_pk_fma_f32 v[14:15], v[14:15], v[214:215], v[18:19]
	s_nop 0
	v_addc_co_u32_e32 v13, vcc, 0, v145, vcc
	v_cvt_pk_bf16_f32 v9, v14, v15
	v_cvt_pk_bf16_f32 v10, v10, v11
	v_cvt_pk_bf16_f32 v11, v16, v17
	global_store_dwordx4 v[12:13], v[8:11], off
	s_waitcnt vmcnt(15)
	v_lshlrev_b32_e32 v14, 16, v122
	v_and_b32_e32 v15, 0xffff0000, v122
	v_lshlrev_b32_e32 v8, 16, v120
	v_and_b32_e32 v9, 0xffff0000, v120
	v_lshlrev_b32_e32 v16, 16, v123
	v_and_b32_e32 v17, 0xffff0000, v123
	v_lshlrev_b32_e32 v10, 16, v121
	v_and_b32_e32 v11, 0xffff0000, v121
	v_pk_fma_f32 v[4:5], v[4:5], v[204:205], v[8:9]
	v_pk_fma_f32 v[8:9], v[2:3], v[202:203], v[16:17]
	v_pk_fma_f32 v[2:3], v[0:1], v[200:201], v[14:15]
	s_and_b64 vcc, exec, s[4:5]
	v_pk_fma_f32 v[6:7], v[6:7], v[206:207], v[10:11]
	v_cvt_pk_bf16_f32 v0, v4, v5
	s_nop 0
	v_cvt_pk_bf16_f32 v1, v6, v7
	v_cvt_pk_bf16_f32 v2, v2, v3
	v_cvt_pk_bf16_f32 v3, v8, v9
	global_store_dwordx4 v[12:13], v[0:3], off offset:256
	s_cbranch_vccz .LBB0_603
	s_waitcnt vmcnt(0)
	s_cmpk_gt_u32 s16, 0xff
	v_readlane_b32 s38, v255, 44
	s_movk_i32 s30, 0x7ff
	s_cbranch_scc1 .LBB0_614

; #define PG8_STAGE(bufoff, gbase, hoff, imm) do { _Pragma("unroll") for (int _i = 0; _i < 2; ++_i) { \
;         asm volatile("s_mov_b32 m0, %0\n\ts_nop 0\n\tglobal_load_lds_dwordx4 %1, %2" \
;             :: "s"(lds0 + (unsigned)((bufoff) + _i * 8192)), "v"(voff0), "s"((const char*)(gbase) + (size_t)(hoff) + (size_t)(_i * 8192)) : "memory"); } } while (0)
; #define PG8_WAIT_V(n) asm volatile("s_waitcnt vmcnt(" #n ")" ::: "memory")
; #define PG8_BAR __builtin_amdgcn_s_barrier()
; template <class Epi>
; __device__ __forceinline__ void gemm_phase(LAS unsigned char* lds, const Gemm g, const StaticOrder& S, const Epi& E) {
;     int tid = threadIdx.x; asm volatile("" : "+v"(tid));
;     const int wid = __builtin_amdgcn_readfirstlane(tid >> 6), lane = tid & 63, wr = wid >> 2, wc = wid & 3, fr = lane & 15, fq = lane >> 4;
;     const int K = g.K, nt = K / BK;
;     const unsigned voff0 = (unsigned)(tid * 16);
;     const unsigned hA = (unsigned)(g.lda * 256), hB = (unsigned)(K * 256);
;     constexpr int KS = 16384;
;     const size_t tstepA = (size_t)BM * g.lda * 2, tstepB = (size_t)BM * K * 2;
;     const unsigned lds0 = (unsigned)__builtin_amdgcn_readfirstlane((int)((unsigned)(size_t)lds + (unsigned)wid * 1024u));
;     const int aoff = lds_byte(wr * 64 + fr, fq * 8), boff = lds_byte(wc * 32 + fr, fq * 8);
;     ...
;     Unit cur, nxt; int ui = 0;
;     if (!S.next(0, cur)) return;
;     f32x4 acc[2][2][4][2];
; #pragma unroll
;     for (int a = 0; a < 2; ++a)
; #pragma unroll
;         for (int b = 0; b < 2; ++b)
; #pragma unroll
;             for (int m = 0; m < 4; ++m)
; #pragma unroll
;                 for (int n = 0; n < 2; ++n) acc[a][b][m][n] = (f32x4){0.f, 0.f, 0.f, 0.f};
;     bf16x8 At[4][2], B0[2][2], B1[2][2];
;     const char* cA = (const char*)g.A + (size_t)cur.pm * tstepA + (size_t)(cur.pn >> g.gshift) * g.gstride; const char* cB = (const char*)g.Bt + (size_t)cur.pn * tstepB;
;     PG8_STAGE(PG8_SB(0, 0), cB, 0, 0); PG8_STAGE(PG8_SA(0, 0), cA, 0, 0); PG8_STAGE(PG8_SB(0, 1), cB, hB, 0); PG8_STAGE(PG8_SA(0, 1), cA, hA, 0);
;     if (wr == 1) PG8_BAR;
;     PG8_WAIT_V(4); PG8_BAR;
;     PG8_STAGE(PG8_SB(1, 0), cB + KS, 0, 0); PG8_STAGE(PG8_SA(1, 0), cA + KS, 0, 0); PG8_STAGE(PG8_SB(1, 1), cB + KS, hB, 0);
;     PG8_WAIT_V(6); PG8_BAR;
.LBB0_845:
	s_waitcnt vmcnt(0)
	v_mov_b32_e32 v0, v235
	v_readlane_b32 s0, v255, 6
	s_barrier
	v_readlane_b32 s1, v255, 7
	v_readfirstlane_b32 s21, v0
	s_andn2_b64 vcc, exec, s[0:1]
	s_ashr_i32 s0, s21, 6
	s_cbranch_vccnz .LBB0_865
	s_add_u32 s1, s8, s13
	s_addc_u32 s4, s9, 0
	s_add_u32 s22, s1, 0x7a00000
	s_addc_u32 s24, s4, 0
	s_lshl_b32 s4, s0, 10
	v_readlane_b32 s5, v255, 14
	s_ashr_i32 s1, s21, 8
	s_add_i32 s25, s4, 0
	s_mul_i32 s4, s5, 0x2c0000
	s_add_u32 s58, s22, s4
	s_mul_hi_i32 s4, s5, 0x2c0000
	s_addc_u32 s59, s24, s4
	s_add_i32 s26, s25, 0x10000
	s_add_i32 s27, s25, 0x12000
	s_add_u32 s4, s58, 0x2000
	v_lshlrev_b32_e32 v188, 4, v0
	s_mov_b32 m0, s26
	s_nop 0
	global_load_lds_dwordx4 v188, s[58:59]
	s_addc_u32 s5, s59, 0
	s_mov_b32 m0, s27
	s_nop 0
	global_load_lds_dwordx4 v188, s[4:5]
	v_readlane_b32 s4, v255, 15
	s_mov_b32 s6, s4
	s_mul_i32 s4, s4, 0x2c0000
	s_add_u32 s56, s10, s4
	s_mul_hi_i32 s4, s6, 0x2c0000
	s_addc_u32 s57, s11, s4
	s_add_i32 s28, s25, 0x2000
	v_readlane_b32 s5, v255, 16
	s_add_u32 s4, s56, 0x2000
	s_mov_b32 m0, s25
	s_nop 0
	global_load_lds_dwordx4 v188, s[56:57]
	s_addc_u32 s5, s57, 0
	s_add_i32 s29, s25, 0x14000
	s_mov_b32 m0, s28
	s_nop 0
	global_load_lds_dwordx4 v188, s[4:5]
	s_add_u32 s4, s58, 0x160000
	s_addc_u32 s5, s59, 0
	s_add_i32 s30, s25, 0x16000
	s_mov_b32 m0, s29
	s_nop 0
	global_load_lds_dwordx4 v188, s[4:5]
	s_add_u32 s4, s58, 0x162000
	s_addc_u32 s5, s59, 0
	s_add_i32 s34, s25, 0x4000
	s_mov_b32 m0, s30
	s_nop 0
	global_load_lds_dwordx4 v188, s[4:5]
	s_add_u32 s4, s56, 0x160000
	s_addc_u32 s5, s57, 0
	s_add_i32 s37, s25, 0x6000
	s_mov_b32 m0, s34
	s_nop 0
	global_load_lds_dwordx4 v188, s[4:5]
	s_add_u32 s4, s56, 0x162000
	s_addc_u32 s5, s57, 0
	s_mov_b32 m0, s37
	s_nop 0
	global_load_lds_dwordx4 v188, s[4:5]
	s_cmp_lg_u32 s1, 1
	s_cbranch_scc1 .LBB0_848
.LBB0_848:
	s_add_u32 s52, s8, 0x29c30000
	s_addc_u32 s53, s9, 0
	s_cmp_eq_u32 s17, 0
	s_cselect_b64 s[4:5], -1, 0
	s_and_b64 s[4:5], s[2:3], s[4:5]
	s_add_u32 s6, s8, 0x31c34000
	s_addc_u32 s7, s9, 0
	s_and_b64 s[4:5], s[4:5], exec
	s_cselect_b32 s55, s7, s53
	s_cselect_b32 s54, s6, s52
	s_add_u32 s4, s8, s16
	s_addc_u32 s5, s9, 0
	s_add_u32 s39, s4, 0xa60a000
	v_lshrrev_b32_e32 v2, 1, v0
	s_addc_u32 s40, s5, 0
	v_and_b32_e32 v2, 24, v2
	s_lshl_b32 s0, s0, 5
	v_and_b32_e32 v1, 15, v0
	v_lshlrev_b32_e32 v3, 1, v2
	v_lshlrev_b32_e32 v0, 2, v0
	s_and_b32 s4, s0, 0x60
	v_lshl_or_b32 v233, s1, 6, v1
	v_lshl_or_b32 v1, v1, 6, v3
	s_lshl_b32 s1, s1, 13
	v_and_b32_e32 v0, 32, v0
	s_lshl_b32 s0, s4, 7
	s_add_i32 s41, s25, 0x18000
	v_bitop3_b32 v3, v1, s1, v0 bitop3:0xde
	v_bitop3_b32 v0, v1, s0, v0 bitop3:0xde
	s_add_u32 s0, s58, 0x4000
	s_addc_u32 s1, s59, 0
	s_add_i32 s42, s25, 0x1a000
	s_waitcnt vmcnt(4)
	s_barrier
	s_mov_b32 m0, s41
	s_nop 0
	global_load_lds_dwordx4 v188, s[0:1]
	s_add_u32 s0, s58, 0x6000
	s_addc_u32 s1, s59, 0
	s_add_i32 s43, s25, 0x8000
	s_mov_b32 m0, s42
	s_nop 0
	global_load_lds_dwordx4 v188, s[0:1]
	s_add_u32 s0, s56, 0x4000
	s_addc_u32 s1, s57, 0
	s_add_i32 s62, s25, 0xa000
	s_mov_b32 m0, s43
	s_nop 0
	global_load_lds_dwordx4 v188, s[0:1]
	s_add_u32 s0, s56, 0x6000
	s_addc_u32 s1, s57, 0
	s_add_i32 s63, s25, 0x1c000
	s_mov_b32 m0, s62
	s_nop 0
	global_load_lds_dwordx4 v188, s[0:1]
	s_add_u32 s0, s58, 0x164000
	s_addc_u32 s1, s59, 0
	s_add_i32 s64, s25, 0x1e000
	s_mov_b32 m0, s63
	s_nop 0
	global_load_lds_dwordx4 v188, s[0:1]
	s_add_u32 s0, s58, 0x166000
	s_addc_u32 s1, s59, 0
	s_mov_b32 m0, s64
	s_nop 0
	global_load_lds_dwordx4 v188, s[0:1]
	s_waitcnt vmcnt(6)
	v_readlane_b32 s0, v255, 15
	s_mov_b32 s38, 0
	s_add_i32 s65, s25, 0xc000
	s_add_i32 s66, s25, 0xe000
	v_or_b32_e32 v234, s4, v2
	v_add_u32_e32 v236, 0x10000, v0
	v_add_u32_e32 v237, 0, v3
	v_readlane_b32 s51, v255, 14
	s_mov_b32 s50, s0
	s_barrier
	v_readlane_b32 s1, v255, 16

; #define PG8_STAGE(bufoff, gbase, hoff, imm) do { _Pragma("unroll") for (int _i = 0; _i < 2; ++_i) { \
;         asm volatile("s_mov_b32 m0, %0\n\ts_nop 0\n\tglobal_load_lds_dwordx4 %1, %2" \
;             :: "s"(lds0 + (unsigned)((bufoff) + _i * 8192)), "v"(voff0), "s"((const char*)(gbase) + (size_t)(hoff) + (size_t)(_i * 8192)) : "memory"); } } while (0)
; #define PG8_LDA(dst, b, h) do { _Pragma("unroll") for (int m = 0; m < 4; ++m) _Pragma("unroll") for (int k = 0; k < 2; ++k) dst[m][k] = *(const LAS bf16x8*)(lds + PG8_SA(b, h) + aoff + m * 2048 + k * 1024); } while (0)
; #define PG8_LDB(dst, b, h) do { _Pragma("unroll") for (int n = 0; n < 2; ++n) _Pragma("unroll") for (int k = 0; k < 2; ++k) dst[n][k] = *(const LAS bf16x8*)(lds + PG8_SB(b, h) + boff + n * 2048 + k * 1024); } while (0)
; #define PG8_MMA(ai, bj, At, Bt) do { __builtin_amdgcn_s_setprio(1); _Pragma("unroll") for (int m = 0; m < 4; ++m) _Pragma("unroll") for (int n = 0; n < 2; ++n) _Pragma("unroll") for (int k = 0; k < 2; ++k) \
;         acc[ai][bj][m][n] = __builtin_amdgcn_mfma_f32_16x16x32_bf16(Bt[n][k], At[m][k], acc[ai][bj][m][n], 0, 0, 0); __builtin_amdgcn_s_setprio(0); } while (0)
; #define PG8_WAIT_V(n) asm volatile("s_waitcnt vmcnt(" #n ")" ::: "memory")
; #define PG8_BAR __builtin_amdgcn_s_barrier()
; template <class Epi>
; __device__ __forceinline__ void gemm_phase(LAS unsigned char* lds, const Gemm g, const StaticOrder& S, const Epi& E) {
;     ...
;         for (int t = 0; t < nt; t += 2) {
;             const bool last = (t == nt - 2);
;             if (last) E.pre(cur, wid, lane, (unsigned)(size_t)(lds + STAGE_BYTES));
;             const char* aT = cA + (size_t)t * KS;
;             const char* a2 = last ? nA : aT + 2 * KS; const char* b2 = last ? nB : cB + (size_t)(t + 2) * KS;
;             PG8_LDB(B0, 0, 0); PG8_SCHED; PG8_LDA(At, 0, 0); PG8_STAGE(PG8_SA(1, 1), aT + KS, hA, 0);
;             PG8_WAIT_L(8); PG8_BAR; PG8_WAIT_L(0); PG8_MMA(0, 0, At, B0); PG8_BAR; PG8_SCHED;
;             PG8_LDB(B1, 0, 1); PG8_STAGE(PG8_SB(0, 0), b2, 0, 0);
;             PG8_BAR; PG8_WAIT_L(0); PG8_MMA(0, 1, At, B1); PG8_BAR;
;             PG8_LDA(At, 0, 1); PG8_STAGE(PG8_SA(0, 0), a2, 0, 0);
;             PG8_BAR; PG8_WAIT_L(0); PG8_MMA(1, 0, At, B0); PG8_BAR; PG8_SCHED;
;             PG8_STAGE(PG8_SB(0, 1), b2, hB, 0);
;             PG8_WAIT_V(6); PG8_BAR; PG8_MMA(1, 1, At, B1); PG8_BAR;
.LBB0_859:
	s_add_u32 s0, s58, 0x8000
	s_addc_u32 s1, s59, 0
	s_mov_b32 s69, -2
	s_waitcnt vmcnt(16)
	v_readfirstlane_b32 s48, v235
	s_nop 1
	s_cmpk_lt_u32 s48, 0x100
	s_cbranch_scc1 .Ldown_st_skip
	s_barrier
.Ldown_st_skip:
	s_add_u32 s58, s56, 0x8000
	s_addc_u32 s59, s57, 0
	ds_read_b128 v[120:123], v236
	ds_read_b128 v[124:127], v236 offset:1024
	ds_read_b128 v[128:131], v236 offset:2048
	ds_read_b128 v[132:135], v236 offset:3072
	s_add_u32 s48, s56, 0x164000
	s_addc_u32 s49, s57, 0
	s_add_u32 s60, s56, 0x166000
	s_addc_u32 s61, s57, 0
	s_cmpk_eq_i32 s69, 0x54
	s_cselect_b32 s57, s7, s59
	s_cselect_b32 s56, s6, s58
	ds_read_b128 v[136:139], v237
	ds_read_b128 v[140:143], v237 offset:1024
	ds_read_b128 v[152:155], v237 offset:2048
	ds_read_b128 v[156:159], v237 offset:3072
	ds_read_b128 v[160:163], v237 offset:4096
	ds_read_b128 v[164:167], v237 offset:5120
	ds_read_b128 v[168:171], v237 offset:6144
	ds_read_b128 v[172:175], v237 offset:7168
	s_mov_b32 m0, s65
	s_nop 0
	global_load_lds_dwordx4 v188, s[48:49]
	s_mov_b32 m0, s66
	s_nop 0
	global_load_lds_dwordx4 v188, s[60:61]
	s_waitcnt lgkmcnt(8)
	s_waitcnt vmcnt(10)
	s_barrier
	s_waitcnt lgkmcnt(7)
	v_mfma_f32_16x16x32_bf16 v[148:151], v[120:123], v[136:139], 0
	v_mfma_f32_16x16x32_bf16 v[144:147], v[128:131], v[136:139], 0
	s_waitcnt lgkmcnt(5)
	v_mfma_f32_16x16x32_bf16 v[108:111], v[120:123], v[152:155], 0
	v_mfma_f32_16x16x32_bf16 v[104:107], v[128:131], v[152:155], 0
	s_waitcnt lgkmcnt(3)
	v_mfma_f32_16x16x32_bf16 v[92:95], v[120:123], v[160:163], 0
	v_mfma_f32_16x16x32_bf16 v[88:91], v[128:131], v[160:163], 0
	s_waitcnt lgkmcnt(1)
	v_mfma_f32_16x16x32_bf16 v[76:79], v[120:123], v[168:171], 0
	v_mfma_f32_16x16x32_bf16 v[72:75], v[128:131], v[168:171], 0
	v_mfma_f32_16x16x32_bf16 v[148:151], v[124:127], v[140:143], v[148:151]
	v_mfma_f32_16x16x32_bf16 v[144:147], v[132:135], v[140:143], v[144:147]
	v_mfma_f32_16x16x32_bf16 v[108:111], v[124:127], v[156:159], v[108:111]
	v_mfma_f32_16x16x32_bf16 v[104:107], v[132:135], v[156:159], v[104:107]
	v_mfma_f32_16x16x32_bf16 v[92:95], v[124:127], v[164:167], v[92:95]
	v_mfma_f32_16x16x32_bf16 v[88:91], v[132:135], v[164:167], v[88:91]
	s_waitcnt lgkmcnt(0)
	v_mfma_f32_16x16x32_bf16 v[76:79], v[124:127], v[172:175], v[76:79]
	v_mfma_f32_16x16x32_bf16 v[72:75], v[132:135], v[172:175], v[72:75]
	s_barrier
	ds_read_b128 v[176:179], v236 offset:16384
	ds_read_b128 v[180:183], v236 offset:17408
	ds_read_b128 v[184:187], v236 offset:18432
	ds_read_b128 v[200:203], v236 offset:19456
	s_cselect_b32 s60, s8, s0
	s_cselect_b32 s61, s9, s1
	s_mov_b32 m0, s26
	s_nop 0
	global_load_lds_dwordx4 v188, s[60:61]
	s_add_u32 s48, s60, 0x2000
	s_addc_u32 s49, s61, 0
	s_mov_b32 m0, s27
	s_nop 0
	global_load_lds_dwordx4 v188, s[48:49]
	s_waitcnt vmcnt(10)
	s_barrier
	s_waitcnt lgkmcnt(3)
	v_mfma_f32_16x16x32_bf16 v[116:119], v[176:179], v[136:139], 0
	s_waitcnt lgkmcnt(1)
	v_mfma_f32_16x16x32_bf16 v[112:115], v[184:187], v[136:139], 0
	v_mfma_f32_16x16x32_bf16 v[100:103], v[176:179], v[152:155], 0
	v_mfma_f32_16x16x32_bf16 v[96:99], v[184:187], v[152:155], 0
	v_mfma_f32_16x16x32_bf16 v[84:87], v[176:179], v[160:163], 0
	v_mfma_f32_16x16x32_bf16 v[80:83], v[184:187], v[160:163], 0
	v_mfma_f32_16x16x32_bf16 v[68:71], v[176:179], v[168:171], 0
	v_mfma_f32_16x16x32_bf16 v[64:67], v[184:187], v[168:171], 0
	v_mfma_f32_16x16x32_bf16 v[116:119], v[180:183], v[140:143], v[116:119]
	s_waitcnt lgkmcnt(0)
	v_mfma_f32_16x16x32_bf16 v[112:115], v[200:203], v[140:143], v[112:115]
	v_mfma_f32_16x16x32_bf16 v[100:103], v[180:183], v[156:159], v[100:103]
	v_mfma_f32_16x16x32_bf16 v[96:99], v[200:203], v[156:159], v[96:99]
	v_mfma_f32_16x16x32_bf16 v[84:87], v[180:183], v[164:167], v[84:87]
	v_mfma_f32_16x16x32_bf16 v[80:83], v[200:203], v[164:167], v[80:83]
	v_mfma_f32_16x16x32_bf16 v[68:71], v[180:183], v[172:175], v[68:71]
	v_mfma_f32_16x16x32_bf16 v[64:67], v[200:203], v[172:175], v[64:67]
	s_barrier
	ds_read_b128 v[136:139], v237 offset:16384
	ds_read_b128 v[140:143], v237 offset:17408
	ds_read_b128 v[152:155], v237 offset:18432
	ds_read_b128 v[156:159], v237 offset:19456
	ds_read_b128 v[160:163], v237 offset:20480
	ds_read_b128 v[164:167], v237 offset:21504
	ds_read_b128 v[168:171], v237 offset:22528
	ds_read_b128 v[172:175], v237 offset:23552
	s_mov_b32 m0, s25
	s_nop 0
	global_load_lds_dwordx4 v188, s[56:57]
	s_add_u32 s48, s56, 0x2000
	s_addc_u32 s49, s57, 0
	s_mov_b32 m0, s28
	s_nop 0
	global_load_lds_dwordx4 v188, s[48:49]
	s_barrier
	s_waitcnt lgkmcnt(7)
	v_mfma_f32_16x16x32_bf16 v[60:63], v[120:123], v[136:139], 0
	v_mfma_f32_16x16x32_bf16 v[56:59], v[128:131], v[136:139], 0
	s_waitcnt lgkmcnt(5)
	v_mfma_f32_16x16x32_bf16 v[44:47], v[120:123], v[152:155], 0
	v_mfma_f32_16x16x32_bf16 v[40:43], v[128:131], v[152:155], 0
	s_waitcnt lgkmcnt(3)
	v_mfma_f32_16x16x32_bf16 v[28:31], v[120:123], v[160:163], 0
	v_mfma_f32_16x16x32_bf16 v[24:27], v[128:131], v[160:163], 0
	s_waitcnt lgkmcnt(1)
	v_mfma_f32_16x16x32_bf16 v[12:15], v[120:123], v[168:171], 0
	v_mfma_f32_16x16x32_bf16 v[8:11], v[128:131], v[168:171], 0
	v_mfma_f32_16x16x32_bf16 v[60:63], v[124:127], v[140:143], v[60:63]
	v_mfma_f32_16x16x32_bf16 v[56:59], v[132:135], v[140:143], v[56:59]
	v_mfma_f32_16x16x32_bf16 v[44:47], v[124:127], v[156:159], v[44:47]
	v_mfma_f32_16x16x32_bf16 v[40:43], v[132:135], v[156:159], v[40:43]
	v_mfma_f32_16x16x32_bf16 v[28:31], v[124:127], v[164:167], v[28:31]
	v_mfma_f32_16x16x32_bf16 v[24:27], v[132:135], v[164:167], v[24:27]
	s_waitcnt lgkmcnt(0)
	v_mfma_f32_16x16x32_bf16 v[12:15], v[124:127], v[172:175], v[12:15]
	v_mfma_f32_16x16x32_bf16 v[8:11], v[132:135], v[172:175], v[8:11]
	s_barrier
; #define PG8_STAGE(bufoff, gbase, hoff, imm) do { _Pragma("unroll") for (int _i = 0; _i < 2; ++_i) { \
;         asm volatile("s_mov_b32 m0, %0\n\ts_nop 0\n\tglobal_load_lds_dwordx4 %1, %2" \
;             :: "s"(lds0 + (unsigned)((bufoff) + _i * 8192)), "v"(voff0), "s"((const char*)(gbase) + (size_t)(hoff) + (size_t)(_i * 8192)) : "memory"); } } while (0)
; #define PG8_LDA(dst, b, h) do { _Pragma("unroll") for (int m = 0; m < 4; ++m) _Pragma("unroll") for (int k = 0; k < 2; ++k) dst[m][k] = *(const LAS bf16x8*)(lds + PG8_SA(b, h) + aoff + m * 2048 + k * 1024); } while (0)
; #define PG8_LDB(dst, b, h) do { _Pragma("unroll") for (int n = 0; n < 2; ++n) _Pragma("unroll") for (int k = 0; k < 2; ++k) dst[n][k] = *(const LAS bf16x8*)(lds + PG8_SB(b, h) + boff + n * 2048 + k * 1024); } while (0)
; #define PG8_MMA(ai, bj, At, Bt) do { __builtin_amdgcn_s_setprio(1); _Pragma("unroll") for (int m = 0; m < 4; ++m) _Pragma("unroll") for (int n = 0; n < 2; ++n) _Pragma("unroll") for (int k = 0; k < 2; ++k) \
;         acc[ai][bj][m][n] = __builtin_amdgcn_mfma_f32_16x16x32_bf16(Bt[n][k], At[m][k], acc[ai][bj][m][n], 0, 0, 0); __builtin_amdgcn_s_setprio(0); } while (0)
; #define PG8_WAIT_V(n) asm volatile("s_waitcnt vmcnt(" #n ")" ::: "memory")
; #define PG8_WAIT_L(n) asm volatile("s_waitcnt lgkmcnt(" #n ")" ::: "memory")
; template <class Epi>
; __device__ __forceinline__ void gemm_phase(LAS unsigned char* lds, const Gemm g, const StaticOrder& S, const Epi& E) {
;     ...
;             PG8_LDA(At, 0, 1); PG8_STAGE(PG8_SA(0, 0), a2, 0, 0);
;             PG8_BAR; PG8_WAIT_L(0); PG8_MMA(1, 0, At, B0); PG8_BAR; PG8_SCHED;
;             PG8_STAGE(PG8_SB(0, 1), b2, hB, 0);
;             PG8_WAIT_V(6); PG8_BAR; PG8_MMA(1, 1, At, B1); PG8_BAR;
;             PG8_LDB(B0, 1, 0); PG8_SCHED; PG8_LDA(At, 1, 0); PG8_STAGE(PG8_SA(0, 1), a2, hA, 0);
;             PG8_WAIT_L(8); PG8_BAR; PG8_WAIT_L(0); PG8_MMA(0, 0, At, B0); PG8_BAR; PG8_SCHED;
;             PG8_LDB(B1, 1, 1); PG8_STAGE(PG8_SB(1, 0), b2 + KS, 0, 0);
;             PG8_BAR; PG8_WAIT_L(0); PG8_MMA(0, 1, At, B1); PG8_BAR;
;             PG8_LDA(At, 1, 1); PG8_STAGE(PG8_SA(1, 0), a2 + KS, 0, 0);
;             PG8_BAR; PG8_WAIT_L(0); PG8_MMA(1, 0, At, B0); PG8_BAR; PG8_SCHED;
;             PG8_STAGE(PG8_SB(1, 1), b2 + KS, hB, 0);
;             PG8_WAIT_V(6); PG8_BAR; PG8_MMA(1, 1, At, B1); PG8_BAR;
	s_add_u32 s48, s60, 0x160000
	s_addc_u32 s49, s61, 0
	s_mov_b32 m0, s29
	s_nop 0
	global_load_lds_dwordx4 v188, s[48:49]
	s_add_u32 s48, s60, 0x162000
	s_addc_u32 s49, s61, 0
	s_mov_b32 m0, s30
	s_nop 0
	global_load_lds_dwordx4 v188, s[48:49]
	s_waitcnt vmcnt(10)
	s_barrier
	v_mfma_f32_16x16x32_bf16 v[52:55], v[176:179], v[136:139], 0
	v_mfma_f32_16x16x32_bf16 v[48:51], v[184:187], v[136:139], 0
	v_mfma_f32_16x16x32_bf16 v[36:39], v[176:179], v[152:155], 0
	v_mfma_f32_16x16x32_bf16 v[32:35], v[184:187], v[152:155], 0
	v_mfma_f32_16x16x32_bf16 v[20:23], v[176:179], v[160:163], 0
	v_mfma_f32_16x16x32_bf16 v[16:19], v[184:187], v[160:163], 0
	v_mfma_f32_16x16x32_bf16 v[4:7], v[176:179], v[168:171], 0
	v_mfma_f32_16x16x32_bf16 v[0:3], v[184:187], v[168:171], 0
	v_mfma_f32_16x16x32_bf16 v[52:55], v[180:183], v[140:143], v[52:55]
	v_mfma_f32_16x16x32_bf16 v[48:51], v[200:203], v[140:143], v[48:51]
	v_mfma_f32_16x16x32_bf16 v[36:39], v[180:183], v[156:159], v[36:39]
	v_mfma_f32_16x16x32_bf16 v[32:35], v[200:203], v[156:159], v[32:35]
	v_mfma_f32_16x16x32_bf16 v[20:23], v[180:183], v[164:167], v[20:23]
	v_mfma_f32_16x16x32_bf16 v[16:19], v[200:203], v[164:167], v[16:19]
	v_mfma_f32_16x16x32_bf16 v[4:7], v[180:183], v[172:175], v[4:7]
	v_mfma_f32_16x16x32_bf16 v[0:3], v[200:203], v[172:175], v[0:3]
	s_barrier
	ds_read_b128 v[120:123], v236 offset:32768
	ds_read_b128 v[124:127], v236 offset:33792
	ds_read_b128 v[128:131], v236 offset:34816
	ds_read_b128 v[132:135], v236 offset:35840
	ds_read_b128 v[136:139], v237 offset:32768
	ds_read_b128 v[140:143], v237 offset:33792
	ds_read_b128 v[152:155], v237 offset:34816
	ds_read_b128 v[156:159], v237 offset:35840
	ds_read_b128 v[160:163], v237 offset:36864
	ds_read_b128 v[164:167], v237 offset:37888
	ds_read_b128 v[168:171], v237 offset:38912
	ds_read_b128 v[172:175], v237 offset:39936
	s_add_u32 s48, s56, 0x160000
	s_addc_u32 s49, s57, 0
	s_mov_b32 m0, s34
	s_nop 0
	global_load_lds_dwordx4 v188, s[48:49]
	s_add_u32 s48, s56, 0x162000
	s_addc_u32 s49, s57, 0
	s_mov_b32 m0, s37
	s_nop 0
	global_load_lds_dwordx4 v188, s[48:49]
	s_waitcnt lgkmcnt(8)
	s_waitcnt vmcnt(10)
	s_barrier
	s_waitcnt lgkmcnt(7)
	v_mfma_f32_16x16x32_bf16 v[148:151], v[120:123], v[136:139], v[148:151]
	v_mfma_f32_16x16x32_bf16 v[144:147], v[128:131], v[136:139], v[144:147]
	s_waitcnt lgkmcnt(5)
	v_mfma_f32_16x16x32_bf16 v[108:111], v[120:123], v[152:155], v[108:111]
	v_mfma_f32_16x16x32_bf16 v[104:107], v[128:131], v[152:155], v[104:107]
	s_waitcnt lgkmcnt(3)
	v_mfma_f32_16x16x32_bf16 v[92:95], v[120:123], v[160:163], v[92:95]
	v_mfma_f32_16x16x32_bf16 v[88:91], v[128:131], v[160:163], v[88:91]
	s_waitcnt lgkmcnt(1)
	v_mfma_f32_16x16x32_bf16 v[76:79], v[120:123], v[168:171], v[76:79]
	v_mfma_f32_16x16x32_bf16 v[72:75], v[128:131], v[168:171], v[72:75]
	v_mfma_f32_16x16x32_bf16 v[148:151], v[124:127], v[140:143], v[148:151]
	v_mfma_f32_16x16x32_bf16 v[144:147], v[132:135], v[140:143], v[144:147]
	v_mfma_f32_16x16x32_bf16 v[108:111], v[124:127], v[156:159], v[108:111]
	v_mfma_f32_16x16x32_bf16 v[104:107], v[132:135], v[156:159], v[104:107]
	v_mfma_f32_16x16x32_bf16 v[92:95], v[124:127], v[164:167], v[92:95]
	v_mfma_f32_16x16x32_bf16 v[88:91], v[132:135], v[164:167], v[88:91]
	s_waitcnt lgkmcnt(0)
	v_mfma_f32_16x16x32_bf16 v[76:79], v[124:127], v[172:175], v[76:79]
	v_mfma_f32_16x16x32_bf16 v[72:75], v[132:135], v[172:175], v[72:75]
	s_barrier
	ds_read_b128 v[176:179], v236 offset:49152
	ds_read_b128 v[180:183], v236 offset:50176
	ds_read_b128 v[184:187], v236 offset:51200
	ds_read_b128 v[200:203], v236 offset:52224
	s_add_u32 s48, s60, 0x4000
	s_addc_u32 s49, s61, 0
	s_mov_b32 m0, s41
	s_nop 0
	global_load_lds_dwordx4 v188, s[48:49]
	s_add_u32 s48, s60, 0x6000
	s_addc_u32 s49, s61, 0
	s_mov_b32 m0, s42
	s_nop 0
	global_load_lds_dwordx4 v188, s[48:49]
	s_waitcnt vmcnt(10)
	s_barrier
	s_waitcnt lgkmcnt(3)
	v_mfma_f32_16x16x32_bf16 v[116:119], v[176:179], v[136:139], v[116:119]
	s_waitcnt lgkmcnt(1)
	v_mfma_f32_16x16x32_bf16 v[112:115], v[184:187], v[136:139], v[112:115]
	v_mfma_f32_16x16x32_bf16 v[100:103], v[176:179], v[152:155], v[100:103]
	v_mfma_f32_16x16x32_bf16 v[96:99], v[184:187], v[152:155], v[96:99]
	v_mfma_f32_16x16x32_bf16 v[84:87], v[176:179], v[160:163], v[84:87]
	v_mfma_f32_16x16x32_bf16 v[80:83], v[184:187], v[160:163], v[80:83]
	v_mfma_f32_16x16x32_bf16 v[68:71], v[176:179], v[168:171], v[68:71]
	v_mfma_f32_16x16x32_bf16 v[64:67], v[184:187], v[168:171], v[64:67]
	v_mfma_f32_16x16x32_bf16 v[116:119], v[180:183], v[140:143], v[116:119]
	s_waitcnt lgkmcnt(0)
	v_mfma_f32_16x16x32_bf16 v[112:115], v[200:203], v[140:143], v[112:115]
	v_mfma_f32_16x16x32_bf16 v[100:103], v[180:183], v[156:159], v[100:103]
	v_mfma_f32_16x16x32_bf16 v[96:99], v[200:203], v[156:159], v[96:99]
	v_mfma_f32_16x16x32_bf16 v[84:87], v[180:183], v[164:167], v[84:87]
	v_mfma_f32_16x16x32_bf16 v[80:83], v[200:203], v[164:167], v[80:83]
	v_mfma_f32_16x16x32_bf16 v[68:71], v[180:183], v[172:175], v[68:71]
	v_mfma_f32_16x16x32_bf16 v[64:67], v[200:203], v[172:175], v[64:67]
	s_barrier
	ds_read_b128 v[136:139], v237 offset:49152
	ds_read_b128 v[140:143], v237 offset:50176
	ds_read_b128 v[152:155], v237 offset:51200
	ds_read_b128 v[156:159], v237 offset:52224
	ds_read_b128 v[160:163], v237 offset:53248
	ds_read_b128 v[164:167], v237 offset:54272
	ds_read_b128 v[168:171], v237 offset:55296
	ds_read_b128 v[172:175], v237 offset:56320
	s_add_u32 s48, s56, 0x4000
	s_addc_u32 s49, s57, 0
	s_mov_b32 m0, s43
	s_nop 0
	global_load_lds_dwordx4 v188, s[48:49]
	s_add_u32 s48, s56, 0x6000
	s_addc_u32 s49, s57, 0
	s_mov_b32 m0, s62
	s_nop 0
	global_load_lds_dwordx4 v188, s[48:49]
	s_barrier
; #define PG8_STAGE(bufoff, gbase, hoff, imm) do { _Pragma("unroll") for (int _i = 0; _i < 2; ++_i) { \
;         asm volatile("s_mov_b32 m0, %0\n\ts_nop 0\n\tglobal_load_lds_dwordx4 %1, %2" \
;             :: "s"(lds0 + (unsigned)((bufoff) + _i * 8192)), "v"(voff0), "s"((const char*)(gbase) + (size_t)(hoff) + (size_t)(_i * 8192)) : "memory"); } } while (0)
; #define PG8_LDA(dst, b, h) do { _Pragma("unroll") for (int m = 0; m < 4; ++m) _Pragma("unroll") for (int k = 0; k < 2; ++k) dst[m][k] = *(const LAS bf16x8*)(lds + PG8_SA(b, h) + aoff + m * 2048 + k * 1024); } while (0)
; #define PG8_LDB(dst, b, h) do { _Pragma("unroll") for (int n = 0; n < 2; ++n) _Pragma("unroll") for (int k = 0; k < 2; ++k) dst[n][k] = *(const LAS bf16x8*)(lds + PG8_SB(b, h) + boff + n * 2048 + k * 1024); } while (0)
; #define PG8_BAR __builtin_amdgcn_s_barrier()
; template <class Epi>
; __device__ __forceinline__ void gemm_phase(LAS unsigned char* lds, const Gemm g, const StaticOrder& S, const Epi& E) {
;     ...
;             const char* aT = cA + (size_t)t * KS;
;             const char* a2 = last ? nA : aT + 2 * KS; const char* b2 = last ? nB : cB + (size_t)(t + 2) * KS;
;             PG8_LDB(B0, 0, 0); PG8_SCHED; PG8_LDA(At, 0, 0); PG8_STAGE(PG8_SA(1, 1), aT + KS, hA, 0);
;             PG8_WAIT_L(8); PG8_BAR; PG8_WAIT_L(0); PG8_MMA(0, 0, At, B0); PG8_BAR; PG8_SCHED;
;             PG8_LDB(B1, 0, 1); PG8_STAGE(PG8_SB(0, 0), b2, 0, 0);
;             PG8_BAR; PG8_WAIT_L(0); PG8_MMA(0, 1, At, B1); PG8_BAR;
;             PG8_LDA(At, 0, 1); PG8_STAGE(PG8_SA(0, 0), a2, 0, 0);
;             PG8_BAR; PG8_WAIT_L(0); PG8_MMA(1, 0, At, B0); PG8_BAR; PG8_SCHED;
;             PG8_STAGE(PG8_SB(0, 1), b2, hB, 0);
;             PG8_WAIT_V(6); PG8_BAR; PG8_MMA(1, 1, At, B1); PG8_BAR;
;             PG8_LDB(B0, 1, 0); PG8_SCHED; PG8_LDA(At, 1, 0); PG8_STAGE(PG8_SA(0, 1), a2, hA, 0);
;             PG8_WAIT_L(8); PG8_BAR; PG8_WAIT_L(0); PG8_MMA(0, 0, At, B0); PG8_BAR; PG8_SCHED;
;             PG8_LDB(B1, 1, 1); PG8_STAGE(PG8_SB(1, 0), b2 + KS, 0, 0);
;             PG8_BAR; PG8_WAIT_L(0); PG8_MMA(0, 1, At, B1); PG8_BAR;
;             PG8_LDA(At, 1, 1); PG8_STAGE(PG8_SA(1, 0), a2 + KS, 0, 0);
;             PG8_BAR; PG8_WAIT_L(0); PG8_MMA(1, 0, At, B0); PG8_BAR; PG8_SCHED;
;             PG8_STAGE(PG8_SB(1, 1), b2 + KS, hB, 0);
;             PG8_WAIT_V(6); PG8_BAR; PG8_MMA(1, 1, At, B1); PG8_BAR;
	s_waitcnt lgkmcnt(7)
	v_mfma_f32_16x16x32_bf16 v[60:63], v[120:123], v[136:139], v[60:63]
	v_mfma_f32_16x16x32_bf16 v[56:59], v[128:131], v[136:139], v[56:59]
	s_waitcnt lgkmcnt(5)
	v_mfma_f32_16x16x32_bf16 v[44:47], v[120:123], v[152:155], v[44:47]
	v_mfma_f32_16x16x32_bf16 v[40:43], v[128:131], v[152:155], v[40:43]
	s_waitcnt lgkmcnt(3)
	v_mfma_f32_16x16x32_bf16 v[28:31], v[120:123], v[160:163], v[28:31]
	v_mfma_f32_16x16x32_bf16 v[24:27], v[128:131], v[160:163], v[24:27]
	s_waitcnt lgkmcnt(1)
	v_mfma_f32_16x16x32_bf16 v[12:15], v[120:123], v[168:171], v[12:15]
	v_mfma_f32_16x16x32_bf16 v[8:11], v[128:131], v[168:171], v[8:11]
	v_mfma_f32_16x16x32_bf16 v[60:63], v[124:127], v[140:143], v[60:63]
	v_mfma_f32_16x16x32_bf16 v[56:59], v[132:135], v[140:143], v[56:59]
	v_mfma_f32_16x16x32_bf16 v[44:47], v[124:127], v[156:159], v[44:47]
	v_mfma_f32_16x16x32_bf16 v[40:43], v[132:135], v[156:159], v[40:43]
	v_mfma_f32_16x16x32_bf16 v[28:31], v[124:127], v[164:167], v[28:31]
	v_mfma_f32_16x16x32_bf16 v[24:27], v[132:135], v[164:167], v[24:27]
	s_waitcnt lgkmcnt(0)
	v_mfma_f32_16x16x32_bf16 v[12:15], v[124:127], v[172:175], v[12:15]
	v_mfma_f32_16x16x32_bf16 v[8:11], v[132:135], v[172:175], v[8:11]
	s_barrier
	s_add_u32 s48, s60, 0x164000
	s_addc_u32 s49, s61, 0
	s_mov_b32 m0, s63
	s_nop 0
	global_load_lds_dwordx4 v188, s[48:49]
	s_add_u32 s48, s60, 0x166000
	s_addc_u32 s49, s61, 0
	s_mov_b32 m0, s64
	s_nop 0
	global_load_lds_dwordx4 v188, s[48:49]
	s_waitcnt vmcnt(10)
	s_barrier
	v_mfma_f32_16x16x32_bf16 v[52:55], v[176:179], v[136:139], v[52:55]
	v_mfma_f32_16x16x32_bf16 v[48:51], v[184:187], v[136:139], v[48:51]
	v_mfma_f32_16x16x32_bf16 v[36:39], v[176:179], v[152:155], v[36:39]
	v_mfma_f32_16x16x32_bf16 v[32:35], v[184:187], v[152:155], v[32:35]
	v_mfma_f32_16x16x32_bf16 v[20:23], v[176:179], v[160:163], v[20:23]
	v_mfma_f32_16x16x32_bf16 v[16:19], v[184:187], v[160:163], v[16:19]
	v_mfma_f32_16x16x32_bf16 v[4:7], v[176:179], v[168:171], v[4:7]
	v_mfma_f32_16x16x32_bf16 v[0:3], v[184:187], v[168:171], v[0:3]
	v_mfma_f32_16x16x32_bf16 v[52:55], v[180:183], v[140:143], v[52:55]
	v_mfma_f32_16x16x32_bf16 v[48:51], v[200:203], v[140:143], v[48:51]
	v_mfma_f32_16x16x32_bf16 v[36:39], v[180:183], v[156:159], v[36:39]
	v_mfma_f32_16x16x32_bf16 v[32:35], v[200:203], v[156:159], v[32:35]
	v_mfma_f32_16x16x32_bf16 v[20:23], v[180:183], v[164:167], v[20:23]
	v_mfma_f32_16x16x32_bf16 v[16:19], v[200:203], v[164:167], v[16:19]
	v_mfma_f32_16x16x32_bf16 v[4:7], v[180:183], v[172:175], v[4:7]
	v_mfma_f32_16x16x32_bf16 v[0:3], v[200:203], v[172:175], v[0:3]
	s_add_i32 s69, s69, 2
	s_add_u32 s0, s0, 0x8000
	s_addc_u32 s1, s1, 0
	s_cmpk_gt_u32 s69, 0x55
	s_mov_b64 s[56:57], s[58:59]
	s_barrier
.LBB0_860:
	s_add_u32 s58, s56, 0x8000
	s_addc_u32 s59, s57, 0
	ds_read_b128 v[120:123], v236
	ds_read_b128 v[124:127], v236 offset:1024
	ds_read_b128 v[128:131], v236 offset:2048
	ds_read_b128 v[132:135], v236 offset:3072
	s_add_u32 s48, s56, 0x164000
	s_addc_u32 s49, s57, 0
	s_add_u32 s60, s56, 0x166000
	s_addc_u32 s61, s57, 0
	s_cmpk_eq_i32 s69, 0x54
	s_cselect_b32 s57, s7, s59
	s_cselect_b32 s56, s6, s58
	ds_read_b128 v[136:139], v237
	ds_read_b128 v[140:143], v237 offset:1024
	ds_read_b128 v[152:155], v237 offset:2048
	ds_read_b128 v[156:159], v237 offset:3072
	ds_read_b128 v[160:163], v237 offset:4096
	ds_read_b128 v[164:167], v237 offset:5120
	ds_read_b128 v[168:171], v237 offset:6144
	ds_read_b128 v[172:175], v237 offset:7168
	s_mov_b32 m0, s65
	s_nop 0
	global_load_lds_dwordx4 v188, s[48:49]
	s_mov_b32 m0, s66
	s_nop 0
	global_load_lds_dwordx4 v188, s[60:61]
	s_waitcnt lgkmcnt(8)
	s_waitcnt vmcnt(10)
	s_barrier
	s_waitcnt lgkmcnt(7)
	v_mfma_f32_16x16x32_bf16 v[148:151], v[120:123], v[136:139], v[148:151]
	v_mfma_f32_16x16x32_bf16 v[144:147], v[128:131], v[136:139], v[144:147]
	s_waitcnt lgkmcnt(5)
	v_mfma_f32_16x16x32_bf16 v[108:111], v[120:123], v[152:155], v[108:111]
	v_mfma_f32_16x16x32_bf16 v[104:107], v[128:131], v[152:155], v[104:107]
	s_waitcnt lgkmcnt(3)
	v_mfma_f32_16x16x32_bf16 v[92:95], v[120:123], v[160:163], v[92:95]
	v_mfma_f32_16x16x32_bf16 v[88:91], v[128:131], v[160:163], v[88:91]
	s_waitcnt lgkmcnt(1)
	v_mfma_f32_16x16x32_bf16 v[76:79], v[120:123], v[168:171], v[76:79]
	v_mfma_f32_16x16x32_bf16 v[72:75], v[128:131], v[168:171], v[72:75]
	v_mfma_f32_16x16x32_bf16 v[148:151], v[124:127], v[140:143], v[148:151]
	v_mfma_f32_16x16x32_bf16 v[144:147], v[132:135], v[140:143], v[144:147]
	v_mfma_f32_16x16x32_bf16 v[108:111], v[124:127], v[156:159], v[108:111]
	v_mfma_f32_16x16x32_bf16 v[104:107], v[132:135], v[156:159], v[104:107]
	v_mfma_f32_16x16x32_bf16 v[92:95], v[124:127], v[164:167], v[92:95]
	v_mfma_f32_16x16x32_bf16 v[88:91], v[132:135], v[164:167], v[88:91]
	s_waitcnt lgkmcnt(0)
	v_mfma_f32_16x16x32_bf16 v[76:79], v[124:127], v[172:175], v[76:79]
	v_mfma_f32_16x16x32_bf16 v[72:75], v[132:135], v[172:175], v[72:75]
	s_barrier
	ds_read_b128 v[176:179], v236 offset:16384
	ds_read_b128 v[180:183], v236 offset:17408
	ds_read_b128 v[184:187], v236 offset:18432
	ds_read_b128 v[200:203], v236 offset:19456
	s_cselect_b32 s60, s8, s0
	s_cselect_b32 s61, s9, s1
	s_mov_b32 m0, s26
	s_nop 0
	global_load_lds_dwordx4 v188, s[60:61]
	s_add_u32 s48, s60, 0x2000
	s_addc_u32 s49, s61, 0
	s_mov_b32 m0, s27
	s_nop 0
	global_load_lds_dwordx4 v188, s[48:49]
	s_waitcnt vmcnt(10)
	s_barrier
; #define PG8_STAGE(bufoff, gbase, hoff, imm) do { _Pragma("unroll") for (int _i = 0; _i < 2; ++_i) { \
;         asm volatile("s_mov_b32 m0, %0\n\ts_nop 0\n\tglobal_load_lds_dwordx4 %1, %2" \
;             :: "s"(lds0 + (unsigned)((bufoff) + _i * 8192)), "v"(voff0), "s"((const char*)(gbase) + (size_t)(hoff) + (size_t)(_i * 8192)) : "memory"); } } while (0)
; #define PG8_LDA(dst, b, h) do { _Pragma("unroll") for (int m = 0; m < 4; ++m) _Pragma("unroll") for (int k = 0; k < 2; ++k) dst[m][k] = *(const LAS bf16x8*)(lds + PG8_SA(b, h) + aoff + m * 2048 + k * 1024); } while (0)
; #define PG8_LDB(dst, b, h) do { _Pragma("unroll") for (int n = 0; n < 2; ++n) _Pragma("unroll") for (int k = 0; k < 2; ++k) dst[n][k] = *(const LAS bf16x8*)(lds + PG8_SB(b, h) + boff + n * 2048 + k * 1024); } while (0)
; #define PG8_MMA(ai, bj, At, Bt) do { __builtin_amdgcn_s_setprio(1); _Pragma("unroll") for (int m = 0; m < 4; ++m) _Pragma("unroll") for (int n = 0; n < 2; ++n) _Pragma("unroll") for (int k = 0; k < 2; ++k) \
;         acc[ai][bj][m][n] = __builtin_amdgcn_mfma_f32_16x16x32_bf16(Bt[n][k], At[m][k], acc[ai][bj][m][n], 0, 0, 0); __builtin_amdgcn_s_setprio(0); } while (0)
; #define PG8_WAIT_V(n) asm volatile("s_waitcnt vmcnt(" #n ")" ::: "memory")
; #define PG8_WAIT_L(n) asm volatile("s_waitcnt lgkmcnt(" #n ")" ::: "memory")
; template <class Epi>
; __device__ __forceinline__ void gemm_phase(LAS unsigned char* lds, const Gemm g, const StaticOrder& S, const Epi& E) {
;     ...
;             PG8_LDA(At, 0, 1); PG8_STAGE(PG8_SA(0, 0), a2, 0, 0);
;             PG8_BAR; PG8_WAIT_L(0); PG8_MMA(1, 0, At, B0); PG8_BAR; PG8_SCHED;
;             PG8_STAGE(PG8_SB(0, 1), b2, hB, 0);
;             PG8_WAIT_V(6); PG8_BAR; PG8_MMA(1, 1, At, B1); PG8_BAR;
;             PG8_LDB(B0, 1, 0); PG8_SCHED; PG8_LDA(At, 1, 0); PG8_STAGE(PG8_SA(0, 1), a2, hA, 0);
;             PG8_WAIT_L(8); PG8_BAR; PG8_WAIT_L(0); PG8_MMA(0, 0, At, B0); PG8_BAR; PG8_SCHED;
;             PG8_LDB(B1, 1, 1); PG8_STAGE(PG8_SB(1, 0), b2 + KS, 0, 0);
;             PG8_BAR; PG8_WAIT_L(0); PG8_MMA(0, 1, At, B1); PG8_BAR;
;             PG8_LDA(At, 1, 1); PG8_STAGE(PG8_SA(1, 0), a2 + KS, 0, 0);
;             PG8_BAR; PG8_WAIT_L(0); PG8_MMA(1, 0, At, B0); PG8_BAR; PG8_SCHED;
;             PG8_STAGE(PG8_SB(1, 1), b2 + KS, hB, 0);
;             PG8_WAIT_V(6); PG8_BAR; PG8_MMA(1, 1, At, B1); PG8_BAR;
	s_waitcnt lgkmcnt(3)
	v_mfma_f32_16x16x32_bf16 v[116:119], v[176:179], v[136:139], v[116:119]
	s_waitcnt lgkmcnt(1)
	v_mfma_f32_16x16x32_bf16 v[112:115], v[184:187], v[136:139], v[112:115]
	v_mfma_f32_16x16x32_bf16 v[100:103], v[176:179], v[152:155], v[100:103]
	v_mfma_f32_16x16x32_bf16 v[96:99], v[184:187], v[152:155], v[96:99]
	v_mfma_f32_16x16x32_bf16 v[84:87], v[176:179], v[160:163], v[84:87]
	v_mfma_f32_16x16x32_bf16 v[80:83], v[184:187], v[160:163], v[80:83]
	v_mfma_f32_16x16x32_bf16 v[68:71], v[176:179], v[168:171], v[68:71]
	v_mfma_f32_16x16x32_bf16 v[64:67], v[184:187], v[168:171], v[64:67]
	v_mfma_f32_16x16x32_bf16 v[116:119], v[180:183], v[140:143], v[116:119]
	s_waitcnt lgkmcnt(0)
	v_mfma_f32_16x16x32_bf16 v[112:115], v[200:203], v[140:143], v[112:115]
	v_mfma_f32_16x16x32_bf16 v[100:103], v[180:183], v[156:159], v[100:103]
	v_mfma_f32_16x16x32_bf16 v[96:99], v[200:203], v[156:159], v[96:99]
	v_mfma_f32_16x16x32_bf16 v[84:87], v[180:183], v[164:167], v[84:87]
	v_mfma_f32_16x16x32_bf16 v[80:83], v[200:203], v[164:167], v[80:83]
	v_mfma_f32_16x16x32_bf16 v[68:71], v[180:183], v[172:175], v[68:71]
	v_mfma_f32_16x16x32_bf16 v[64:67], v[200:203], v[172:175], v[64:67]
	s_barrier
	ds_read_b128 v[136:139], v237 offset:16384
	ds_read_b128 v[140:143], v237 offset:17408
	ds_read_b128 v[152:155], v237 offset:18432
	ds_read_b128 v[156:159], v237 offset:19456
	ds_read_b128 v[160:163], v237 offset:20480
	ds_read_b128 v[164:167], v237 offset:21504
	ds_read_b128 v[168:171], v237 offset:22528
	ds_read_b128 v[172:175], v237 offset:23552
	s_mov_b32 m0, s25
	s_nop 0
	global_load_lds_dwordx4 v188, s[56:57]
	s_add_u32 s48, s56, 0x2000
	s_addc_u32 s49, s57, 0
	s_mov_b32 m0, s28
	s_nop 0
	global_load_lds_dwordx4 v188, s[48:49]
	s_barrier
	s_waitcnt lgkmcnt(7)
	v_mfma_f32_16x16x32_bf16 v[60:63], v[120:123], v[136:139], v[60:63]
	v_mfma_f32_16x16x32_bf16 v[56:59], v[128:131], v[136:139], v[56:59]
	s_waitcnt lgkmcnt(5)
	v_mfma_f32_16x16x32_bf16 v[44:47], v[120:123], v[152:155], v[44:47]
	v_mfma_f32_16x16x32_bf16 v[40:43], v[128:131], v[152:155], v[40:43]
	s_waitcnt lgkmcnt(3)
	v_mfma_f32_16x16x32_bf16 v[28:31], v[120:123], v[160:163], v[28:31]
	v_mfma_f32_16x16x32_bf16 v[24:27], v[128:131], v[160:163], v[24:27]
	s_waitcnt lgkmcnt(1)
	v_mfma_f32_16x16x32_bf16 v[12:15], v[120:123], v[168:171], v[12:15]
	v_mfma_f32_16x16x32_bf16 v[8:11], v[128:131], v[168:171], v[8:11]
	v_mfma_f32_16x16x32_bf16 v[60:63], v[124:127], v[140:143], v[60:63]
	v_mfma_f32_16x16x32_bf16 v[56:59], v[132:135], v[140:143], v[56:59]
	v_mfma_f32_16x16x32_bf16 v[44:47], v[124:127], v[156:159], v[44:47]
	v_mfma_f32_16x16x32_bf16 v[40:43], v[132:135], v[156:159], v[40:43]
	v_mfma_f32_16x16x32_bf16 v[28:31], v[124:127], v[164:167], v[28:31]
	v_mfma_f32_16x16x32_bf16 v[24:27], v[132:135], v[164:167], v[24:27]
	s_waitcnt lgkmcnt(0)
	v_mfma_f32_16x16x32_bf16 v[12:15], v[124:127], v[172:175], v[12:15]
	v_mfma_f32_16x16x32_bf16 v[8:11], v[132:135], v[172:175], v[8:11]
	s_barrier
	s_add_u32 s48, s60, 0x160000
	s_addc_u32 s49, s61, 0
	s_mov_b32 m0, s29
	s_nop 0
	global_load_lds_dwordx4 v188, s[48:49]
	s_add_u32 s48, s60, 0x162000
	s_addc_u32 s49, s61, 0
	s_mov_b32 m0, s30
	s_nop 0
	global_load_lds_dwordx4 v188, s[48:49]
	s_waitcnt vmcnt(10)
	s_barrier
	v_mfma_f32_16x16x32_bf16 v[52:55], v[176:179], v[136:139], v[52:55]
	v_mfma_f32_16x16x32_bf16 v[48:51], v[184:187], v[136:139], v[48:51]
	v_mfma_f32_16x16x32_bf16 v[36:39], v[176:179], v[152:155], v[36:39]
	v_mfma_f32_16x16x32_bf16 v[32:35], v[184:187], v[152:155], v[32:35]
	v_mfma_f32_16x16x32_bf16 v[20:23], v[176:179], v[160:163], v[20:23]
	v_mfma_f32_16x16x32_bf16 v[16:19], v[184:187], v[160:163], v[16:19]
	v_mfma_f32_16x16x32_bf16 v[4:7], v[176:179], v[168:171], v[4:7]
	v_mfma_f32_16x16x32_bf16 v[0:3], v[184:187], v[168:171], v[0:3]
	v_mfma_f32_16x16x32_bf16 v[52:55], v[180:183], v[140:143], v[52:55]
	v_mfma_f32_16x16x32_bf16 v[48:51], v[200:203], v[140:143], v[48:51]
	v_mfma_f32_16x16x32_bf16 v[36:39], v[180:183], v[156:159], v[36:39]
	v_mfma_f32_16x16x32_bf16 v[32:35], v[200:203], v[156:159], v[32:35]
	v_mfma_f32_16x16x32_bf16 v[20:23], v[180:183], v[164:167], v[20:23]
	v_mfma_f32_16x16x32_bf16 v[16:19], v[200:203], v[164:167], v[16:19]
	v_mfma_f32_16x16x32_bf16 v[4:7], v[180:183], v[172:175], v[4:7]
	v_mfma_f32_16x16x32_bf16 v[0:3], v[200:203], v[172:175], v[0:3]
	s_barrier
	ds_read_b128 v[120:123], v236 offset:32768
	ds_read_b128 v[124:127], v236 offset:33792
	ds_read_b128 v[128:131], v236 offset:34816
	ds_read_b128 v[132:135], v236 offset:35840
	ds_read_b128 v[136:139], v237 offset:32768
	ds_read_b128 v[140:143], v237 offset:33792
	ds_read_b128 v[152:155], v237 offset:34816
	ds_read_b128 v[156:159], v237 offset:35840
	ds_read_b128 v[160:163], v237 offset:36864
	ds_read_b128 v[164:167], v237 offset:37888
	ds_read_b128 v[168:171], v237 offset:38912
	ds_read_b128 v[172:175], v237 offset:39936
	s_add_u32 s48, s56, 0x160000
	s_addc_u32 s49, s57, 0
	s_mov_b32 m0, s34
	s_nop 0
	global_load_lds_dwordx4 v188, s[48:49]
	s_add_u32 s48, s56, 0x162000
	s_addc_u32 s49, s57, 0
	s_mov_b32 m0, s37
	s_nop 0
	global_load_lds_dwordx4 v188, s[48:49]
	s_waitcnt lgkmcnt(8)
	s_waitcnt vmcnt(10)
	s_barrier
; #define PG8_STAGE(bufoff, gbase, hoff, imm) do { _Pragma("unroll") for (int _i = 0; _i < 2; ++_i) { \
;         asm volatile("s_mov_b32 m0, %0\n\ts_nop 0\n\tglobal_load_lds_dwordx4 %1, %2" \
;             :: "s"(lds0 + (unsigned)((bufoff) + _i * 8192)), "v"(voff0), "s"((const char*)(gbase) + (size_t)(hoff) + (size_t)(_i * 8192)) : "memory"); } } while (0)
; #define PG8_LDA(dst, b, h) do { _Pragma("unroll") for (int m = 0; m < 4; ++m) _Pragma("unroll") for (int k = 0; k < 2; ++k) dst[m][k] = *(const LAS bf16x8*)(lds + PG8_SA(b, h) + aoff + m * 2048 + k * 1024); } while (0)
; #define PG8_LDB(dst, b, h) do { _Pragma("unroll") for (int n = 0; n < 2; ++n) _Pragma("unroll") for (int k = 0; k < 2; ++k) dst[n][k] = *(const LAS bf16x8*)(lds + PG8_SB(b, h) + boff + n * 2048 + k * 1024); } while (0)
; #define PG8_MMA(ai, bj, At, Bt) do { __builtin_amdgcn_s_setprio(1); _Pragma("unroll") for (int m = 0; m < 4; ++m) _Pragma("unroll") for (int n = 0; n < 2; ++n) _Pragma("unroll") for (int k = 0; k < 2; ++k) \
;         acc[ai][bj][m][n] = __builtin_amdgcn_mfma_f32_16x16x32_bf16(Bt[n][k], At[m][k], acc[ai][bj][m][n], 0, 0, 0); __builtin_amdgcn_s_setprio(0); } while (0)
; #define PG8_WAIT_V(n) asm volatile("s_waitcnt vmcnt(" #n ")" ::: "memory")
; #define PG8_WAIT_L(n) asm volatile("s_waitcnt lgkmcnt(" #n ")" ::: "memory")
; #define PG8_BAR __builtin_amdgcn_s_barrier()
; #define PG8_SCHED __builtin_amdgcn_sched_barrier(0)
; template <class Epi>
; __device__ __forceinline__ void gemm_phase(LAS unsigned char* lds, const Gemm g, const StaticOrder& S, const Epi& E) {
;     ...
;             PG8_WAIT_V(6); PG8_BAR; PG8_MMA(1, 1, At, B1); PG8_BAR;
;             PG8_LDB(B0, 1, 0); PG8_SCHED; PG8_LDA(At, 1, 0); PG8_STAGE(PG8_SA(0, 1), a2, hA, 0);
;             PG8_WAIT_L(8); PG8_BAR; PG8_WAIT_L(0); PG8_MMA(0, 0, At, B0); PG8_BAR; PG8_SCHED;
;             PG8_LDB(B1, 1, 1); PG8_STAGE(PG8_SB(1, 0), b2 + KS, 0, 0);
;             PG8_BAR; PG8_WAIT_L(0); PG8_MMA(0, 1, At, B1); PG8_BAR;
;             PG8_LDA(At, 1, 1); PG8_STAGE(PG8_SA(1, 0), a2 + KS, 0, 0);
;             PG8_BAR; PG8_WAIT_L(0); PG8_MMA(1, 0, At, B0); PG8_BAR; PG8_SCHED;
;             PG8_STAGE(PG8_SB(1, 1), b2 + KS, hB, 0);
;             PG8_WAIT_V(6); PG8_BAR; PG8_MMA(1, 1, At, B1); PG8_BAR;
;         }
	s_waitcnt lgkmcnt(7)
	v_mfma_f32_16x16x32_bf16 v[148:151], v[120:123], v[136:139], v[148:151]
	v_mfma_f32_16x16x32_bf16 v[144:147], v[128:131], v[136:139], v[144:147]
	s_waitcnt lgkmcnt(5)
	v_mfma_f32_16x16x32_bf16 v[108:111], v[120:123], v[152:155], v[108:111]
	v_mfma_f32_16x16x32_bf16 v[104:107], v[128:131], v[152:155], v[104:107]
	s_waitcnt lgkmcnt(3)
	v_mfma_f32_16x16x32_bf16 v[92:95], v[120:123], v[160:163], v[92:95]
	v_mfma_f32_16x16x32_bf16 v[88:91], v[128:131], v[160:163], v[88:91]
	s_waitcnt lgkmcnt(1)
	v_mfma_f32_16x16x32_bf16 v[76:79], v[120:123], v[168:171], v[76:79]
	v_mfma_f32_16x16x32_bf16 v[72:75], v[128:131], v[168:171], v[72:75]
	v_mfma_f32_16x16x32_bf16 v[148:151], v[124:127], v[140:143], v[148:151]
	v_mfma_f32_16x16x32_bf16 v[144:147], v[132:135], v[140:143], v[144:147]
	v_mfma_f32_16x16x32_bf16 v[108:111], v[124:127], v[156:159], v[108:111]
	v_mfma_f32_16x16x32_bf16 v[104:107], v[132:135], v[156:159], v[104:107]
	v_mfma_f32_16x16x32_bf16 v[92:95], v[124:127], v[164:167], v[92:95]
	v_mfma_f32_16x16x32_bf16 v[88:91], v[132:135], v[164:167], v[88:91]
	s_waitcnt lgkmcnt(0)
	v_mfma_f32_16x16x32_bf16 v[76:79], v[124:127], v[172:175], v[76:79]
	v_mfma_f32_16x16x32_bf16 v[72:75], v[132:135], v[172:175], v[72:75]
	s_barrier
	ds_read_b128 v[176:179], v236 offset:49152
	ds_read_b128 v[180:183], v236 offset:50176
	ds_read_b128 v[184:187], v236 offset:51200
	ds_read_b128 v[200:203], v236 offset:52224
	s_add_u32 s48, s60, 0x4000
	s_addc_u32 s49, s61, 0
	s_mov_b32 m0, s41
	s_nop 0
	global_load_lds_dwordx4 v188, s[48:49]
	s_add_u32 s48, s60, 0x6000
	s_addc_u32 s49, s61, 0
	s_mov_b32 m0, s42
	s_nop 0
	global_load_lds_dwordx4 v188, s[48:49]
	s_waitcnt vmcnt(10)
	s_barrier
	s_waitcnt lgkmcnt(3)
	v_mfma_f32_16x16x32_bf16 v[116:119], v[176:179], v[136:139], v[116:119]
	s_waitcnt lgkmcnt(1)
	v_mfma_f32_16x16x32_bf16 v[112:115], v[184:187], v[136:139], v[112:115]
	v_mfma_f32_16x16x32_bf16 v[100:103], v[176:179], v[152:155], v[100:103]
	v_mfma_f32_16x16x32_bf16 v[96:99], v[184:187], v[152:155], v[96:99]
	v_mfma_f32_16x16x32_bf16 v[84:87], v[176:179], v[160:163], v[84:87]
	v_mfma_f32_16x16x32_bf16 v[80:83], v[184:187], v[160:163], v[80:83]
	v_mfma_f32_16x16x32_bf16 v[68:71], v[176:179], v[168:171], v[68:71]
	v_mfma_f32_16x16x32_bf16 v[64:67], v[184:187], v[168:171], v[64:67]
	v_mfma_f32_16x16x32_bf16 v[116:119], v[180:183], v[140:143], v[116:119]
	s_waitcnt lgkmcnt(0)
	v_mfma_f32_16x16x32_bf16 v[112:115], v[200:203], v[140:143], v[112:115]
	v_mfma_f32_16x16x32_bf16 v[100:103], v[180:183], v[156:159], v[100:103]
	v_mfma_f32_16x16x32_bf16 v[96:99], v[200:203], v[156:159], v[96:99]
	v_mfma_f32_16x16x32_bf16 v[84:87], v[180:183], v[164:167], v[84:87]
	v_mfma_f32_16x16x32_bf16 v[80:83], v[200:203], v[164:167], v[80:83]
	v_mfma_f32_16x16x32_bf16 v[68:71], v[180:183], v[172:175], v[68:71]
	v_mfma_f32_16x16x32_bf16 v[64:67], v[200:203], v[172:175], v[64:67]
	s_barrier
	ds_read_b128 v[136:139], v237 offset:49152
	ds_read_b128 v[140:143], v237 offset:50176
	ds_read_b128 v[152:155], v237 offset:51200
	ds_read_b128 v[156:159], v237 offset:52224
	ds_read_b128 v[160:163], v237 offset:53248
	ds_read_b128 v[164:167], v237 offset:54272
	ds_read_b128 v[168:171], v237 offset:55296
	ds_read_b128 v[172:175], v237 offset:56320
	s_add_u32 s48, s56, 0x4000
	s_addc_u32 s49, s57, 0
	s_mov_b32 m0, s43
	s_nop 0
	global_load_lds_dwordx4 v188, s[48:49]
	s_add_u32 s48, s56, 0x6000
	s_addc_u32 s49, s57, 0
	s_mov_b32 m0, s62
	s_nop 0
	global_load_lds_dwordx4 v188, s[48:49]
	s_barrier
	s_waitcnt lgkmcnt(7)
	v_mfma_f32_16x16x32_bf16 v[60:63], v[120:123], v[136:139], v[60:63]
	v_mfma_f32_16x16x32_bf16 v[56:59], v[128:131], v[136:139], v[56:59]
	s_waitcnt lgkmcnt(5)
	v_mfma_f32_16x16x32_bf16 v[44:47], v[120:123], v[152:155], v[44:47]
	v_mfma_f32_16x16x32_bf16 v[40:43], v[128:131], v[152:155], v[40:43]
	s_waitcnt lgkmcnt(3)
	v_mfma_f32_16x16x32_bf16 v[28:31], v[120:123], v[160:163], v[28:31]
	v_mfma_f32_16x16x32_bf16 v[24:27], v[128:131], v[160:163], v[24:27]
	s_waitcnt lgkmcnt(1)
	v_mfma_f32_16x16x32_bf16 v[12:15], v[120:123], v[168:171], v[12:15]
	v_mfma_f32_16x16x32_bf16 v[8:11], v[128:131], v[168:171], v[8:11]
	v_mfma_f32_16x16x32_bf16 v[60:63], v[124:127], v[140:143], v[60:63]
	v_mfma_f32_16x16x32_bf16 v[56:59], v[132:135], v[140:143], v[56:59]
	v_mfma_f32_16x16x32_bf16 v[44:47], v[124:127], v[156:159], v[44:47]
	v_mfma_f32_16x16x32_bf16 v[40:43], v[132:135], v[156:159], v[40:43]
	v_mfma_f32_16x16x32_bf16 v[28:31], v[124:127], v[164:167], v[28:31]
	v_mfma_f32_16x16x32_bf16 v[24:27], v[132:135], v[164:167], v[24:27]
	s_waitcnt lgkmcnt(0)
	v_mfma_f32_16x16x32_bf16 v[12:15], v[124:127], v[172:175], v[12:15]
	v_mfma_f32_16x16x32_bf16 v[8:11], v[132:135], v[172:175], v[8:11]
	s_barrier
	s_add_u32 s48, s60, 0x164000
	s_addc_u32 s49, s61, 0
	s_mov_b32 m0, s63
	s_nop 0
	global_load_lds_dwordx4 v188, s[48:49]
	s_add_u32 s48, s60, 0x166000
	s_addc_u32 s49, s61, 0
	s_mov_b32 m0, s64
	s_nop 0
	global_load_lds_dwordx4 v188, s[48:49]
	s_waitcnt vmcnt(10)
	s_barrier
	v_mfma_f32_16x16x32_bf16 v[52:55], v[176:179], v[136:139], v[52:55]
	v_mfma_f32_16x16x32_bf16 v[48:51], v[184:187], v[136:139], v[48:51]
	v_mfma_f32_16x16x32_bf16 v[36:39], v[176:179], v[152:155], v[36:39]
	v_mfma_f32_16x16x32_bf16 v[32:35], v[184:187], v[152:155], v[32:35]
	v_mfma_f32_16x16x32_bf16 v[20:23], v[176:179], v[160:163], v[20:23]
	v_mfma_f32_16x16x32_bf16 v[16:19], v[184:187], v[160:163], v[16:19]
	v_mfma_f32_16x16x32_bf16 v[4:7], v[176:179], v[168:171], v[4:7]
	v_mfma_f32_16x16x32_bf16 v[0:3], v[184:187], v[168:171], v[0:3]
	v_mfma_f32_16x16x32_bf16 v[52:55], v[180:183], v[140:143], v[52:55]
	v_mfma_f32_16x16x32_bf16 v[48:51], v[200:203], v[140:143], v[48:51]
	v_mfma_f32_16x16x32_bf16 v[36:39], v[180:183], v[156:159], v[36:39]
	v_mfma_f32_16x16x32_bf16 v[32:35], v[200:203], v[156:159], v[32:35]
	v_mfma_f32_16x16x32_bf16 v[20:23], v[180:183], v[164:167], v[20:23]
	v_mfma_f32_16x16x32_bf16 v[16:19], v[200:203], v[164:167], v[16:19]
	v_mfma_f32_16x16x32_bf16 v[4:7], v[180:183], v[172:175], v[4:7]
	v_mfma_f32_16x16x32_bf16 v[0:3], v[200:203], v[172:175], v[0:3]
	s_add_i32 s69, s69, 2
	s_add_u32 s0, s0, 0x8000
	s_addc_u32 s1, s1, 0
	s_cmpk_gt_u32 s69, 0x55
	s_mov_b64 s[56:57], s[58:59]
	s_barrier
	s_cbranch_scc0 .LBB0_860
	v_readfirstlane_b32 s48, v235
	s_nop 1
	s_cmpk_lt_u32 s48, 0x100
	s_cbranch_scc0 .Ldown_al_skip
	s_barrier
;     __device__ __forceinline__ void operator()(f32x4 (&acc)[2][2][4][2], const Unit& u, int wr, int wc, int fr, int fq, LAS unsigned char*) const {
;         const int b = u.pm >> 6;
;         const int col0 = u.pn * BM + wc * 32 + 8 * fq;
;         const size_t off0 = (size_t)(u.pm * BM + wr * 64 + fr) * D + col0;
;         f32x4 sc[2][2];
; #pragma unroll
;         for (int bj = 0; bj < 2; ++bj)
; #pragma unroll
;             for (int n = 0; n < 2; ++n) { f32x4 gt = *(const f32x4*)(gate + (size_t)b * MODW + col0 + bj * HALF + n * 4); sc[bj][n] = gt + 1.0f;
;                 if (cs) sc[bj][n] *= *(const f32x4*)(cs + col0 + bj * HALF + n * 4); }
;         if (IN_F32) {
; #pragma unroll
;             for (int ai = 0; ai < 2; ++ai) {
;                 f32x4 r[4][2][2];
; #pragma unroll
;                 for (int m = 0; m < 4; ++m)
; #pragma unroll
;                     for (int bj = 0; bj < 2; ++bj)
; #pragma unroll
;                         for (int n = 0; n < 2; ++n) r[m][bj][n] = *(const f32x4*)((const float*)in + off0 + (size_t)(ai * HALF + m * 16) * D + bj * HALF + n * 4);
; #pragma unroll
;                 for (int m = 0; m < 4; ++m)
; #pragma unroll
;                     for (int bj = 0; bj < 2; ++bj) { const f32x4 r0 = r[m][bj][0] + sc[bj][0] * acc[ai][bj][m][0], r1 = r[m][bj][1] + sc[bj][1] * acc[ai][bj][m][1];
;                         u32x4 w; w.x = cvt_pk_bf16(r0[0], r0[1]); w.y = cvt_pk_bf16(r0[2], r0[3]); w.z = cvt_pk_bf16(r1[0], r1[1]); w.w = cvt_pk_bf16(r1[2], r1[3]);
;                         *(u32x4*)(out + off0 + (size_t)(ai * HALF + m * 16) * D + bj * HALF) = w; }
;                 asm volatile("" ::: "memory");
;             }
;         } else {
;             u32x4 xb[2][4][2];
; #pragma unroll
;             for (int ai = 0; ai < 2; ++ai)
; #pragma unroll
;                 for (int m = 0; m < 4; ++m)
; #pragma unroll
;                     for (int bj = 0; bj < 2; ++bj) xb[ai][m][bj] = *(const u32x4*)((const bf16_t*)in + off0 + (size_t)(ai * HALF + m * 16) * D + bj * HALF);
; #pragma unroll
;             for (int ai = 0; ai < 2; ++ai)
; #pragma unroll
;                 for (int m = 0; m < 4; ++m)
; #pragma unroll
;                     for (int bj = 0; bj < 2; ++bj) { const u32x4 x = xb[ai][m][bj];
.Ldown_al_skip:
	s_ashr_i32 s0, s50, 6
	s_mul_hi_i32 s1, s0, 0xc000
	s_mul_i32 s0, s0, 0xc000
	v_lshl_or_b32 v128, s51, 8, v234
	s_add_u32 s0, s39, s0
	v_ashrrev_i32_e32 v129, 31, v128
	s_addc_u32 s1, s40, s1
	v_lshl_add_u64 v[130:131], v[128:129], 2, s[0:1]
	global_load_dwordx4 v[120:123], v[130:131], off offset:16
	global_load_dwordx4 v[124:127], v[130:131], off
	s_mov_b32 s51, s67
	s_mov_b64 s[58:59], s[8:9]
	s_mov_b64 s[56:57], s[6:7]
	s_waitcnt vmcnt(1)
	v_pk_add_f32 v[210:211], v[122:123], 1.0 op_sel_hi:[1,0]
	s_waitcnt vmcnt(0)
	v_pk_add_f32 v[214:215], v[126:127], 1.0 op_sel_hi:[1,0]
	v_pk_add_f32 v[212:213], v[124:125], 1.0 op_sel_hi:[1,0]
	v_pk_add_f32 v[208:209], v[120:121], 1.0 op_sel_hi:[1,0]
	global_load_dwordx4 v[120:123], v[130:131], off offset:528
	global_load_dwordx4 v[124:127], v[130:131], off offset:512
	s_waitcnt vmcnt(1)
	v_pk_add_f32 v[200:201], v[120:121], 1.0 op_sel_hi:[1,0]
	v_lshl_add_u32 v120, s50, 8, v233
	v_ashrrev_i32_e32 v121, 31, v120
	v_lshlrev_b64 v[120:121], 11, v[120:121]
	v_lshl_add_u64 v[120:121], v[120:121], 0, v[128:129]
	v_lshlrev_b64 v[216:217], 1, v[120:121]
	v_lshl_add_u64 v[120:121], s[52:53], 0, v[216:217]
	global_load_dwordx4 v[238:241], v[120:121], off
	global_load_dwordx4 v[184:187], v[120:121], off offset:256
	v_pk_add_f32 v[202:203], v[122:123], 1.0 op_sel_hi:[1,0]
	v_add_co_u32_e32 v122, vcc, s45, v120
	s_waitcnt vmcnt(2)
	v_pk_add_f32 v[206:207], v[126:127], 1.0 op_sel_hi:[1,0]
	v_addc_co_u32_e32 v123, vcc, 0, v121, vcc
	global_load_dwordx4 v[180:183], v[122:123], off
	global_load_dwordx4 v[176:179], v[122:123], off offset:256
	v_add_co_u32_e32 v122, vcc, s36, v120
	v_pk_add_f32 v[204:205], v[124:125], 1.0 op_sel_hi:[1,0]
	s_nop 0
	v_addc_co_u32_e32 v123, vcc, 0, v121, vcc
	global_load_dwordx4 v[172:175], v[122:123], off
	global_load_dwordx4 v[168:171], v[122:123], off offset:256
	v_add_co_u32_e32 v122, vcc, s23, v120
	s_mov_b32 s50, s68
	s_nop 0
	v_addc_co_u32_e32 v123, vcc, 0, v121, vcc
	global_load_dwordx4 v[164:167], v[122:123], off
	global_load_dwordx4 v[160:163], v[122:123], off offset:256
	v_add_co_u32_e32 v122, vcc, s93, v120
	s_waitcnt vmcnt(7)
	v_lshlrev_b32_e32 v230, 16, v238
	v_addc_co_u32_e32 v123, vcc, 0, v121, vcc
	global_load_dwordx4 v[156:159], v[122:123], off
	global_load_dwordx4 v[152:155], v[122:123], off offset:256
	v_add_co_u32_e32 v122, vcc, s33, v120
	v_and_b32_e32 v231, 0xffff0000, v238
	s_nop 0
	v_addc_co_u32_e32 v123, vcc, 0, v121, vcc
	global_load_dwordx4 v[140:143], v[122:123], off
	global_load_dwordx4 v[136:139], v[122:123], off offset:256
	v_add_co_u32_e32 v122, vcc, s18, v120
	v_lshlrev_b32_e32 v242, 16, v240
	s_nop 0
	v_addc_co_u32_e32 v123, vcc, 0, v121, vcc
	global_load_dwordx4 v[132:135], v[122:123], off
	global_load_dwordx4 v[128:131], v[122:123], off offset:256
	v_add_co_u32_e32 v120, vcc, s19, v120
	v_and_b32_e32 v243, 0xffff0000, v240
	s_nop 0
	v_addc_co_u32_e32 v121, vcc, 0, v121, vcc
	global_load_dwordx4 v[124:127], v[120:121], off
	s_nop 0
	global_load_dwordx4 v[120:123], v[120:121], off offset:256
	v_lshlrev_b32_e32 v238, 16, v239
	v_and_b32_e32 v239, 0xffff0000, v239
	v_lshlrev_b32_e32 v240, 16, v241
	v_and_b32_e32 v241, 0xffff0000, v241
	v_pk_fma_f32 v[148:149], v[148:149], v[212:213], v[230:231]
	v_pk_fma_f32 v[144:145], v[144:145], v[208:209], v[242:243]
	v_pk_fma_f32 v[150:151], v[150:151], v[214:215], v[238:239]
	v_pk_fma_f32 v[230:231], v[146:147], v[210:211], v[240:241]
	v_cvt_pk_bf16_f32 v146, v148, v149
	v_cvt_pk_bf16_f32 v147, v150, v151
	v_cvt_pk_bf16_f32 v148, v144, v145
	v_lshl_add_u64 v[144:145], s[54:55], 0, v[216:217]
	v_cvt_pk_bf16_f32 v149, v230, v231
	global_store_dwordx4 v[144:145], v[146:149], off
	s_waitcnt vmcnt(15)
	v_lshlrev_b32_e32 v150, 16, v186
	v_and_b32_e32 v151, 0xffff0000, v186
	v_lshlrev_b32_e32 v146, 16, v184
	v_and_b32_e32 v147, 0xffff0000, v184
	v_lshlrev_b32_e32 v148, 16, v185
	v_and_b32_e32 v149, 0xffff0000, v185
	v_lshlrev_b32_e32 v184, 16, v187
	v_and_b32_e32 v185, 0xffff0000, v187
	v_pk_fma_f32 v[118:119], v[118:119], v[206:207], v[148:149]
	v_pk_fma_f32 v[116:117], v[116:117], v[204:205], v[146:147]
	v_pk_fma_f32 v[146:147], v[114:115], v[202:203], v[184:185]
	v_pk_fma_f32 v[114:115], v[112:113], v[200:201], v[150:151]
	v_cvt_pk_bf16_f32 v112, v116, v117
	v_cvt_pk_bf16_f32 v113, v118, v119
	s_waitcnt vmcnt(14)
	v_lshlrev_b32_e32 v116, 16, v182
	v_cvt_pk_bf16_f32 v114, v114, v115
	v_cvt_pk_bf16_f32 v115, v146, v147
	global_store_dwordx4 v[144:145], v[112:115], off offset:256
	v_and_b32_e32 v117, 0xffff0000, v182
	v_lshlrev_b32_e32 v118, 16, v183
	v_lshlrev_b32_e32 v112, 16, v180
	v_and_b32_e32 v113, 0xffff0000, v180
	v_and_b32_e32 v119, 0xffff0000, v183
	v_pk_fma_f32 v[108:109], v[108:109], v[212:213], v[112:113]
	v_lshlrev_b32_e32 v114, 16, v181
	v_and_b32_e32 v115, 0xffff0000, v181
	v_pk_fma_f32 v[112:113], v[106:107], v[210:211], v[118:119]
	v_pk_fma_f32 v[106:107], v[104:105], v[208:209], v[116:117]
	v_cvt_pk_bf16_f32 v104, v108, v109
	v_add_co_u32_e32 v108, vcc, s45, v144
	v_pk_fma_f32 v[110:111], v[110:111], v[214:215], v[114:115]
	s_nop 0
	v_addc_co_u32_e32 v109, vcc, 0, v145, vcc
	v_cvt_pk_bf16_f32 v105, v110, v111
	v_cvt_pk_bf16_f32 v106, v106, v107
	v_cvt_pk_bf16_f32 v107, v112, v113
	global_store_dwordx4 v[108:109], v[104:107], off
	s_waitcnt vmcnt(15)
	v_lshlrev_b32_e32 v110, 16, v178
	v_and_b32_e32 v111, 0xffff0000, v178
	v_lshlrev_b32_e32 v104, 16, v176
	v_and_b32_e32 v105, 0xffff0000, v176
	v_lshlrev_b32_e32 v106, 16, v177
	v_and_b32_e32 v107, 0xffff0000, v177
	v_lshlrev_b32_e32 v112, 16, v179
	v_and_b32_e32 v113, 0xffff0000, v179
	v_pk_fma_f32 v[102:103], v[102:103], v[206:207], v[106:107]
	v_pk_fma_f32 v[100:101], v[100:101], v[204:205], v[104:105]
	v_pk_fma_f32 v[104:105], v[98:99], v[202:203], v[112:113]
	v_pk_fma_f32 v[98:99], v[96:97], v[200:201], v[110:111]
	v_cvt_pk_bf16_f32 v96, v100, v101
	v_cvt_pk_bf16_f32 v97, v102, v103
	s_waitcnt vmcnt(14)
; __device__ __forceinline__ unsigned cvt_pk_bf16(float lo, float hi) { unsigned r; asm volatile("v_cvt_pk_bf16_f32 %0, %1, %2" : "=v"(r) : "v"(lo), "v"(hi)); return r; }
;     __device__ __forceinline__ void operator()(f32x4 (&acc)[2][2][4][2], const Unit& u, int wr, int wc, int fr, int fq, LAS unsigned char*) const {
;     ...
;             for (int ai = 0; ai < 2; ++ai)
; #pragma unroll
;                 for (int m = 0; m < 4; ++m)
; #pragma unroll
;                     for (int bj = 0; bj < 2; ++bj) { const u32x4 x = xb[ai][m][bj];
;                         f32x4 r0 = (f32x4){__uint_as_float(x.x << 16), __uint_as_float(x.x & 0xffff0000u), __uint_as_float(x.y << 16), __uint_as_float(x.y & 0xffff0000u)};
;                         f32x4 r1 = (f32x4){__uint_as_float(x.z << 16), __uint_as_float(x.z & 0xffff0000u), __uint_as_float(x.w << 16), __uint_as_float(x.w & 0xffff0000u)};
;                         r0 += sc[bj][0] * acc[ai][bj][m][0]; r1 += sc[bj][1] * acc[ai][bj][m][1];
;                         u32x4 w; w.x = cvt_pk_bf16(r0[0], r0[1]); w.y = cvt_pk_bf16(r0[2], r0[3]); w.z = cvt_pk_bf16(r1[0], r1[1]); w.w = cvt_pk_bf16(r1[2], r1[3]);
;                         *(u32x4*)(out + off0 + (size_t)(ai * HALF + m * 16) * D + bj * HALF) = w; }
	v_lshlrev_b32_e32 v100, 16, v174
	v_cvt_pk_bf16_f32 v98, v98, v99
	v_cvt_pk_bf16_f32 v99, v104, v105
	global_store_dwordx4 v[108:109], v[96:99], off offset:256
	v_and_b32_e32 v101, 0xffff0000, v174
	v_lshlrev_b32_e32 v102, 16, v175
	v_lshlrev_b32_e32 v96, 16, v172
	v_and_b32_e32 v97, 0xffff0000, v172
	v_and_b32_e32 v103, 0xffff0000, v175
	v_pk_fma_f32 v[92:93], v[92:93], v[212:213], v[96:97]
	v_lshlrev_b32_e32 v98, 16, v173
	v_and_b32_e32 v99, 0xffff0000, v173
	v_pk_fma_f32 v[96:97], v[90:91], v[210:211], v[102:103]
	v_pk_fma_f32 v[90:91], v[88:89], v[208:209], v[100:101]
	v_cvt_pk_bf16_f32 v88, v92, v93
	v_add_co_u32_e32 v92, vcc, s36, v144
	v_pk_fma_f32 v[94:95], v[94:95], v[214:215], v[98:99]
	s_nop 0
	v_addc_co_u32_e32 v93, vcc, 0, v145, vcc
	v_cvt_pk_bf16_f32 v89, v94, v95
	v_cvt_pk_bf16_f32 v90, v90, v91
	v_cvt_pk_bf16_f32 v91, v96, v97
	global_store_dwordx4 v[92:93], v[88:91], off
	s_waitcnt vmcnt(15)
	v_lshlrev_b32_e32 v94, 16, v170
	v_and_b32_e32 v95, 0xffff0000, v170
	v_lshlrev_b32_e32 v88, 16, v168
	v_and_b32_e32 v89, 0xffff0000, v168
	v_lshlrev_b32_e32 v90, 16, v169
	v_and_b32_e32 v91, 0xffff0000, v169
	v_lshlrev_b32_e32 v96, 16, v171
	v_and_b32_e32 v97, 0xffff0000, v171
	v_pk_fma_f32 v[86:87], v[86:87], v[206:207], v[90:91]
	v_pk_fma_f32 v[84:85], v[84:85], v[204:205], v[88:89]
	v_pk_fma_f32 v[88:89], v[82:83], v[202:203], v[96:97]
	v_pk_fma_f32 v[82:83], v[80:81], v[200:201], v[94:95]
	v_cvt_pk_bf16_f32 v80, v84, v85
	v_cvt_pk_bf16_f32 v81, v86, v87
	s_waitcnt vmcnt(14)
	v_lshlrev_b32_e32 v84, 16, v166
	v_cvt_pk_bf16_f32 v82, v82, v83
	v_cvt_pk_bf16_f32 v83, v88, v89
	global_store_dwordx4 v[92:93], v[80:83], off offset:256
	v_and_b32_e32 v85, 0xffff0000, v166
	v_lshlrev_b32_e32 v86, 16, v167
	v_lshlrev_b32_e32 v80, 16, v164
	v_and_b32_e32 v81, 0xffff0000, v164
	v_and_b32_e32 v87, 0xffff0000, v167
	v_pk_fma_f32 v[76:77], v[76:77], v[212:213], v[80:81]
	v_lshlrev_b32_e32 v82, 16, v165
	v_and_b32_e32 v83, 0xffff0000, v165
	v_pk_fma_f32 v[80:81], v[74:75], v[210:211], v[86:87]
	v_pk_fma_f32 v[74:75], v[72:73], v[208:209], v[84:85]
	v_cvt_pk_bf16_f32 v72, v76, v77
	v_add_co_u32_e32 v76, vcc, s23, v144
	v_pk_fma_f32 v[78:79], v[78:79], v[214:215], v[82:83]
	s_nop 0
	v_addc_co_u32_e32 v77, vcc, 0, v145, vcc
	v_cvt_pk_bf16_f32 v73, v78, v79
	v_cvt_pk_bf16_f32 v74, v74, v75
	v_cvt_pk_bf16_f32 v75, v80, v81
	global_store_dwordx4 v[76:77], v[72:75], off
	s_waitcnt vmcnt(15)
	v_lshlrev_b32_e32 v78, 16, v162
	v_and_b32_e32 v79, 0xffff0000, v162
	v_lshlrev_b32_e32 v72, 16, v160
	v_and_b32_e32 v73, 0xffff0000, v160
	v_lshlrev_b32_e32 v74, 16, v161
	v_and_b32_e32 v75, 0xffff0000, v161
	v_lshlrev_b32_e32 v80, 16, v163
	v_and_b32_e32 v81, 0xffff0000, v163
	v_pk_fma_f32 v[70:71], v[70:71], v[206:207], v[74:75]
	v_pk_fma_f32 v[68:69], v[68:69], v[204:205], v[72:73]
	v_pk_fma_f32 v[72:73], v[66:67], v[202:203], v[80:81]
	v_pk_fma_f32 v[66:67], v[64:65], v[200:201], v[78:79]
	v_cvt_pk_bf16_f32 v64, v68, v69
	v_cvt_pk_bf16_f32 v65, v70, v71
	s_waitcnt vmcnt(14)
	v_lshlrev_b32_e32 v68, 16, v158
	v_cvt_pk_bf16_f32 v66, v66, v67
	v_cvt_pk_bf16_f32 v67, v72, v73
	global_store_dwordx4 v[76:77], v[64:67], off offset:256
	v_and_b32_e32 v69, 0xffff0000, v158
	v_lshlrev_b32_e32 v70, 16, v159
	v_lshlrev_b32_e32 v64, 16, v156
	v_and_b32_e32 v65, 0xffff0000, v156
	v_and_b32_e32 v71, 0xffff0000, v159
	v_pk_fma_f32 v[60:61], v[60:61], v[212:213], v[64:65]
	v_lshlrev_b32_e32 v66, 16, v157
	v_and_b32_e32 v67, 0xffff0000, v157
	v_pk_fma_f32 v[64:65], v[58:59], v[210:211], v[70:71]
	v_pk_fma_f32 v[58:59], v[56:57], v[208:209], v[68:69]
	v_cvt_pk_bf16_f32 v56, v60, v61
	v_add_co_u32_e32 v60, vcc, s93, v144
	v_pk_fma_f32 v[62:63], v[62:63], v[214:215], v[66:67]
	s_nop 0
	v_addc_co_u32_e32 v61, vcc, 0, v145, vcc
	v_cvt_pk_bf16_f32 v57, v62, v63
	v_cvt_pk_bf16_f32 v58, v58, v59
	v_cvt_pk_bf16_f32 v59, v64, v65
	global_store_dwordx4 v[60:61], v[56:59], off
	s_waitcnt vmcnt(15)
	v_lshlrev_b32_e32 v62, 16, v154
	v_and_b32_e32 v63, 0xffff0000, v154
	v_lshlrev_b32_e32 v56, 16, v152
	v_and_b32_e32 v57, 0xffff0000, v152
	v_lshlrev_b32_e32 v58, 16, v153
	v_and_b32_e32 v59, 0xffff0000, v153
	v_lshlrev_b32_e32 v64, 16, v155
	v_and_b32_e32 v65, 0xffff0000, v155
	v_pk_fma_f32 v[54:55], v[54:55], v[206:207], v[58:59]
	v_pk_fma_f32 v[52:53], v[52:53], v[204:205], v[56:57]
	v_pk_fma_f32 v[56:57], v[50:51], v[202:203], v[64:65]
	v_pk_fma_f32 v[50:51], v[48:49], v[200:201], v[62:63]
	v_cvt_pk_bf16_f32 v48, v52, v53
	v_cvt_pk_bf16_f32 v49, v54, v55
	s_waitcnt vmcnt(14)
; __device__ __forceinline__ unsigned cvt_pk_bf16(float lo, float hi) { unsigned r; asm volatile("v_cvt_pk_bf16_f32 %0, %1, %2" : "=v"(r) : "v"(lo), "v"(hi)); return r; }
; #define PG8_WAIT_V(n) asm volatile("s_waitcnt vmcnt(" #n ")" ::: "memory")
; #define PG8_BAR __builtin_amdgcn_s_barrier()
; template <class Epi>
; __device__ __forceinline__ void gemm_phase(LAS unsigned char* lds, const Gemm g, const StaticOrder& S, const Epi& E) {
;     ...
;     PG8_WAIT_V(0);
;     if (wr == 0) PG8_BAR;
;     PG8_BAR;
;     __device__ __forceinline__ void operator()(f32x4 (&acc)[2][2][4][2], const Unit& u, int wr, int wc, int fr, int fq, LAS unsigned char*) const {
;     ...
;             for (int ai = 0; ai < 2; ++ai)
; #pragma unroll
;                 for (int m = 0; m < 4; ++m)
; #pragma unroll
;                     for (int bj = 0; bj < 2; ++bj) { const u32x4 x = xb[ai][m][bj];
;                         f32x4 r0 = (f32x4){__uint_as_float(x.x << 16), __uint_as_float(x.x & 0xffff0000u), __uint_as_float(x.y << 16), __uint_as_float(x.y & 0xffff0000u)};
;                         f32x4 r1 = (f32x4){__uint_as_float(x.z << 16), __uint_as_float(x.z & 0xffff0000u), __uint_as_float(x.w << 16), __uint_as_float(x.w & 0xffff0000u)};
;                         r0 += sc[bj][0] * acc[ai][bj][m][0]; r1 += sc[bj][1] * acc[ai][bj][m][1];
;                         u32x4 w; w.x = cvt_pk_bf16(r0[0], r0[1]); w.y = cvt_pk_bf16(r0[2], r0[3]); w.z = cvt_pk_bf16(r1[0], r1[1]); w.w = cvt_pk_bf16(r1[2], r1[3]);
;                         *(u32x4*)(out + off0 + (size_t)(ai * HALF + m * 16) * D + bj * HALF) = w; }
	v_lshlrev_b32_e32 v52, 16, v142
	v_cvt_pk_bf16_f32 v50, v50, v51
	v_cvt_pk_bf16_f32 v51, v56, v57
	global_store_dwordx4 v[60:61], v[48:51], off offset:256
	v_and_b32_e32 v53, 0xffff0000, v142
	v_lshlrev_b32_e32 v54, 16, v143
	v_lshlrev_b32_e32 v48, 16, v140
	v_and_b32_e32 v49, 0xffff0000, v140
	v_and_b32_e32 v55, 0xffff0000, v143
	v_pk_fma_f32 v[44:45], v[44:45], v[212:213], v[48:49]
	v_lshlrev_b32_e32 v50, 16, v141
	v_and_b32_e32 v51, 0xffff0000, v141
	v_pk_fma_f32 v[48:49], v[42:43], v[210:211], v[54:55]
	v_pk_fma_f32 v[42:43], v[40:41], v[208:209], v[52:53]
	v_cvt_pk_bf16_f32 v40, v44, v45
	v_add_co_u32_e32 v44, vcc, s33, v144
	v_pk_fma_f32 v[46:47], v[46:47], v[214:215], v[50:51]
	s_nop 0
	v_addc_co_u32_e32 v45, vcc, 0, v145, vcc
	v_cvt_pk_bf16_f32 v41, v46, v47
	v_cvt_pk_bf16_f32 v42, v42, v43
	v_cvt_pk_bf16_f32 v43, v48, v49
	global_store_dwordx4 v[44:45], v[40:43], off
	s_waitcnt vmcnt(15)
	v_lshlrev_b32_e32 v46, 16, v138
	v_and_b32_e32 v47, 0xffff0000, v138
	v_lshlrev_b32_e32 v40, 16, v136
	v_and_b32_e32 v41, 0xffff0000, v136
	v_lshlrev_b32_e32 v42, 16, v137
	v_and_b32_e32 v43, 0xffff0000, v137
	v_lshlrev_b32_e32 v48, 16, v139
	v_and_b32_e32 v49, 0xffff0000, v139
	v_pk_fma_f32 v[38:39], v[38:39], v[206:207], v[42:43]
	v_pk_fma_f32 v[36:37], v[36:37], v[204:205], v[40:41]
	v_pk_fma_f32 v[40:41], v[34:35], v[202:203], v[48:49]
	v_pk_fma_f32 v[34:35], v[32:33], v[200:201], v[46:47]
	v_cvt_pk_bf16_f32 v32, v36, v37
	v_cvt_pk_bf16_f32 v33, v38, v39
	s_waitcnt vmcnt(14)
	v_lshlrev_b32_e32 v36, 16, v134
	v_cvt_pk_bf16_f32 v34, v34, v35
	v_cvt_pk_bf16_f32 v35, v40, v41
	global_store_dwordx4 v[44:45], v[32:35], off offset:256
	v_and_b32_e32 v37, 0xffff0000, v134
	v_lshlrev_b32_e32 v38, 16, v135
	v_lshlrev_b32_e32 v32, 16, v132
	v_and_b32_e32 v33, 0xffff0000, v132
	v_and_b32_e32 v39, 0xffff0000, v135
	v_pk_fma_f32 v[28:29], v[28:29], v[212:213], v[32:33]
	v_lshlrev_b32_e32 v34, 16, v133
	v_and_b32_e32 v35, 0xffff0000, v133
	v_pk_fma_f32 v[32:33], v[26:27], v[210:211], v[38:39]
	v_pk_fma_f32 v[26:27], v[24:25], v[208:209], v[36:37]
	v_cvt_pk_bf16_f32 v24, v28, v29
	v_add_co_u32_e32 v28, vcc, s18, v144
	v_pk_fma_f32 v[30:31], v[30:31], v[214:215], v[34:35]
	s_nop 0
	v_addc_co_u32_e32 v29, vcc, 0, v145, vcc
	v_cvt_pk_bf16_f32 v25, v30, v31
	v_cvt_pk_bf16_f32 v26, v26, v27
	v_cvt_pk_bf16_f32 v27, v32, v33
	global_store_dwordx4 v[28:29], v[24:27], off
	s_waitcnt vmcnt(15)
	v_lshlrev_b32_e32 v30, 16, v130
	v_and_b32_e32 v31, 0xffff0000, v130
	v_lshlrev_b32_e32 v24, 16, v128
	v_and_b32_e32 v25, 0xffff0000, v128
	v_lshlrev_b32_e32 v26, 16, v129
	v_and_b32_e32 v27, 0xffff0000, v129
	v_lshlrev_b32_e32 v32, 16, v131
	v_and_b32_e32 v33, 0xffff0000, v131
	v_pk_fma_f32 v[22:23], v[22:23], v[206:207], v[26:27]
	v_pk_fma_f32 v[20:21], v[20:21], v[204:205], v[24:25]
	v_pk_fma_f32 v[24:25], v[18:19], v[202:203], v[32:33]
	v_pk_fma_f32 v[18:19], v[16:17], v[200:201], v[30:31]
	v_cvt_pk_bf16_f32 v16, v20, v21
	v_cvt_pk_bf16_f32 v17, v22, v23
	s_waitcnt vmcnt(14)
	v_lshlrev_b32_e32 v20, 16, v126
	v_cvt_pk_bf16_f32 v18, v18, v19
	v_cvt_pk_bf16_f32 v19, v24, v25
	global_store_dwordx4 v[28:29], v[16:19], off offset:256
	v_and_b32_e32 v21, 0xffff0000, v126
	v_lshlrev_b32_e32 v22, 16, v127
	v_lshlrev_b32_e32 v16, 16, v124
	v_and_b32_e32 v17, 0xffff0000, v124
	v_and_b32_e32 v23, 0xffff0000, v127
	v_pk_fma_f32 v[12:13], v[12:13], v[212:213], v[16:17]
	v_lshlrev_b32_e32 v18, 16, v125
	v_and_b32_e32 v19, 0xffff0000, v125
	v_pk_fma_f32 v[16:17], v[10:11], v[210:211], v[22:23]
	v_pk_fma_f32 v[10:11], v[8:9], v[208:209], v[20:21]
	v_cvt_pk_bf16_f32 v8, v12, v13
	v_add_co_u32_e32 v12, vcc, s19, v144
	v_pk_fma_f32 v[14:15], v[14:15], v[214:215], v[18:19]
	s_nop 0
	v_addc_co_u32_e32 v13, vcc, 0, v145, vcc
	v_cvt_pk_bf16_f32 v9, v14, v15
	v_cvt_pk_bf16_f32 v10, v10, v11
	v_cvt_pk_bf16_f32 v11, v16, v17
	global_store_dwordx4 v[12:13], v[8:11], off
	s_waitcnt vmcnt(15)
	v_lshlrev_b32_e32 v14, 16, v122
	v_and_b32_e32 v15, 0xffff0000, v122
	v_lshlrev_b32_e32 v8, 16, v120
	v_and_b32_e32 v9, 0xffff0000, v120
	v_lshlrev_b32_e32 v16, 16, v123
	v_and_b32_e32 v17, 0xffff0000, v123
	v_lshlrev_b32_e32 v10, 16, v121
	v_and_b32_e32 v11, 0xffff0000, v121
	v_pk_fma_f32 v[4:5], v[4:5], v[204:205], v[8:9]
	v_pk_fma_f32 v[8:9], v[2:3], v[202:203], v[16:17]
	v_pk_fma_f32 v[2:3], v[0:1], v[200:201], v[14:15]
	s_and_b64 vcc, exec, s[4:5]
	v_pk_fma_f32 v[6:7], v[6:7], v[206:207], v[10:11]
	v_cvt_pk_bf16_f32 v0, v4, v5
	s_nop 0
	v_cvt_pk_bf16_f32 v1, v6, v7
	v_cvt_pk_bf16_f32 v2, v2, v3
	v_cvt_pk_bf16_f32 v3, v8, v9
	global_store_dwordx4 v[12:13], v[0:3], off offset:256
	s_cbranch_vccz .LBB0_849
	s_waitcnt vmcnt(0)
	s_cmpk_gt_u32 s21, 0xff
	v_readlane_b32 s38, v255, 44
	s_cbranch_scc1 .LBB0_864
